# all hand-written lean epilogues (in-proj plain/sigmoid/gelu, up, gated-merge) + attention staging loads de-serialized + GEMM prologue loads issued before first wait
# speedup vs baseline: 1.0038x; 1.0009x over previous
.Llean_F_entry:
	v_and_b32_e32 v136, 15, v226
	v_lshrrev_b32_e32 v137, 4, v226
	v_or_b32_e32 v136, s49, v136
	v_lshl_add_u32 v138, s6, 8, v136
	v_lshlrev_b32_e32 v140, 4, v137
	v_lshl_add_u32 v140, v138, 6, v140
	v_mov_b32_e32 v141, 0
	v_lshl_add_u64 v[142:143], s[26:27], 0, v[140:141]
	v_add_u32_e32 v140, 0x2000, v140
	v_lshl_add_u64 v[144:145], s[26:27], 0, v[140:141]
	global_load_dwordx4 v[72:75], v[142:143], off
	global_load_dwordx4 v[76:79], v[142:143], off offset:1024
	global_load_dwordx4 v[80:83], v[142:143], off offset:2048
	global_load_dwordx4 v[84:87], v[142:143], off offset:3072
	global_load_dwordx4 v[104:107], v[144:145], off
	global_load_dwordx4 v[108:111], v[144:145], off offset:1024
	global_load_dwordx4 v[112:115], v[144:145], off offset:2048
	global_load_dwordx4 v[116:119], v[144:145], off offset:3072
	v_mul_lo_u32 v146, v138, s39
	v_mov_b32_e32 v147, 0
	s_lshl_b32 s0, s14, 8
	s_add_i32 s0, s0, s20
	v_lshl_add_u32 v148, v137, 3, s0
	v_lshlrev_b32_e32 v148, 1, v148
	v_mov_b32_e32 v149, 0
	v_lshl_add_u64 v[146:147], v[146:147], 1, s[72:73]
	v_lshl_add_u64 v[146:147], v[146:147], 0, v[148:149]
	s_lshl_b32 s2, s39, 5
	s_mov_b32 s3, 0
	s_mul_i32 s0, s39, 0xa0
	s_mov_b32 s1, 0
	v_mov_b32_e32 v213, 0x260
	s_waitcnt vmcnt(0)
	v_add_f32_e32 v168, v72, v73
	v_add_f32_e32 v169, v74, v75
	v_add_f32_e32 v168, v168, v169
	v_add_f32_e32 v170, v76, v77
	v_add_f32_e32 v171, v78, v79
	v_add_f32_e32 v170, v170, v171
	v_add_f32_e32 v172, v80, v81
	v_add_f32_e32 v173, v82, v83
	v_add_f32_e32 v172, v172, v173
	v_add_f32_e32 v174, v84, v85
	v_add_f32_e32 v175, v86, v87
	v_add_f32_e32 v174, v174, v175
	v_add_f32_e32 v176, v104, v105
	v_add_f32_e32 v177, v106, v107
	v_add_f32_e32 v176, v176, v177
	v_add_f32_e32 v178, v108, v109
	v_add_f32_e32 v179, v110, v111
	v_add_f32_e32 v178, v178, v179
	v_add_f32_e32 v180, v112, v113
	v_add_f32_e32 v181, v114, v115
	v_add_f32_e32 v180, v180, v181
	v_add_f32_e32 v182, v116, v117
	v_add_f32_e32 v183, v118, v119
	v_add_f32_e32 v182, v182, v183
	ds_swizzle_b32 v169, v168 offset:swizzle(SWAP,16)
	ds_swizzle_b32 v171, v170 offset:swizzle(SWAP,16)
	ds_swizzle_b32 v173, v172 offset:swizzle(SWAP,16)
	ds_swizzle_b32 v175, v174 offset:swizzle(SWAP,16)
	ds_swizzle_b32 v177, v176 offset:swizzle(SWAP,16)
	ds_swizzle_b32 v179, v178 offset:swizzle(SWAP,16)
	ds_swizzle_b32 v181, v180 offset:swizzle(SWAP,16)
	ds_swizzle_b32 v183, v182 offset:swizzle(SWAP,16)
	s_waitcnt lgkmcnt(0)
	v_add_f32_e32 v168, v168, v169
	v_add_f32_e32 v170, v170, v171
	v_add_f32_e32 v172, v172, v173
	v_add_f32_e32 v174, v174, v175
	v_add_f32_e32 v176, v176, v177
	v_add_f32_e32 v178, v178, v179
	v_add_f32_e32 v180, v180, v181
	v_add_f32_e32 v182, v182, v183
	v_mov_b32_e32 v169, v168
	v_mov_b32_e32 v171, v170
	v_mov_b32_e32 v173, v172
	v_mov_b32_e32 v175, v174
	v_mov_b32_e32 v177, v176
	v_mov_b32_e32 v179, v178
	v_mov_b32_e32 v181, v180
	v_mov_b32_e32 v183, v182
	s_nop 1
	v_permlane32_swap_b32_e32 v168, v169
	v_permlane32_swap_b32_e32 v170, v171
	v_permlane32_swap_b32_e32 v172, v173
	v_permlane32_swap_b32_e32 v174, v175
	v_permlane32_swap_b32_e32 v176, v177
	v_permlane32_swap_b32_e32 v178, v179
	v_permlane32_swap_b32_e32 v180, v181
	v_permlane32_swap_b32_e32 v182, v183
	v_add_f32_e32 v168, v168, v169
	v_add_f32_e32 v170, v170, v171
	v_add_f32_e32 v172, v172, v173
	v_add_f32_e32 v174, v174, v175
	v_add_f32_e32 v176, v176, v177
	v_add_f32_e32 v178, v178, v179
	v_add_f32_e32 v180, v180, v181
	v_add_f32_e32 v182, v182, v183
	v_fmamk_f32 v168, v168, 0x3a800000, v246
	v_fmamk_f32 v170, v170, 0x3a800000, v246
	v_sqrt_f32_e32 v208, v168
	v_sqrt_f32_e32 v139, v170
	v_add_u32_e32 v209, -1, v208
	v_add_u32_e32 v140, -1, v139
	v_fma_f32 v210, -v209, v208, v168
	v_fma_f32 v141, -v140, v139, v170
	v_cmp_ge_f32_e64 s[98:99], 0, v210
	v_cmp_ge_f32_e64 s[16:17], 0, v141
	v_add_u32_e32 v210, 1, v208
	v_add_u32_e32 v141, 1, v139
	v_cndmask_b32_e64 v209, v208, v209, s[98:99]
	v_cndmask_b32_e64 v140, v139, v140, s[16:17]
	v_fma_f32 v211, -v210, v208, v168
	v_fma_f32 v142, -v141, v139, v170
	v_cmp_lt_f32_e64 s[98:99], 0, v211
	v_cmp_lt_f32_e64 s[16:17], 0, v142
	s_nop 0
	v_cndmask_b32_e64 v208, v209, v210, s[98:99]
	v_cndmask_b32_e64 v139, v140, v141, s[16:17]
	v_rcp_f32_e32 v209, v208
	v_rcp_f32_e32 v140, v139
	v_fma_f32 v210, -v208, v209, 1.0
	v_fma_f32 v141, -v139, v140, 1.0
	v_fmac_f32_e32 v209, v210, v209
	v_fmac_f32_e32 v140, v141, v140
	v_fma_f32 v212, -v208, v209, 1.0
	v_fma_f32 v143, -v139, v140, 1.0
	v_fma_f32 v211, v212, v209, v209
	v_fma_f32 v142, v143, v140, v140
	v_fma_f32 v212, -v208, v211, 1.0
	v_fma_f32 v143, -v139, v142, 1.0
	v_fma_f32 v168, v212, v209, v211
	v_fma_f32 v170, v143, v140, v142
	v_fmamk_f32 v172, v172, 0x3a800000, v246
	v_fmamk_f32 v174, v174, 0x3a800000, v246
	v_sqrt_f32_e32 v208, v172
	v_sqrt_f32_e32 v139, v174
	v_add_u32_e32 v209, -1, v208
	v_add_u32_e32 v140, -1, v139
	v_fma_f32 v210, -v209, v208, v172
	v_fma_f32 v141, -v140, v139, v174
	v_cmp_ge_f32_e64 s[98:99], 0, v210
	v_cmp_ge_f32_e64 s[16:17], 0, v141
	v_add_u32_e32 v210, 1, v208
	v_add_u32_e32 v141, 1, v139
	v_cndmask_b32_e64 v209, v208, v209, s[98:99]
	v_cndmask_b32_e64 v140, v139, v140, s[16:17]
	v_fma_f32 v211, -v210, v208, v172
	v_fma_f32 v142, -v141, v139, v174
	v_cmp_lt_f32_e64 s[98:99], 0, v211
	v_cmp_lt_f32_e64 s[16:17], 0, v142
	s_nop 0
	v_cndmask_b32_e64 v208, v209, v210, s[98:99]
	v_cndmask_b32_e64 v139, v140, v141, s[16:17]
	v_rcp_f32_e32 v209, v208
	v_rcp_f32_e32 v140, v139
	v_fma_f32 v210, -v208, v209, 1.0
	v_fma_f32 v141, -v139, v140, 1.0
	v_fmac_f32_e32 v209, v210, v209
	v_fmac_f32_e32 v140, v141, v140
	v_fma_f32 v212, -v208, v209, 1.0
	v_fma_f32 v143, -v139, v140, 1.0
; __device__ __forceinline__ unsigned cvt_pk_bf16(float lo, float hi) { unsigned r; asm volatile("v_cvt_pk_bf16_f32 %0, %1, %2" : "=v"(r) : "v"(lo), "v"(hi)); return r; }
; #define GAS __attribute__((address_space(1)))
;     DI void operator()(AccRef acc, const pg8::Unit& u, int wr, int wc, int, int) const {
;     ...
;         for (int m = 0; m < 4; ++m) { const int lrow = u.pm * 256 + ai * 128 + wr * 64 + m * 16 + fr;
;             const float rs = rs8[ai * 4 + m];
;             const f32x4 c0 = rc0[m], c1 = rc1[m], s0 = rs0[m], s1 = rs1[m];
;             EPI_COLS_BEGIN
;                 { const float rsk = (kind == 4) ? rs * -1.4426950408889634f : rs; v0 = v0 * rsk; v1 = v1 * rsk; }
;                 if (kind < 2) {
;                     if (rot) {
;                         f32x4 p0, p1;
; #pragma unroll
;                         for (int e = 0; e < 4; ++e) { p0[e] = lane_xor<16>(v0[e]); p1[e] = lane_xor<16>(v1[e]); }
;                         if (fq == 0) { v0 = v0 * c0 - p0 * s0; v1 = v1 * c1 - p1 * s1; }
;                         else if (fq == 1) { v0 = v0 * c0 + p0 * s0; v1 = v1 * c1 + p1 * s1; }
;                     }
;                     v0 = v0 * qs; v1 = v1 * qs;
;                 } else if (kind == 3) {
;                     f32x2 a = pg8::gelu_pk((f32x2){v0[0], v0[1]}), b = pg8::gelu_pk((f32x2){v0[2], v0[3]}), c = pg8::gelu_pk((f32x2){v1[0], v1[1]}), d = pg8::gelu_pk((f32x2){v1[2], v1[3]});
;                     v0 = (f32x4){a.x, a.y, b.x, b.y}; v1 = (f32x4){c.x, c.y, d.x, d.y};
;                 } else if (kind == 4) {
; #pragma unroll
;                     for (int e = 0; e < 4; ++e) { v0[e] = __builtin_amdgcn_rcpf(1.0f + __builtin_amdgcn_exp2f(v0[e])); v1[e] = __builtin_amdgcn_rcpf(1.0f + __builtin_amdgcn_exp2f(v1[e])); }
;                 }
;                 u32x4 w; w.x = cvt_pk_bf16(v0[0], v0[1]); w.y = cvt_pk_bf16(v0[2], v0[3]); w.z = cvt_pk_bf16(v1[0], v1[1]); w.w = cvt_pk_bf16(v1[2], v1[3]);
;                 *(GAS u32x4*)(dummy ? dummy + lane_ * 8 : Z + (size_t)lrow * ldz + col) = w;
	v_fma_f32 v211, v212, v209, v209
	v_fma_f32 v142, v143, v140, v140
	v_fma_f32 v212, -v208, v211, 1.0
	v_fma_f32 v143, -v139, v142, 1.0
	v_fma_f32 v172, v212, v209, v211
	v_fma_f32 v174, v143, v140, v142
	v_fmamk_f32 v176, v176, 0x3a800000, v246
	v_fmamk_f32 v178, v178, 0x3a800000, v246
	v_sqrt_f32_e32 v208, v176
	v_sqrt_f32_e32 v139, v178
	v_add_u32_e32 v209, -1, v208
	v_add_u32_e32 v140, -1, v139
	v_fma_f32 v210, -v209, v208, v176
	v_fma_f32 v141, -v140, v139, v178
	v_cmp_ge_f32_e64 s[98:99], 0, v210
	v_cmp_ge_f32_e64 s[16:17], 0, v141
	v_add_u32_e32 v210, 1, v208
	v_add_u32_e32 v141, 1, v139
	v_cndmask_b32_e64 v209, v208, v209, s[98:99]
	v_cndmask_b32_e64 v140, v139, v140, s[16:17]
	v_fma_f32 v211, -v210, v208, v176
	v_fma_f32 v142, -v141, v139, v178
	v_cmp_lt_f32_e64 s[98:99], 0, v211
	v_cmp_lt_f32_e64 s[16:17], 0, v142
	s_nop 0
	v_cndmask_b32_e64 v208, v209, v210, s[98:99]
	v_cndmask_b32_e64 v139, v140, v141, s[16:17]
	v_rcp_f32_e32 v209, v208
	v_rcp_f32_e32 v140, v139
	v_fma_f32 v210, -v208, v209, 1.0
	v_fma_f32 v141, -v139, v140, 1.0
	v_fmac_f32_e32 v209, v210, v209
	v_fmac_f32_e32 v140, v141, v140
	v_fma_f32 v212, -v208, v209, 1.0
	v_fma_f32 v143, -v139, v140, 1.0
	v_fma_f32 v211, v212, v209, v209
	v_fma_f32 v142, v143, v140, v140
	v_fma_f32 v212, -v208, v211, 1.0
	v_fma_f32 v143, -v139, v142, 1.0
	v_fma_f32 v176, v212, v209, v211
	v_fma_f32 v178, v143, v140, v142
	v_fmamk_f32 v180, v180, 0x3a800000, v246
	v_fmamk_f32 v182, v182, 0x3a800000, v246
	v_sqrt_f32_e32 v208, v180
	v_sqrt_f32_e32 v139, v182
	v_add_u32_e32 v209, -1, v208
	v_add_u32_e32 v140, -1, v139
	v_fma_f32 v210, -v209, v208, v180
	v_fma_f32 v141, -v140, v139, v182
	v_cmp_ge_f32_e64 s[98:99], 0, v210
	v_cmp_ge_f32_e64 s[16:17], 0, v141
	v_add_u32_e32 v210, 1, v208
	v_add_u32_e32 v141, 1, v139
	v_cndmask_b32_e64 v209, v208, v209, s[98:99]
	v_cndmask_b32_e64 v140, v139, v140, s[16:17]
	v_fma_f32 v211, -v210, v208, v180
	v_fma_f32 v142, -v141, v139, v182
	v_cmp_lt_f32_e64 s[98:99], 0, v211
	v_cmp_lt_f32_e64 s[16:17], 0, v142
	s_nop 0
	v_cndmask_b32_e64 v208, v209, v210, s[98:99]
	v_cndmask_b32_e64 v139, v140, v141, s[16:17]
	v_rcp_f32_e32 v209, v208
	v_rcp_f32_e32 v140, v139
	v_fma_f32 v210, -v208, v209, 1.0
	v_fma_f32 v141, -v139, v140, 1.0
	v_fmac_f32_e32 v209, v210, v209
	v_fmac_f32_e32 v140, v141, v140
	v_fma_f32 v212, -v208, v209, 1.0
	v_fma_f32 v143, -v139, v140, 1.0
	v_fma_f32 v211, v212, v209, v209
	v_fma_f32 v142, v143, v140, v140
	v_fma_f32 v212, -v208, v211, 1.0
	v_fma_f32 v143, -v139, v142, 1.0
	v_fma_f32 v180, v212, v209, v211
	v_fma_f32 v182, v143, v140, v142
	s_cmp_eq_u32 s8, 4
	s_cbranch_scc1 .Llean_F_sig
	s_cmp_eq_u32 s8, 3
	s_cbranch_scc1 .Llean_F_gelu
	v_pk_mul_f32 v[188:189], v[188:189], v[168:169] op_sel_hi:[1,0]
	v_pk_mul_f32 v[190:191], v[190:191], v[168:169] op_sel_hi:[1,0]
	v_pk_mul_f32 v[184:185], v[184:185], v[168:169] op_sel_hi:[1,0]
	v_pk_mul_f32 v[186:187], v[186:187], v[168:169] op_sel_hi:[1,0]
	v_cvt_pk_bf16_f32 v216, v188, v189
	v_cvt_pk_bf16_f32 v217, v190, v191
	v_cvt_pk_bf16_f32 v218, v184, v185
	v_cvt_pk_bf16_f32 v219, v186, v187
	global_store_dwordx4 v[146:147], v[216:219], off
	v_pk_mul_f32 v[164:165], v[164:165], v[168:169] op_sel_hi:[1,0]
	v_pk_mul_f32 v[166:167], v[166:167], v[168:169] op_sel_hi:[1,0]
	v_pk_mul_f32 v[160:161], v[160:161], v[168:169] op_sel_hi:[1,0]
	v_pk_mul_f32 v[162:163], v[162:163], v[168:169] op_sel_hi:[1,0]
	v_cvt_pk_bf16_f32 v220, v164, v165
	v_cvt_pk_bf16_f32 v221, v166, v167
	v_cvt_pk_bf16_f32 v222, v160, v161
	v_cvt_pk_bf16_f32 v223, v162, v163
	global_store_dwordx4 v[146:147], v[220:223], off offset:256
	v_lshl_add_u64 v[150:151], v[146:147], 0, s[2:3]
	v_pk_mul_f32 v[156:157], v[156:157], v[170:171] op_sel_hi:[1,0]
	v_pk_mul_f32 v[158:159], v[158:159], v[170:171] op_sel_hi:[1,0]
	v_pk_mul_f32 v[152:153], v[152:153], v[170:171] op_sel_hi:[1,0]
	v_pk_mul_f32 v[154:155], v[154:155], v[170:171] op_sel_hi:[1,0]
	v_cvt_pk_bf16_f32 v224, v156, v157
	v_cvt_pk_bf16_f32 v225, v158, v159
	v_cvt_pk_bf16_f32 v226, v152, v153
	v_cvt_pk_bf16_f32 v227, v154, v155
	global_store_dwordx4 v[150:151], v[224:227], off
	v_pk_mul_f32 v[132:133], v[132:133], v[170:171] op_sel_hi:[1,0]
	v_pk_mul_f32 v[134:135], v[134:135], v[170:171] op_sel_hi:[1,0]
	v_pk_mul_f32 v[128:129], v[128:129], v[170:171] op_sel_hi:[1,0]
	v_pk_mul_f32 v[130:131], v[130:131], v[170:171] op_sel_hi:[1,0]
	v_cvt_pk_bf16_f32 v228, v132, v133
	v_cvt_pk_bf16_f32 v229, v134, v135
	v_cvt_pk_bf16_f32 v230, v128, v129
	v_cvt_pk_bf16_f32 v231, v130, v131
	global_store_dwordx4 v[150:151], v[228:231], off offset:256
	v_lshl_add_u64 v[146:147], v[150:151], 0, s[2:3]
	v_pk_mul_f32 v[124:125], v[124:125], v[172:173] op_sel_hi:[1,0]
	v_pk_mul_f32 v[126:127], v[126:127], v[172:173] op_sel_hi:[1,0]
	v_pk_mul_f32 v[120:121], v[120:121], v[172:173] op_sel_hi:[1,0]
	v_pk_mul_f32 v[122:123], v[122:123], v[172:173] op_sel_hi:[1,0]
	v_cvt_pk_bf16_f32 v216, v124, v125
	v_cvt_pk_bf16_f32 v217, v126, v127
	v_cvt_pk_bf16_f32 v218, v120, v121
	v_cvt_pk_bf16_f32 v219, v122, v123
	global_store_dwordx4 v[146:147], v[216:219], off
	v_pk_mul_f32 v[100:101], v[100:101], v[172:173] op_sel_hi:[1,0]
	v_pk_mul_f32 v[102:103], v[102:103], v[172:173] op_sel_hi:[1,0]
	v_pk_mul_f32 v[96:97], v[96:97], v[172:173] op_sel_hi:[1,0]
	v_pk_mul_f32 v[98:99], v[98:99], v[172:173] op_sel_hi:[1,0]
	v_cvt_pk_bf16_f32 v220, v100, v101
	v_cvt_pk_bf16_f32 v221, v102, v103
	v_cvt_pk_bf16_f32 v222, v96, v97
	v_cvt_pk_bf16_f32 v223, v98, v99
	global_store_dwordx4 v[146:147], v[220:223], off offset:256
	v_lshl_add_u64 v[150:151], v[146:147], 0, s[2:3]
	v_pk_mul_f32 v[92:93], v[92:93], v[174:175] op_sel_hi:[1,0]
; __device__ __forceinline__ unsigned cvt_pk_bf16(float lo, float hi) { unsigned r; asm volatile("v_cvt_pk_bf16_f32 %0, %1, %2" : "=v"(r) : "v"(lo), "v"(hi)); return r; }
; #define GAS __attribute__((address_space(1)))
;     DI void operator()(AccRef acc, const pg8::Unit& u, int wr, int wc, int, int) const {
;     ...
;         for (int m = 0; m < 4; ++m) { const int lrow = u.pm * 256 + ai * 128 + wr * 64 + m * 16 + fr;
;             const float rs = rs8[ai * 4 + m];
;             const f32x4 c0 = rc0[m], c1 = rc1[m], s0 = rs0[m], s1 = rs1[m];
;             EPI_COLS_BEGIN
;                 { const float rsk = (kind == 4) ? rs * -1.4426950408889634f : rs; v0 = v0 * rsk; v1 = v1 * rsk; }
;                 if (kind < 2) {
;                     if (rot) {
;                         f32x4 p0, p1;
; #pragma unroll
;                         for (int e = 0; e < 4; ++e) { p0[e] = lane_xor<16>(v0[e]); p1[e] = lane_xor<16>(v1[e]); }
;                         if (fq == 0) { v0 = v0 * c0 - p0 * s0; v1 = v1 * c1 - p1 * s1; }
;                         else if (fq == 1) { v0 = v0 * c0 + p0 * s0; v1 = v1 * c1 + p1 * s1; }
;                     }
;                     v0 = v0 * qs; v1 = v1 * qs;
;                 } else if (kind == 3) {
;                     f32x2 a = pg8::gelu_pk((f32x2){v0[0], v0[1]}), b = pg8::gelu_pk((f32x2){v0[2], v0[3]}), c = pg8::gelu_pk((f32x2){v1[0], v1[1]}), d = pg8::gelu_pk((f32x2){v1[2], v1[3]});
;                     v0 = (f32x4){a.x, a.y, b.x, b.y}; v1 = (f32x4){c.x, c.y, d.x, d.y};
;                 } else if (kind == 4) {
; #pragma unroll
;                     for (int e = 0; e < 4; ++e) { v0[e] = __builtin_amdgcn_rcpf(1.0f + __builtin_amdgcn_exp2f(v0[e])); v1[e] = __builtin_amdgcn_rcpf(1.0f + __builtin_amdgcn_exp2f(v1[e])); }
;                 }
;                 u32x4 w; w.x = cvt_pk_bf16(v0[0], v0[1]); w.y = cvt_pk_bf16(v0[2], v0[3]); w.z = cvt_pk_bf16(v1[0], v1[1]); w.w = cvt_pk_bf16(v1[2], v1[3]);
;                 *(GAS u32x4*)(dummy ? dummy + lane_ * 8 : Z + (size_t)lrow * ldz + col) = w;
;             EPI_END
	v_pk_mul_f32 v[94:95], v[94:95], v[174:175] op_sel_hi:[1,0]
	v_pk_mul_f32 v[88:89], v[88:89], v[174:175] op_sel_hi:[1,0]
	v_pk_mul_f32 v[90:91], v[90:91], v[174:175] op_sel_hi:[1,0]
	v_cvt_pk_bf16_f32 v224, v92, v93
	v_cvt_pk_bf16_f32 v225, v94, v95
	v_cvt_pk_bf16_f32 v226, v88, v89
	v_cvt_pk_bf16_f32 v227, v90, v91
	global_store_dwordx4 v[150:151], v[224:227], off
	v_pk_mul_f32 v[68:69], v[68:69], v[174:175] op_sel_hi:[1,0]
	v_pk_mul_f32 v[70:71], v[70:71], v[174:175] op_sel_hi:[1,0]
	v_pk_mul_f32 v[64:65], v[64:65], v[174:175] op_sel_hi:[1,0]
	v_pk_mul_f32 v[66:67], v[66:67], v[174:175] op_sel_hi:[1,0]
	v_cvt_pk_bf16_f32 v228, v68, v69
	v_cvt_pk_bf16_f32 v229, v70, v71
	v_cvt_pk_bf16_f32 v230, v64, v65
	v_cvt_pk_bf16_f32 v231, v66, v67
	global_store_dwordx4 v[150:151], v[228:231], off offset:256
	v_lshl_add_u64 v[146:147], v[150:151], 0, s[0:1]
	v_pk_mul_f32 v[60:61], v[60:61], v[176:177] op_sel_hi:[1,0]
	v_pk_mul_f32 v[62:63], v[62:63], v[176:177] op_sel_hi:[1,0]
	v_pk_mul_f32 v[56:57], v[56:57], v[176:177] op_sel_hi:[1,0]
	v_pk_mul_f32 v[58:59], v[58:59], v[176:177] op_sel_hi:[1,0]
	v_cvt_pk_bf16_f32 v216, v60, v61
	v_cvt_pk_bf16_f32 v217, v62, v63
	v_cvt_pk_bf16_f32 v218, v56, v57
	v_cvt_pk_bf16_f32 v219, v58, v59
	global_store_dwordx4 v[146:147], v[216:219], off
	v_pk_mul_f32 v[52:53], v[52:53], v[176:177] op_sel_hi:[1,0]
	v_pk_mul_f32 v[54:55], v[54:55], v[176:177] op_sel_hi:[1,0]
	v_pk_mul_f32 v[48:49], v[48:49], v[176:177] op_sel_hi:[1,0]
	v_pk_mul_f32 v[50:51], v[50:51], v[176:177] op_sel_hi:[1,0]
	v_cvt_pk_bf16_f32 v220, v52, v53
	v_cvt_pk_bf16_f32 v221, v54, v55
	v_cvt_pk_bf16_f32 v222, v48, v49
	v_cvt_pk_bf16_f32 v223, v50, v51
	global_store_dwordx4 v[146:147], v[220:223], off offset:256
	v_lshl_add_u64 v[150:151], v[146:147], 0, s[2:3]
	v_pk_mul_f32 v[44:45], v[44:45], v[178:179] op_sel_hi:[1,0]
	v_pk_mul_f32 v[46:47], v[46:47], v[178:179] op_sel_hi:[1,0]
	v_pk_mul_f32 v[40:41], v[40:41], v[178:179] op_sel_hi:[1,0]
	v_pk_mul_f32 v[42:43], v[42:43], v[178:179] op_sel_hi:[1,0]
	v_cvt_pk_bf16_f32 v224, v44, v45
	v_cvt_pk_bf16_f32 v225, v46, v47
	v_cvt_pk_bf16_f32 v226, v40, v41
	v_cvt_pk_bf16_f32 v227, v42, v43
	global_store_dwordx4 v[150:151], v[224:227], off
	v_pk_mul_f32 v[36:37], v[36:37], v[178:179] op_sel_hi:[1,0]
	v_pk_mul_f32 v[38:39], v[38:39], v[178:179] op_sel_hi:[1,0]
	v_pk_mul_f32 v[32:33], v[32:33], v[178:179] op_sel_hi:[1,0]
	v_pk_mul_f32 v[34:35], v[34:35], v[178:179] op_sel_hi:[1,0]
	v_cvt_pk_bf16_f32 v228, v36, v37
	v_cvt_pk_bf16_f32 v229, v38, v39
	v_cvt_pk_bf16_f32 v230, v32, v33
	v_cvt_pk_bf16_f32 v231, v34, v35
	global_store_dwordx4 v[150:151], v[228:231], off offset:256
	v_lshl_add_u64 v[146:147], v[150:151], 0, s[2:3]
	v_pk_mul_f32 v[28:29], v[28:29], v[180:181] op_sel_hi:[1,0]
	v_pk_mul_f32 v[30:31], v[30:31], v[180:181] op_sel_hi:[1,0]
	v_pk_mul_f32 v[24:25], v[24:25], v[180:181] op_sel_hi:[1,0]
	v_pk_mul_f32 v[26:27], v[26:27], v[180:181] op_sel_hi:[1,0]
	v_cvt_pk_bf16_f32 v216, v28, v29
	v_cvt_pk_bf16_f32 v217, v30, v31
	v_cvt_pk_bf16_f32 v218, v24, v25
	v_cvt_pk_bf16_f32 v219, v26, v27
	global_store_dwordx4 v[146:147], v[216:219], off
	v_pk_mul_f32 v[20:21], v[20:21], v[180:181] op_sel_hi:[1,0]
	v_pk_mul_f32 v[22:23], v[22:23], v[180:181] op_sel_hi:[1,0]
	v_pk_mul_f32 v[16:17], v[16:17], v[180:181] op_sel_hi:[1,0]
	v_pk_mul_f32 v[18:19], v[18:19], v[180:181] op_sel_hi:[1,0]
	v_cvt_pk_bf16_f32 v220, v20, v21
	v_cvt_pk_bf16_f32 v221, v22, v23
	v_cvt_pk_bf16_f32 v222, v16, v17
	v_cvt_pk_bf16_f32 v223, v18, v19
	global_store_dwordx4 v[146:147], v[220:223], off offset:256
	v_lshl_add_u64 v[150:151], v[146:147], 0, s[2:3]
	v_pk_mul_f32 v[12:13], v[12:13], v[182:183] op_sel_hi:[1,0]
	v_pk_mul_f32 v[14:15], v[14:15], v[182:183] op_sel_hi:[1,0]
	v_pk_mul_f32 v[8:9], v[8:9], v[182:183] op_sel_hi:[1,0]
	v_pk_mul_f32 v[10:11], v[10:11], v[182:183] op_sel_hi:[1,0]
	v_cvt_pk_bf16_f32 v224, v12, v13
	v_cvt_pk_bf16_f32 v225, v14, v15
	v_cvt_pk_bf16_f32 v226, v8, v9
	v_cvt_pk_bf16_f32 v227, v10, v11
	global_store_dwordx4 v[150:151], v[224:227], off
	v_pk_mul_f32 v[4:5], v[4:5], v[182:183] op_sel_hi:[1,0]
	v_pk_mul_f32 v[6:7], v[6:7], v[182:183] op_sel_hi:[1,0]
	v_pk_mul_f32 v[0:1], v[0:1], v[182:183] op_sel_hi:[1,0]
	v_pk_mul_f32 v[2:3], v[2:3], v[182:183] op_sel_hi:[1,0]
	v_cvt_pk_bf16_f32 v228, v4, v5
	v_cvt_pk_bf16_f32 v229, v6, v7
	v_cvt_pk_bf16_f32 v230, v0, v1
	v_cvt_pk_bf16_f32 v231, v2, v3
	global_store_dwordx4 v[150:151], v[228:231], off offset:256
	s_branch .Llean_F_exit
; __device__ __forceinline__ unsigned cvt_pk_bf16(float lo, float hi) { unsigned r; asm volatile("v_cvt_pk_bf16_f32 %0, %1, %2" : "=v"(r) : "v"(lo), "v"(hi)); return r; }
; #define GAS __attribute__((address_space(1)))
;     DI void operator()(AccRef acc, const pg8::Unit& u, int wr, int wc, int, int) const {
;     ...
;                 { const float rsk = (kind == 4) ? rs * -1.4426950408889634f : rs; v0 = v0 * rsk; v1 = v1 * rsk; }
;     ...
;                 } else if (kind == 4) {
; #pragma unroll
;                     for (int e = 0; e < 4; ++e) { v0[e] = __builtin_amdgcn_rcpf(1.0f + __builtin_amdgcn_exp2f(v0[e])); v1[e] = __builtin_amdgcn_rcpf(1.0f + __builtin_amdgcn_exp2f(v1[e])); }
;                 }
;                 u32x4 w; w.x = cvt_pk_bf16(v0[0], v0[1]); w.y = cvt_pk_bf16(v0[2], v0[3]); w.z = cvt_pk_bf16(v1[0], v1[1]); w.w = cvt_pk_bf16(v1[2], v1[3]);
;                 *(GAS u32x4*)(dummy ? dummy + lane_ * 8 : Z + (size_t)lrow * ldz + col) = w;
.Llean_F_sig:
	v_mul_f32_e32 v168, 0xbfb8aa3b, v168
	v_mul_f32_e32 v170, 0xbfb8aa3b, v170
	v_mul_f32_e32 v172, 0xbfb8aa3b, v172
	v_mul_f32_e32 v174, 0xbfb8aa3b, v174
	v_mul_f32_e32 v176, 0xbfb8aa3b, v176
	v_mul_f32_e32 v178, 0xbfb8aa3b, v178
	v_mul_f32_e32 v180, 0xbfb8aa3b, v180
	v_mul_f32_e32 v182, 0xbfb8aa3b, v182
	v_pk_mul_f32 v[188:189], v[188:189], v[168:169] op_sel_hi:[1,0]
	v_pk_mul_f32 v[190:191], v[190:191], v[168:169] op_sel_hi:[1,0]
	v_pk_mul_f32 v[184:185], v[184:185], v[168:169] op_sel_hi:[1,0]
	v_pk_mul_f32 v[186:187], v[186:187], v[168:169] op_sel_hi:[1,0]
	v_exp_f32_e32 v188, v188
	v_exp_f32_e32 v189, v189
	v_exp_f32_e32 v190, v190
	v_exp_f32_e32 v191, v191
	v_exp_f32_e32 v184, v184
	v_exp_f32_e32 v185, v185
	v_exp_f32_e32 v186, v186
	v_exp_f32_e32 v187, v187
	v_add_f32_e32 v188, 1.0, v188
	v_add_f32_e32 v189, 1.0, v189
	v_add_f32_e32 v190, 1.0, v190
	v_add_f32_e32 v191, 1.0, v191
	v_add_f32_e32 v184, 1.0, v184
	v_add_f32_e32 v185, 1.0, v185
	v_add_f32_e32 v186, 1.0, v186
	v_add_f32_e32 v187, 1.0, v187
	v_rcp_f32_e32 v188, v188
	v_rcp_f32_e32 v189, v189
	v_rcp_f32_e32 v190, v190
	v_rcp_f32_e32 v191, v191
	v_rcp_f32_e32 v184, v184
	v_rcp_f32_e32 v185, v185
	v_rcp_f32_e32 v186, v186
	v_rcp_f32_e32 v187, v187
	s_nop 0
	v_cvt_pk_bf16_f32 v216, v188, v189
	v_cvt_pk_bf16_f32 v217, v190, v191
	v_cvt_pk_bf16_f32 v218, v184, v185
	v_cvt_pk_bf16_f32 v219, v186, v187
	global_store_dwordx4 v[146:147], v[216:219], off
	v_pk_mul_f32 v[164:165], v[164:165], v[168:169] op_sel_hi:[1,0]
	v_pk_mul_f32 v[166:167], v[166:167], v[168:169] op_sel_hi:[1,0]
	v_pk_mul_f32 v[160:161], v[160:161], v[168:169] op_sel_hi:[1,0]
	v_pk_mul_f32 v[162:163], v[162:163], v[168:169] op_sel_hi:[1,0]
	v_exp_f32_e32 v164, v164
	v_exp_f32_e32 v165, v165
	v_exp_f32_e32 v166, v166
	v_exp_f32_e32 v167, v167
	v_exp_f32_e32 v160, v160
	v_exp_f32_e32 v161, v161
	v_exp_f32_e32 v162, v162
	v_exp_f32_e32 v163, v163
	v_add_f32_e32 v164, 1.0, v164
	v_add_f32_e32 v165, 1.0, v165
	v_add_f32_e32 v166, 1.0, v166
	v_add_f32_e32 v167, 1.0, v167
	v_add_f32_e32 v160, 1.0, v160
	v_add_f32_e32 v161, 1.0, v161
	v_add_f32_e32 v162, 1.0, v162
	v_add_f32_e32 v163, 1.0, v163
	v_rcp_f32_e32 v164, v164
	v_rcp_f32_e32 v165, v165
	v_rcp_f32_e32 v166, v166
	v_rcp_f32_e32 v167, v167
	v_rcp_f32_e32 v160, v160
	v_rcp_f32_e32 v161, v161
	v_rcp_f32_e32 v162, v162
	v_rcp_f32_e32 v163, v163
	s_nop 0
	v_cvt_pk_bf16_f32 v220, v164, v165
	v_cvt_pk_bf16_f32 v221, v166, v167
	v_cvt_pk_bf16_f32 v222, v160, v161
	v_cvt_pk_bf16_f32 v223, v162, v163
	global_store_dwordx4 v[146:147], v[220:223], off offset:256
	v_lshl_add_u64 v[150:151], v[146:147], 0, s[2:3]
	v_pk_mul_f32 v[156:157], v[156:157], v[170:171] op_sel_hi:[1,0]
	v_pk_mul_f32 v[158:159], v[158:159], v[170:171] op_sel_hi:[1,0]
	v_pk_mul_f32 v[152:153], v[152:153], v[170:171] op_sel_hi:[1,0]
	v_pk_mul_f32 v[154:155], v[154:155], v[170:171] op_sel_hi:[1,0]
	v_exp_f32_e32 v156, v156
	v_exp_f32_e32 v157, v157
	v_exp_f32_e32 v158, v158
	v_exp_f32_e32 v159, v159
	v_exp_f32_e32 v152, v152
	v_exp_f32_e32 v153, v153
	v_exp_f32_e32 v154, v154
	v_exp_f32_e32 v155, v155
	v_add_f32_e32 v156, 1.0, v156
	v_add_f32_e32 v157, 1.0, v157
	v_add_f32_e32 v158, 1.0, v158
	v_add_f32_e32 v159, 1.0, v159
	v_add_f32_e32 v152, 1.0, v152
	v_add_f32_e32 v153, 1.0, v153
	v_add_f32_e32 v154, 1.0, v154
	v_add_f32_e32 v155, 1.0, v155
	v_rcp_f32_e32 v156, v156
	v_rcp_f32_e32 v157, v157
	v_rcp_f32_e32 v158, v158
	v_rcp_f32_e32 v159, v159
	v_rcp_f32_e32 v152, v152
	v_rcp_f32_e32 v153, v153
	v_rcp_f32_e32 v154, v154
	v_rcp_f32_e32 v155, v155
	s_nop 0
	v_cvt_pk_bf16_f32 v224, v156, v157
	v_cvt_pk_bf16_f32 v225, v158, v159
	v_cvt_pk_bf16_f32 v226, v152, v153
	v_cvt_pk_bf16_f32 v227, v154, v155
	global_store_dwordx4 v[150:151], v[224:227], off
	v_pk_mul_f32 v[132:133], v[132:133], v[170:171] op_sel_hi:[1,0]
	v_pk_mul_f32 v[134:135], v[134:135], v[170:171] op_sel_hi:[1,0]
	v_pk_mul_f32 v[128:129], v[128:129], v[170:171] op_sel_hi:[1,0]
	v_pk_mul_f32 v[130:131], v[130:131], v[170:171] op_sel_hi:[1,0]
	v_exp_f32_e32 v132, v132
	v_exp_f32_e32 v133, v133
	v_exp_f32_e32 v134, v134
	v_exp_f32_e32 v135, v135
	v_exp_f32_e32 v128, v128
	v_exp_f32_e32 v129, v129
	v_exp_f32_e32 v130, v130
	v_exp_f32_e32 v131, v131
	v_add_f32_e32 v132, 1.0, v132
	v_add_f32_e32 v133, 1.0, v133
	v_add_f32_e32 v134, 1.0, v134
	v_add_f32_e32 v135, 1.0, v135
	v_add_f32_e32 v128, 1.0, v128
	v_add_f32_e32 v129, 1.0, v129
	v_add_f32_e32 v130, 1.0, v130
	v_add_f32_e32 v131, 1.0, v131
	v_rcp_f32_e32 v132, v132
	v_rcp_f32_e32 v133, v133
	v_rcp_f32_e32 v134, v134
	v_rcp_f32_e32 v135, v135
	v_rcp_f32_e32 v128, v128
	v_rcp_f32_e32 v129, v129
	v_rcp_f32_e32 v130, v130
	v_rcp_f32_e32 v131, v131
	s_nop 0
	v_cvt_pk_bf16_f32 v228, v132, v133
	v_cvt_pk_bf16_f32 v229, v134, v135
	v_cvt_pk_bf16_f32 v230, v128, v129
	v_cvt_pk_bf16_f32 v231, v130, v131
	global_store_dwordx4 v[150:151], v[228:231], off offset:256
	v_lshl_add_u64 v[146:147], v[150:151], 0, s[2:3]
	v_pk_mul_f32 v[124:125], v[124:125], v[172:173] op_sel_hi:[1,0]
	v_pk_mul_f32 v[126:127], v[126:127], v[172:173] op_sel_hi:[1,0]
	v_pk_mul_f32 v[120:121], v[120:121], v[172:173] op_sel_hi:[1,0]
	v_pk_mul_f32 v[122:123], v[122:123], v[172:173] op_sel_hi:[1,0]
	v_exp_f32_e32 v124, v124
	v_exp_f32_e32 v125, v125
	v_exp_f32_e32 v126, v126
	v_exp_f32_e32 v127, v127
	v_exp_f32_e32 v120, v120
	v_exp_f32_e32 v121, v121
	v_exp_f32_e32 v122, v122
	v_exp_f32_e32 v123, v123
	v_add_f32_e32 v124, 1.0, v124
	v_add_f32_e32 v125, 1.0, v125
	v_add_f32_e32 v126, 1.0, v126
	v_add_f32_e32 v127, 1.0, v127
	v_add_f32_e32 v120, 1.0, v120
	v_add_f32_e32 v121, 1.0, v121
	v_add_f32_e32 v122, 1.0, v122
; __device__ __forceinline__ unsigned cvt_pk_bf16(float lo, float hi) { unsigned r; asm volatile("v_cvt_pk_bf16_f32 %0, %1, %2" : "=v"(r) : "v"(lo), "v"(hi)); return r; }
; #define GAS __attribute__((address_space(1)))
;     DI void operator()(AccRef acc, const pg8::Unit& u, int wr, int wc, int, int) const {
;     ...
;                 { const float rsk = (kind == 4) ? rs * -1.4426950408889634f : rs; v0 = v0 * rsk; v1 = v1 * rsk; }
;     ...
;                 } else if (kind == 4) {
; #pragma unroll
;                     for (int e = 0; e < 4; ++e) { v0[e] = __builtin_amdgcn_rcpf(1.0f + __builtin_amdgcn_exp2f(v0[e])); v1[e] = __builtin_amdgcn_rcpf(1.0f + __builtin_amdgcn_exp2f(v1[e])); }
;                 }
;                 u32x4 w; w.x = cvt_pk_bf16(v0[0], v0[1]); w.y = cvt_pk_bf16(v0[2], v0[3]); w.z = cvt_pk_bf16(v1[0], v1[1]); w.w = cvt_pk_bf16(v1[2], v1[3]);
;                 *(GAS u32x4*)(dummy ? dummy + lane_ * 8 : Z + (size_t)lrow * ldz + col) = w;
	v_add_f32_e32 v123, 1.0, v123
	v_rcp_f32_e32 v124, v124
	v_rcp_f32_e32 v125, v125
	v_rcp_f32_e32 v126, v126
	v_rcp_f32_e32 v127, v127
	v_rcp_f32_e32 v120, v120
	v_rcp_f32_e32 v121, v121
	v_rcp_f32_e32 v122, v122
	v_rcp_f32_e32 v123, v123
	s_nop 0
	v_cvt_pk_bf16_f32 v216, v124, v125
	v_cvt_pk_bf16_f32 v217, v126, v127
	v_cvt_pk_bf16_f32 v218, v120, v121
	v_cvt_pk_bf16_f32 v219, v122, v123
	global_store_dwordx4 v[146:147], v[216:219], off
	v_pk_mul_f32 v[100:101], v[100:101], v[172:173] op_sel_hi:[1,0]
	v_pk_mul_f32 v[102:103], v[102:103], v[172:173] op_sel_hi:[1,0]
	v_pk_mul_f32 v[96:97], v[96:97], v[172:173] op_sel_hi:[1,0]
	v_pk_mul_f32 v[98:99], v[98:99], v[172:173] op_sel_hi:[1,0]
	v_exp_f32_e32 v100, v100
	v_exp_f32_e32 v101, v101
	v_exp_f32_e32 v102, v102
	v_exp_f32_e32 v103, v103
	v_exp_f32_e32 v96, v96
	v_exp_f32_e32 v97, v97
	v_exp_f32_e32 v98, v98
	v_exp_f32_e32 v99, v99
	v_add_f32_e32 v100, 1.0, v100
	v_add_f32_e32 v101, 1.0, v101
	v_add_f32_e32 v102, 1.0, v102
	v_add_f32_e32 v103, 1.0, v103
	v_add_f32_e32 v96, 1.0, v96
	v_add_f32_e32 v97, 1.0, v97
	v_add_f32_e32 v98, 1.0, v98
	v_add_f32_e32 v99, 1.0, v99
	v_rcp_f32_e32 v100, v100
	v_rcp_f32_e32 v101, v101
	v_rcp_f32_e32 v102, v102
	v_rcp_f32_e32 v103, v103
	v_rcp_f32_e32 v96, v96
	v_rcp_f32_e32 v97, v97
	v_rcp_f32_e32 v98, v98
	v_rcp_f32_e32 v99, v99
	s_nop 0
	v_cvt_pk_bf16_f32 v220, v100, v101
	v_cvt_pk_bf16_f32 v221, v102, v103
	v_cvt_pk_bf16_f32 v222, v96, v97
	v_cvt_pk_bf16_f32 v223, v98, v99
	global_store_dwordx4 v[146:147], v[220:223], off offset:256
	v_lshl_add_u64 v[150:151], v[146:147], 0, s[2:3]
	v_pk_mul_f32 v[92:93], v[92:93], v[174:175] op_sel_hi:[1,0]
	v_pk_mul_f32 v[94:95], v[94:95], v[174:175] op_sel_hi:[1,0]
	v_pk_mul_f32 v[88:89], v[88:89], v[174:175] op_sel_hi:[1,0]
	v_pk_mul_f32 v[90:91], v[90:91], v[174:175] op_sel_hi:[1,0]
	v_exp_f32_e32 v92, v92
	v_exp_f32_e32 v93, v93
	v_exp_f32_e32 v94, v94
	v_exp_f32_e32 v95, v95
	v_exp_f32_e32 v88, v88
	v_exp_f32_e32 v89, v89
	v_exp_f32_e32 v90, v90
	v_exp_f32_e32 v91, v91
	v_add_f32_e32 v92, 1.0, v92
	v_add_f32_e32 v93, 1.0, v93
	v_add_f32_e32 v94, 1.0, v94
	v_add_f32_e32 v95, 1.0, v95
	v_add_f32_e32 v88, 1.0, v88
	v_add_f32_e32 v89, 1.0, v89
	v_add_f32_e32 v90, 1.0, v90
	v_add_f32_e32 v91, 1.0, v91
	v_rcp_f32_e32 v92, v92
	v_rcp_f32_e32 v93, v93
	v_rcp_f32_e32 v94, v94
	v_rcp_f32_e32 v95, v95
	v_rcp_f32_e32 v88, v88
	v_rcp_f32_e32 v89, v89
	v_rcp_f32_e32 v90, v90
	v_rcp_f32_e32 v91, v91
	s_nop 0
	v_cvt_pk_bf16_f32 v224, v92, v93
	v_cvt_pk_bf16_f32 v225, v94, v95
	v_cvt_pk_bf16_f32 v226, v88, v89
	v_cvt_pk_bf16_f32 v227, v90, v91
	global_store_dwordx4 v[150:151], v[224:227], off
	v_pk_mul_f32 v[68:69], v[68:69], v[174:175] op_sel_hi:[1,0]
	v_pk_mul_f32 v[70:71], v[70:71], v[174:175] op_sel_hi:[1,0]
	v_pk_mul_f32 v[64:65], v[64:65], v[174:175] op_sel_hi:[1,0]
	v_pk_mul_f32 v[66:67], v[66:67], v[174:175] op_sel_hi:[1,0]
	v_exp_f32_e32 v68, v68
	v_exp_f32_e32 v69, v69
	v_exp_f32_e32 v70, v70
	v_exp_f32_e32 v71, v71
	v_exp_f32_e32 v64, v64
	v_exp_f32_e32 v65, v65
	v_exp_f32_e32 v66, v66
	v_exp_f32_e32 v67, v67
	v_add_f32_e32 v68, 1.0, v68
	v_add_f32_e32 v69, 1.0, v69
	v_add_f32_e32 v70, 1.0, v70
	v_add_f32_e32 v71, 1.0, v71
	v_add_f32_e32 v64, 1.0, v64
	v_add_f32_e32 v65, 1.0, v65
	v_add_f32_e32 v66, 1.0, v66
	v_add_f32_e32 v67, 1.0, v67
	v_rcp_f32_e32 v68, v68
	v_rcp_f32_e32 v69, v69
	v_rcp_f32_e32 v70, v70
	v_rcp_f32_e32 v71, v71
	v_rcp_f32_e32 v64, v64
	v_rcp_f32_e32 v65, v65
	v_rcp_f32_e32 v66, v66
	v_rcp_f32_e32 v67, v67
	s_nop 0
	v_cvt_pk_bf16_f32 v228, v68, v69
	v_cvt_pk_bf16_f32 v229, v70, v71
	v_cvt_pk_bf16_f32 v230, v64, v65
	v_cvt_pk_bf16_f32 v231, v66, v67
	global_store_dwordx4 v[150:151], v[228:231], off offset:256
	v_lshl_add_u64 v[146:147], v[150:151], 0, s[0:1]
	v_pk_mul_f32 v[60:61], v[60:61], v[176:177] op_sel_hi:[1,0]
	v_pk_mul_f32 v[62:63], v[62:63], v[176:177] op_sel_hi:[1,0]
	v_pk_mul_f32 v[56:57], v[56:57], v[176:177] op_sel_hi:[1,0]
	v_pk_mul_f32 v[58:59], v[58:59], v[176:177] op_sel_hi:[1,0]
	v_exp_f32_e32 v60, v60
	v_exp_f32_e32 v61, v61
	v_exp_f32_e32 v62, v62
	v_exp_f32_e32 v63, v63
	v_exp_f32_e32 v56, v56
	v_exp_f32_e32 v57, v57
	v_exp_f32_e32 v58, v58
	v_exp_f32_e32 v59, v59
	v_add_f32_e32 v60, 1.0, v60
	v_add_f32_e32 v61, 1.0, v61
	v_add_f32_e32 v62, 1.0, v62
	v_add_f32_e32 v63, 1.0, v63
	v_add_f32_e32 v56, 1.0, v56
	v_add_f32_e32 v57, 1.0, v57
	v_add_f32_e32 v58, 1.0, v58
	v_add_f32_e32 v59, 1.0, v59
	v_rcp_f32_e32 v60, v60
	v_rcp_f32_e32 v61, v61
	v_rcp_f32_e32 v62, v62
	v_rcp_f32_e32 v63, v63
	v_rcp_f32_e32 v56, v56
	v_rcp_f32_e32 v57, v57
	v_rcp_f32_e32 v58, v58
	v_rcp_f32_e32 v59, v59
	s_nop 0
	v_cvt_pk_bf16_f32 v216, v60, v61
	v_cvt_pk_bf16_f32 v217, v62, v63
	v_cvt_pk_bf16_f32 v218, v56, v57
	v_cvt_pk_bf16_f32 v219, v58, v59
	global_store_dwordx4 v[146:147], v[216:219], off
	v_pk_mul_f32 v[52:53], v[52:53], v[176:177] op_sel_hi:[1,0]
	v_pk_mul_f32 v[54:55], v[54:55], v[176:177] op_sel_hi:[1,0]
	v_pk_mul_f32 v[48:49], v[48:49], v[176:177] op_sel_hi:[1,0]
	v_pk_mul_f32 v[50:51], v[50:51], v[176:177] op_sel_hi:[1,0]
	v_exp_f32_e32 v52, v52
	v_exp_f32_e32 v53, v53
	v_exp_f32_e32 v54, v54
	v_exp_f32_e32 v55, v55
	v_exp_f32_e32 v48, v48
	v_exp_f32_e32 v49, v49
	v_exp_f32_e32 v50, v50
	v_exp_f32_e32 v51, v51
	v_add_f32_e32 v52, 1.0, v52
	v_add_f32_e32 v53, 1.0, v53
	v_add_f32_e32 v54, 1.0, v54
	v_add_f32_e32 v55, 1.0, v55
	v_add_f32_e32 v48, 1.0, v48
	v_add_f32_e32 v49, 1.0, v49
	v_add_f32_e32 v50, 1.0, v50
	v_add_f32_e32 v51, 1.0, v51
	v_rcp_f32_e32 v52, v52
	v_rcp_f32_e32 v53, v53
	v_rcp_f32_e32 v54, v54
	v_rcp_f32_e32 v55, v55
	v_rcp_f32_e32 v48, v48
	v_rcp_f32_e32 v49, v49
; __device__ __forceinline__ unsigned cvt_pk_bf16(float lo, float hi) { unsigned r; asm volatile("v_cvt_pk_bf16_f32 %0, %1, %2" : "=v"(r) : "v"(lo), "v"(hi)); return r; }
; #define GAS __attribute__((address_space(1)))
;     DI void operator()(AccRef acc, const pg8::Unit& u, int wr, int wc, int, int) const {
;     ...
;                 { const float rsk = (kind == 4) ? rs * -1.4426950408889634f : rs; v0 = v0 * rsk; v1 = v1 * rsk; }
;     ...
;                 } else if (kind == 4) {
; #pragma unroll
;                     for (int e = 0; e < 4; ++e) { v0[e] = __builtin_amdgcn_rcpf(1.0f + __builtin_amdgcn_exp2f(v0[e])); v1[e] = __builtin_amdgcn_rcpf(1.0f + __builtin_amdgcn_exp2f(v1[e])); }
;                 }
;                 u32x4 w; w.x = cvt_pk_bf16(v0[0], v0[1]); w.y = cvt_pk_bf16(v0[2], v0[3]); w.z = cvt_pk_bf16(v1[0], v1[1]); w.w = cvt_pk_bf16(v1[2], v1[3]);
;                 *(GAS u32x4*)(dummy ? dummy + lane_ * 8 : Z + (size_t)lrow * ldz + col) = w;
	v_rcp_f32_e32 v50, v50
	v_rcp_f32_e32 v51, v51
	s_nop 0
	v_cvt_pk_bf16_f32 v220, v52, v53
	v_cvt_pk_bf16_f32 v221, v54, v55
	v_cvt_pk_bf16_f32 v222, v48, v49
	v_cvt_pk_bf16_f32 v223, v50, v51
	global_store_dwordx4 v[146:147], v[220:223], off offset:256
	v_lshl_add_u64 v[150:151], v[146:147], 0, s[2:3]
	v_pk_mul_f32 v[44:45], v[44:45], v[178:179] op_sel_hi:[1,0]
	v_pk_mul_f32 v[46:47], v[46:47], v[178:179] op_sel_hi:[1,0]
	v_pk_mul_f32 v[40:41], v[40:41], v[178:179] op_sel_hi:[1,0]
	v_pk_mul_f32 v[42:43], v[42:43], v[178:179] op_sel_hi:[1,0]
	v_exp_f32_e32 v44, v44
	v_exp_f32_e32 v45, v45
	v_exp_f32_e32 v46, v46
	v_exp_f32_e32 v47, v47
	v_exp_f32_e32 v40, v40
	v_exp_f32_e32 v41, v41
	v_exp_f32_e32 v42, v42
	v_exp_f32_e32 v43, v43
	v_add_f32_e32 v44, 1.0, v44
	v_add_f32_e32 v45, 1.0, v45
	v_add_f32_e32 v46, 1.0, v46
	v_add_f32_e32 v47, 1.0, v47
	v_add_f32_e32 v40, 1.0, v40
	v_add_f32_e32 v41, 1.0, v41
	v_add_f32_e32 v42, 1.0, v42
	v_add_f32_e32 v43, 1.0, v43
	v_rcp_f32_e32 v44, v44
	v_rcp_f32_e32 v45, v45
	v_rcp_f32_e32 v46, v46
	v_rcp_f32_e32 v47, v47
	v_rcp_f32_e32 v40, v40
	v_rcp_f32_e32 v41, v41
	v_rcp_f32_e32 v42, v42
	v_rcp_f32_e32 v43, v43
	s_nop 0
	v_cvt_pk_bf16_f32 v224, v44, v45
	v_cvt_pk_bf16_f32 v225, v46, v47
	v_cvt_pk_bf16_f32 v226, v40, v41
	v_cvt_pk_bf16_f32 v227, v42, v43
	global_store_dwordx4 v[150:151], v[224:227], off
	v_pk_mul_f32 v[36:37], v[36:37], v[178:179] op_sel_hi:[1,0]
	v_pk_mul_f32 v[38:39], v[38:39], v[178:179] op_sel_hi:[1,0]
	v_pk_mul_f32 v[32:33], v[32:33], v[178:179] op_sel_hi:[1,0]
	v_pk_mul_f32 v[34:35], v[34:35], v[178:179] op_sel_hi:[1,0]
	v_exp_f32_e32 v36, v36
	v_exp_f32_e32 v37, v37
	v_exp_f32_e32 v38, v38
	v_exp_f32_e32 v39, v39
	v_exp_f32_e32 v32, v32
	v_exp_f32_e32 v33, v33
	v_exp_f32_e32 v34, v34
	v_exp_f32_e32 v35, v35
	v_add_f32_e32 v36, 1.0, v36
	v_add_f32_e32 v37, 1.0, v37
	v_add_f32_e32 v38, 1.0, v38
	v_add_f32_e32 v39, 1.0, v39
	v_add_f32_e32 v32, 1.0, v32
	v_add_f32_e32 v33, 1.0, v33
	v_add_f32_e32 v34, 1.0, v34
	v_add_f32_e32 v35, 1.0, v35
	v_rcp_f32_e32 v36, v36
	v_rcp_f32_e32 v37, v37
	v_rcp_f32_e32 v38, v38
	v_rcp_f32_e32 v39, v39
	v_rcp_f32_e32 v32, v32
	v_rcp_f32_e32 v33, v33
	v_rcp_f32_e32 v34, v34
	v_rcp_f32_e32 v35, v35
	s_nop 0
	v_cvt_pk_bf16_f32 v228, v36, v37
	v_cvt_pk_bf16_f32 v229, v38, v39
	v_cvt_pk_bf16_f32 v230, v32, v33
	v_cvt_pk_bf16_f32 v231, v34, v35
	global_store_dwordx4 v[150:151], v[228:231], off offset:256
	v_lshl_add_u64 v[146:147], v[150:151], 0, s[2:3]
	v_pk_mul_f32 v[28:29], v[28:29], v[180:181] op_sel_hi:[1,0]
	v_pk_mul_f32 v[30:31], v[30:31], v[180:181] op_sel_hi:[1,0]
	v_pk_mul_f32 v[24:25], v[24:25], v[180:181] op_sel_hi:[1,0]
	v_pk_mul_f32 v[26:27], v[26:27], v[180:181] op_sel_hi:[1,0]
	v_exp_f32_e32 v28, v28
	v_exp_f32_e32 v29, v29
	v_exp_f32_e32 v30, v30
	v_exp_f32_e32 v31, v31
	v_exp_f32_e32 v24, v24
	v_exp_f32_e32 v25, v25
	v_exp_f32_e32 v26, v26
	v_exp_f32_e32 v27, v27
	v_add_f32_e32 v28, 1.0, v28
	v_add_f32_e32 v29, 1.0, v29
	v_add_f32_e32 v30, 1.0, v30
	v_add_f32_e32 v31, 1.0, v31
	v_add_f32_e32 v24, 1.0, v24
	v_add_f32_e32 v25, 1.0, v25
	v_add_f32_e32 v26, 1.0, v26
	v_add_f32_e32 v27, 1.0, v27
	v_rcp_f32_e32 v28, v28
	v_rcp_f32_e32 v29, v29
	v_rcp_f32_e32 v30, v30
	v_rcp_f32_e32 v31, v31
	v_rcp_f32_e32 v24, v24
	v_rcp_f32_e32 v25, v25
	v_rcp_f32_e32 v26, v26
	v_rcp_f32_e32 v27, v27
	s_nop 0
	v_cvt_pk_bf16_f32 v216, v28, v29
	v_cvt_pk_bf16_f32 v217, v30, v31
	v_cvt_pk_bf16_f32 v218, v24, v25
	v_cvt_pk_bf16_f32 v219, v26, v27
	global_store_dwordx4 v[146:147], v[216:219], off
	v_pk_mul_f32 v[20:21], v[20:21], v[180:181] op_sel_hi:[1,0]
	v_pk_mul_f32 v[22:23], v[22:23], v[180:181] op_sel_hi:[1,0]
	v_pk_mul_f32 v[16:17], v[16:17], v[180:181] op_sel_hi:[1,0]
	v_pk_mul_f32 v[18:19], v[18:19], v[180:181] op_sel_hi:[1,0]
	v_exp_f32_e32 v20, v20
	v_exp_f32_e32 v21, v21
	v_exp_f32_e32 v22, v22
	v_exp_f32_e32 v23, v23
	v_exp_f32_e32 v16, v16
	v_exp_f32_e32 v17, v17
	v_exp_f32_e32 v18, v18
	v_exp_f32_e32 v19, v19
	v_add_f32_e32 v20, 1.0, v20
	v_add_f32_e32 v21, 1.0, v21
	v_add_f32_e32 v22, 1.0, v22
	v_add_f32_e32 v23, 1.0, v23
	v_add_f32_e32 v16, 1.0, v16
	v_add_f32_e32 v17, 1.0, v17
	v_add_f32_e32 v18, 1.0, v18
	v_add_f32_e32 v19, 1.0, v19
	v_rcp_f32_e32 v20, v20
	v_rcp_f32_e32 v21, v21
	v_rcp_f32_e32 v22, v22
	v_rcp_f32_e32 v23, v23
	v_rcp_f32_e32 v16, v16
	v_rcp_f32_e32 v17, v17
	v_rcp_f32_e32 v18, v18
	v_rcp_f32_e32 v19, v19
	s_nop 0
	v_cvt_pk_bf16_f32 v220, v20, v21
	v_cvt_pk_bf16_f32 v221, v22, v23
	v_cvt_pk_bf16_f32 v222, v16, v17
	v_cvt_pk_bf16_f32 v223, v18, v19
	global_store_dwordx4 v[146:147], v[220:223], off offset:256
	v_lshl_add_u64 v[150:151], v[146:147], 0, s[2:3]
	v_pk_mul_f32 v[12:13], v[12:13], v[182:183] op_sel_hi:[1,0]
	v_pk_mul_f32 v[14:15], v[14:15], v[182:183] op_sel_hi:[1,0]
	v_pk_mul_f32 v[8:9], v[8:9], v[182:183] op_sel_hi:[1,0]
	v_pk_mul_f32 v[10:11], v[10:11], v[182:183] op_sel_hi:[1,0]
	v_exp_f32_e32 v12, v12
	v_exp_f32_e32 v13, v13
	v_exp_f32_e32 v14, v14
	v_exp_f32_e32 v15, v15
	v_exp_f32_e32 v8, v8
	v_exp_f32_e32 v9, v9
	v_exp_f32_e32 v10, v10
	v_exp_f32_e32 v11, v11
	v_add_f32_e32 v12, 1.0, v12
	v_add_f32_e32 v13, 1.0, v13
	v_add_f32_e32 v14, 1.0, v14
	v_add_f32_e32 v15, 1.0, v15
	v_add_f32_e32 v8, 1.0, v8
	v_add_f32_e32 v9, 1.0, v9
	v_add_f32_e32 v10, 1.0, v10
	v_add_f32_e32 v11, 1.0, v11
	v_rcp_f32_e32 v12, v12
	v_rcp_f32_e32 v13, v13
	v_rcp_f32_e32 v14, v14
	v_rcp_f32_e32 v15, v15
	v_rcp_f32_e32 v8, v8
	v_rcp_f32_e32 v9, v9
	v_rcp_f32_e32 v10, v10
	v_rcp_f32_e32 v11, v11
	s_nop 0
	v_cvt_pk_bf16_f32 v224, v12, v13
	v_cvt_pk_bf16_f32 v225, v14, v15
	v_cvt_pk_bf16_f32 v226, v8, v9
	v_cvt_pk_bf16_f32 v227, v10, v11
	global_store_dwordx4 v[150:151], v[224:227], off
	v_pk_mul_f32 v[4:5], v[4:5], v[182:183] op_sel_hi:[1,0]
	v_pk_mul_f32 v[6:7], v[6:7], v[182:183] op_sel_hi:[1,0]
	v_pk_mul_f32 v[0:1], v[0:1], v[182:183] op_sel_hi:[1,0]
	v_pk_mul_f32 v[2:3], v[2:3], v[182:183] op_sel_hi:[1,0]
	v_exp_f32_e32 v4, v4
	v_exp_f32_e32 v5, v5
	v_exp_f32_e32 v6, v6
	v_exp_f32_e32 v7, v7
	v_exp_f32_e32 v0, v0
	v_exp_f32_e32 v1, v1
	v_exp_f32_e32 v2, v2
	v_exp_f32_e32 v3, v3
	v_add_f32_e32 v4, 1.0, v4
	v_add_f32_e32 v5, 1.0, v5
	v_add_f32_e32 v6, 1.0, v6
	v_add_f32_e32 v7, 1.0, v7
	v_add_f32_e32 v0, 1.0, v0
	v_add_f32_e32 v1, 1.0, v1
	v_add_f32_e32 v2, 1.0, v2
	v_add_f32_e32 v3, 1.0, v3
	v_rcp_f32_e32 v4, v4
	v_rcp_f32_e32 v5, v5
	v_rcp_f32_e32 v6, v6
	v_rcp_f32_e32 v7, v7
	v_rcp_f32_e32 v0, v0
	v_rcp_f32_e32 v1, v1
	v_rcp_f32_e32 v2, v2
	v_rcp_f32_e32 v3, v3
	s_nop 0
	v_cvt_pk_bf16_f32 v228, v4, v5
	v_cvt_pk_bf16_f32 v229, v6, v7
	v_cvt_pk_bf16_f32 v230, v0, v1
	v_cvt_pk_bf16_f32 v231, v2, v3
	global_store_dwordx4 v[150:151], v[228:231], off offset:256
	s_branch .Llean_F_exit
; __device__ __forceinline__ unsigned cvt_pk_bf16(float lo, float hi) { unsigned r; asm volatile("v_cvt_pk_bf16_f32 %0, %1, %2" : "=v"(r) : "v"(lo), "v"(hi)); return r; }
; #define GAS __attribute__((address_space(1)))
; __device__ __forceinline__ f32x2 gelu_pk(f32x2 v) {
;     const f32x2 av = __builtin_elementwise_abs(v), d = av * 0.2316418882f + 1.0f;
;     f32x2 t; t.x = __builtin_amdgcn_rcpf(d.x); t.y = __builtin_amdgcn_rcpf(d.y);
;     f32x2 q = t * 0.5307027145f + (-0.7265760135f); q = q * t + 0.7107068705f; q = q * t + (-0.142248368f); q = q * t + 0.127414796f; q = q * t;
;     const f32x2 s = (v * v) * (-0.72134752044f);
;     f32x2 e; e.x = __builtin_amdgcn_exp2f(s.x); e.y = __builtin_amdgcn_exp2f(s.y);
;     const f32x2 m = v * (q * e), r = v - m;
;     f32x2 o; o.x = v.x < 0.f ? m.x : r.x; o.y = v.y < 0.f ? m.y : r.y; return o;
; }
;     DI void operator()(AccRef acc, const pg8::Unit& u, int wr, int wc, int, int) const {
;     ...
;                 } else if (kind == 3) {
;                     f32x2 a = pg8::gelu_pk((f32x2){v0[0], v0[1]}), b = pg8::gelu_pk((f32x2){v0[2], v0[3]}), c = pg8::gelu_pk((f32x2){v1[0], v1[1]}), d = pg8::gelu_pk((f32x2){v1[2], v1[3]});
;                     v0 = (f32x4){a.x, a.y, b.x, b.y}; v1 = (f32x4){c.x, c.y, d.x, d.y};
;                 } else if (kind == 4) {
; #pragma unroll
;                     for (int e = 0; e < 4; ++e) { v0[e] = __builtin_amdgcn_rcpf(1.0f + __builtin_amdgcn_exp2f(v0[e])); v1[e] = __builtin_amdgcn_rcpf(1.0f + __builtin_amdgcn_exp2f(v1[e])); }
;                 }
;                 u32x4 w; w.x = cvt_pk_bf16(v0[0], v0[1]); w.y = cvt_pk_bf16(v0[2], v0[3]); w.z = cvt_pk_bf16(v1[0], v1[1]); w.w = cvt_pk_bf16(v1[2], v1[3]);
;                 *(GAS u32x4*)(dummy ? dummy + lane_ * 8 : Z + (size_t)lrow * ldz + col) = w;
.Llean_F_gelu:
	v_mov_b64_e32 v[144:145], s[46:47]
	v_pk_mul_f32 v[188:189], v[188:189], v[168:169] op_sel_hi:[1,0]
	v_pk_mul_f32 v[190:191], v[190:191], v[168:169] op_sel_hi:[1,0]
	v_pk_mul_f32 v[184:185], v[184:185], v[168:169] op_sel_hi:[1,0]
	v_pk_mul_f32 v[186:187], v[186:187], v[168:169] op_sel_hi:[1,0]
	v_and_b32_e32 v72, 0x7fffffff, v188
	v_and_b32_e32 v73, 0x7fffffff, v189
	v_and_b32_e32 v80, 0x7fffffff, v190
	v_and_b32_e32 v81, 0x7fffffff, v191
	v_and_b32_e32 v104, 0x7fffffff, v184
	v_and_b32_e32 v105, 0x7fffffff, v185
	v_and_b32_e32 v112, 0x7fffffff, v186
	v_and_b32_e32 v113, 0x7fffffff, v187
	v_pk_fma_f32 v[72:73], v[72:73], s[42:43], 1.0 op_sel_hi:[1,0,0]
	v_pk_fma_f32 v[80:81], v[80:81], s[42:43], 1.0 op_sel_hi:[1,0,0]
	v_pk_fma_f32 v[104:105], v[104:105], s[42:43], 1.0 op_sel_hi:[1,0,0]
	v_pk_fma_f32 v[112:113], v[112:113], s[42:43], 1.0 op_sel_hi:[1,0,0]
	v_pk_mul_f32 v[78:79], v[188:189], v[188:189]
	v_pk_mul_f32 v[86:87], v[190:191], v[190:191]
	v_pk_mul_f32 v[110:111], v[184:185], v[184:185]
	v_pk_mul_f32 v[118:119], v[186:187], v[186:187]
	v_rcp_f32_e32 v74, v72
	v_rcp_f32_e32 v75, v73
	v_rcp_f32_e32 v82, v80
	v_rcp_f32_e32 v83, v81
	v_rcp_f32_e32 v106, v104
	v_rcp_f32_e32 v107, v105
	v_rcp_f32_e32 v114, v112
	v_rcp_f32_e32 v115, v113
	v_pk_mul_f32 v[78:79], v[78:79], s[54:55] op_sel_hi:[1,0]
	v_pk_mul_f32 v[86:87], v[86:87], s[54:55] op_sel_hi:[1,0]
	v_pk_mul_f32 v[110:111], v[110:111], s[54:55] op_sel_hi:[1,0]
	v_pk_mul_f32 v[118:119], v[118:119], s[54:55] op_sel_hi:[1,0]
	v_pk_fma_f32 v[76:77], v[74:75], s[44:45], v[144:145] op_sel_hi:[1,0,0]
	v_pk_fma_f32 v[84:85], v[82:83], s[44:45], v[144:145] op_sel_hi:[1,0,0]
	v_pk_fma_f32 v[108:109], v[106:107], s[44:45], v[144:145] op_sel_hi:[1,0,0]
	v_pk_fma_f32 v[116:117], v[114:115], s[44:45], v[144:145] op_sel_hi:[1,0,0]
	v_exp_f32_e32 v78, v78
	v_exp_f32_e32 v79, v79
	v_exp_f32_e32 v86, v86
	v_exp_f32_e32 v87, v87
	v_exp_f32_e32 v110, v110
	v_exp_f32_e32 v111, v111
	v_exp_f32_e32 v118, v118
	v_exp_f32_e32 v119, v119
	v_pk_fma_f32 v[76:77], v[74:75], v[76:77], s[48:49] op_sel_hi:[1,1,0]
	v_pk_fma_f32 v[84:85], v[82:83], v[84:85], s[48:49] op_sel_hi:[1,1,0]
	v_pk_fma_f32 v[108:109], v[106:107], v[108:109], s[48:49] op_sel_hi:[1,1,0]
	v_pk_fma_f32 v[116:117], v[114:115], v[116:117], s[48:49] op_sel_hi:[1,1,0]
	v_pk_fma_f32 v[76:77], v[74:75], v[76:77], s[50:51] op_sel_hi:[1,1,0]
	v_pk_fma_f32 v[84:85], v[82:83], v[84:85], s[50:51] op_sel_hi:[1,1,0]
	v_pk_fma_f32 v[108:109], v[106:107], v[108:109], s[50:51] op_sel_hi:[1,1,0]
	v_pk_fma_f32 v[116:117], v[114:115], v[116:117], s[50:51] op_sel_hi:[1,1,0]
	v_pk_fma_f32 v[76:77], v[74:75], v[76:77], s[52:53] op_sel_hi:[1,1,0]
	v_pk_fma_f32 v[84:85], v[82:83], v[84:85], s[52:53] op_sel_hi:[1,1,0]
	v_pk_fma_f32 v[108:109], v[106:107], v[108:109], s[52:53] op_sel_hi:[1,1,0]
	v_pk_fma_f32 v[116:117], v[114:115], v[116:117], s[52:53] op_sel_hi:[1,1,0]
	v_pk_mul_f32 v[74:75], v[74:75], v[76:77]
	v_pk_mul_f32 v[82:83], v[82:83], v[84:85]
	v_pk_mul_f32 v[106:107], v[106:107], v[108:109]
	v_pk_mul_f32 v[114:115], v[114:115], v[116:117]
	v_pk_mul_f32 v[74:75], v[78:79], v[74:75]
	v_pk_mul_f32 v[82:83], v[86:87], v[82:83]
	v_pk_mul_f32 v[106:107], v[110:111], v[106:107]
	v_pk_mul_f32 v[114:115], v[118:119], v[114:115]
	v_pk_mul_f32 v[78:79], v[188:189], v[74:75]
	v_pk_mul_f32 v[86:87], v[190:191], v[82:83]
	v_pk_mul_f32 v[110:111], v[184:185], v[106:107]
	v_pk_mul_f32 v[118:119], v[186:187], v[114:115]
	v_pk_fma_f32 v[74:75], v[188:189], v[74:75], v[188:189] neg_lo:[1,0,0] neg_hi:[1,0,0]
	v_pk_fma_f32 v[82:83], v[190:191], v[82:83], v[190:191] neg_lo:[1,0,0] neg_hi:[1,0,0]
	v_pk_fma_f32 v[106:107], v[184:185], v[106:107], v[184:185] neg_lo:[1,0,0] neg_hi:[1,0,0]
	v_pk_fma_f32 v[114:115], v[186:187], v[114:115], v[186:187] neg_lo:[1,0,0] neg_hi:[1,0,0]
	v_cmp_gt_f32_e64 s[98:99], 0, v188
	v_cmp_gt_f32_e64 s[16:17], 0, v190
	v_cmp_gt_f32_e64 s[10:11], 0, v184
	v_cmp_gt_f32_e64 s[12:13], 0, v186
	v_cndmask_b32_e64 v188, v74, v78, s[98:99]
	v_cndmask_b32_e64 v190, v82, v86, s[16:17]
	v_cndmask_b32_e64 v184, v106, v110, s[10:11]
	v_cndmask_b32_e64 v186, v114, v118, s[12:13]
	v_cmp_gt_f32_e64 s[98:99], 0, v189
	v_cmp_gt_f32_e64 s[16:17], 0, v191
	v_cmp_gt_f32_e64 s[10:11], 0, v185
	v_cmp_gt_f32_e64 s[12:13], 0, v187
	v_cndmask_b32_e64 v189, v75, v79, s[98:99]
	v_cndmask_b32_e64 v191, v83, v87, s[16:17]
	v_cndmask_b32_e64 v185, v107, v111, s[10:11]
	v_cndmask_b32_e64 v187, v115, v119, s[12:13]
	v_cvt_pk_bf16_f32 v216, v188, v189
	v_cvt_pk_bf16_f32 v217, v190, v191
	v_cvt_pk_bf16_f32 v218, v184, v185
	v_cvt_pk_bf16_f32 v219, v186, v187
	global_store_dwordx4 v[146:147], v[216:219], off
	v_pk_mul_f32 v[164:165], v[164:165], v[168:169] op_sel_hi:[1,0]
	v_pk_mul_f32 v[166:167], v[166:167], v[168:169] op_sel_hi:[1,0]
	v_pk_mul_f32 v[160:161], v[160:161], v[168:169] op_sel_hi:[1,0]
	v_pk_mul_f32 v[162:163], v[162:163], v[168:169] op_sel_hi:[1,0]
	v_and_b32_e32 v72, 0x7fffffff, v164
	v_and_b32_e32 v73, 0x7fffffff, v165
	v_and_b32_e32 v80, 0x7fffffff, v166
	v_and_b32_e32 v81, 0x7fffffff, v167
	v_and_b32_e32 v104, 0x7fffffff, v160
	v_and_b32_e32 v105, 0x7fffffff, v161
	v_and_b32_e32 v112, 0x7fffffff, v162
	v_and_b32_e32 v113, 0x7fffffff, v163
	v_pk_fma_f32 v[72:73], v[72:73], s[42:43], 1.0 op_sel_hi:[1,0,0]
	v_pk_fma_f32 v[80:81], v[80:81], s[42:43], 1.0 op_sel_hi:[1,0,0]
	v_pk_fma_f32 v[104:105], v[104:105], s[42:43], 1.0 op_sel_hi:[1,0,0]
	v_pk_fma_f32 v[112:113], v[112:113], s[42:43], 1.0 op_sel_hi:[1,0,0]
	v_pk_mul_f32 v[78:79], v[164:165], v[164:165]
	v_pk_mul_f32 v[86:87], v[166:167], v[166:167]
	v_pk_mul_f32 v[110:111], v[160:161], v[160:161]
; __device__ __forceinline__ unsigned cvt_pk_bf16(float lo, float hi) { unsigned r; asm volatile("v_cvt_pk_bf16_f32 %0, %1, %2" : "=v"(r) : "v"(lo), "v"(hi)); return r; }
; #define GAS __attribute__((address_space(1)))
; __device__ __forceinline__ f32x2 gelu_pk(f32x2 v) {
;     const f32x2 av = __builtin_elementwise_abs(v), d = av * 0.2316418882f + 1.0f;
;     f32x2 t; t.x = __builtin_amdgcn_rcpf(d.x); t.y = __builtin_amdgcn_rcpf(d.y);
;     f32x2 q = t * 0.5307027145f + (-0.7265760135f); q = q * t + 0.7107068705f; q = q * t + (-0.142248368f); q = q * t + 0.127414796f; q = q * t;
;     const f32x2 s = (v * v) * (-0.72134752044f);
;     f32x2 e; e.x = __builtin_amdgcn_exp2f(s.x); e.y = __builtin_amdgcn_exp2f(s.y);
;     const f32x2 m = v * (q * e), r = v - m;
;     f32x2 o; o.x = v.x < 0.f ? m.x : r.x; o.y = v.y < 0.f ? m.y : r.y; return o;
; }
;     DI void operator()(AccRef acc, const pg8::Unit& u, int wr, int wc, int, int) const {
;     ...
;                 } else if (kind == 3) {
;                     f32x2 a = pg8::gelu_pk((f32x2){v0[0], v0[1]}), b = pg8::gelu_pk((f32x2){v0[2], v0[3]}), c = pg8::gelu_pk((f32x2){v1[0], v1[1]}), d = pg8::gelu_pk((f32x2){v1[2], v1[3]});
;                     v0 = (f32x4){a.x, a.y, b.x, b.y}; v1 = (f32x4){c.x, c.y, d.x, d.y};
;                 } else if (kind == 4) {
; #pragma unroll
;                     for (int e = 0; e < 4; ++e) { v0[e] = __builtin_amdgcn_rcpf(1.0f + __builtin_amdgcn_exp2f(v0[e])); v1[e] = __builtin_amdgcn_rcpf(1.0f + __builtin_amdgcn_exp2f(v1[e])); }
;                 }
;                 u32x4 w; w.x = cvt_pk_bf16(v0[0], v0[1]); w.y = cvt_pk_bf16(v0[2], v0[3]); w.z = cvt_pk_bf16(v1[0], v1[1]); w.w = cvt_pk_bf16(v1[2], v1[3]);
;                 *(GAS u32x4*)(dummy ? dummy + lane_ * 8 : Z + (size_t)lrow * ldz + col) = w;
	v_pk_mul_f32 v[118:119], v[162:163], v[162:163]
	v_rcp_f32_e32 v74, v72
	v_rcp_f32_e32 v75, v73
	v_rcp_f32_e32 v82, v80
	v_rcp_f32_e32 v83, v81
	v_rcp_f32_e32 v106, v104
	v_rcp_f32_e32 v107, v105
	v_rcp_f32_e32 v114, v112
	v_rcp_f32_e32 v115, v113
	v_pk_mul_f32 v[78:79], v[78:79], s[54:55] op_sel_hi:[1,0]
	v_pk_mul_f32 v[86:87], v[86:87], s[54:55] op_sel_hi:[1,0]
	v_pk_mul_f32 v[110:111], v[110:111], s[54:55] op_sel_hi:[1,0]
	v_pk_mul_f32 v[118:119], v[118:119], s[54:55] op_sel_hi:[1,0]
	v_pk_fma_f32 v[76:77], v[74:75], s[44:45], v[144:145] op_sel_hi:[1,0,0]
	v_pk_fma_f32 v[84:85], v[82:83], s[44:45], v[144:145] op_sel_hi:[1,0,0]
	v_pk_fma_f32 v[108:109], v[106:107], s[44:45], v[144:145] op_sel_hi:[1,0,0]
	v_pk_fma_f32 v[116:117], v[114:115], s[44:45], v[144:145] op_sel_hi:[1,0,0]
	v_exp_f32_e32 v78, v78
	v_exp_f32_e32 v79, v79
	v_exp_f32_e32 v86, v86
	v_exp_f32_e32 v87, v87
	v_exp_f32_e32 v110, v110
	v_exp_f32_e32 v111, v111
	v_exp_f32_e32 v118, v118
	v_exp_f32_e32 v119, v119
	v_pk_fma_f32 v[76:77], v[74:75], v[76:77], s[48:49] op_sel_hi:[1,1,0]
	v_pk_fma_f32 v[84:85], v[82:83], v[84:85], s[48:49] op_sel_hi:[1,1,0]
	v_pk_fma_f32 v[108:109], v[106:107], v[108:109], s[48:49] op_sel_hi:[1,1,0]
	v_pk_fma_f32 v[116:117], v[114:115], v[116:117], s[48:49] op_sel_hi:[1,1,0]
	v_pk_fma_f32 v[76:77], v[74:75], v[76:77], s[50:51] op_sel_hi:[1,1,0]
	v_pk_fma_f32 v[84:85], v[82:83], v[84:85], s[50:51] op_sel_hi:[1,1,0]
	v_pk_fma_f32 v[108:109], v[106:107], v[108:109], s[50:51] op_sel_hi:[1,1,0]
	v_pk_fma_f32 v[116:117], v[114:115], v[116:117], s[50:51] op_sel_hi:[1,1,0]
	v_pk_fma_f32 v[76:77], v[74:75], v[76:77], s[52:53] op_sel_hi:[1,1,0]
	v_pk_fma_f32 v[84:85], v[82:83], v[84:85], s[52:53] op_sel_hi:[1,1,0]
	v_pk_fma_f32 v[108:109], v[106:107], v[108:109], s[52:53] op_sel_hi:[1,1,0]
	v_pk_fma_f32 v[116:117], v[114:115], v[116:117], s[52:53] op_sel_hi:[1,1,0]
	v_pk_mul_f32 v[74:75], v[74:75], v[76:77]
	v_pk_mul_f32 v[82:83], v[82:83], v[84:85]
	v_pk_mul_f32 v[106:107], v[106:107], v[108:109]
	v_pk_mul_f32 v[114:115], v[114:115], v[116:117]
	v_pk_mul_f32 v[74:75], v[78:79], v[74:75]
	v_pk_mul_f32 v[82:83], v[86:87], v[82:83]
	v_pk_mul_f32 v[106:107], v[110:111], v[106:107]
	v_pk_mul_f32 v[114:115], v[118:119], v[114:115]
	v_pk_mul_f32 v[78:79], v[164:165], v[74:75]
	v_pk_mul_f32 v[86:87], v[166:167], v[82:83]
	v_pk_mul_f32 v[110:111], v[160:161], v[106:107]
	v_pk_mul_f32 v[118:119], v[162:163], v[114:115]
	v_pk_fma_f32 v[74:75], v[164:165], v[74:75], v[164:165] neg_lo:[1,0,0] neg_hi:[1,0,0]
	v_pk_fma_f32 v[82:83], v[166:167], v[82:83], v[166:167] neg_lo:[1,0,0] neg_hi:[1,0,0]
	v_pk_fma_f32 v[106:107], v[160:161], v[106:107], v[160:161] neg_lo:[1,0,0] neg_hi:[1,0,0]
	v_pk_fma_f32 v[114:115], v[162:163], v[114:115], v[162:163] neg_lo:[1,0,0] neg_hi:[1,0,0]
	v_cmp_gt_f32_e64 s[98:99], 0, v164
	v_cmp_gt_f32_e64 s[16:17], 0, v166
	v_cmp_gt_f32_e64 s[10:11], 0, v160
	v_cmp_gt_f32_e64 s[12:13], 0, v162
	v_cndmask_b32_e64 v164, v74, v78, s[98:99]
	v_cndmask_b32_e64 v166, v82, v86, s[16:17]
	v_cndmask_b32_e64 v160, v106, v110, s[10:11]
	v_cndmask_b32_e64 v162, v114, v118, s[12:13]
	v_cmp_gt_f32_e64 s[98:99], 0, v165
	v_cmp_gt_f32_e64 s[16:17], 0, v167
	v_cmp_gt_f32_e64 s[10:11], 0, v161
	v_cmp_gt_f32_e64 s[12:13], 0, v163
	v_cndmask_b32_e64 v165, v75, v79, s[98:99]
	v_cndmask_b32_e64 v167, v83, v87, s[16:17]
	v_cndmask_b32_e64 v161, v107, v111, s[10:11]
	v_cndmask_b32_e64 v163, v115, v119, s[12:13]
	v_cvt_pk_bf16_f32 v220, v164, v165
	v_cvt_pk_bf16_f32 v221, v166, v167
	v_cvt_pk_bf16_f32 v222, v160, v161
	v_cvt_pk_bf16_f32 v223, v162, v163
	global_store_dwordx4 v[146:147], v[220:223], off offset:256
	v_lshl_add_u64 v[150:151], v[146:147], 0, s[2:3]
	v_pk_mul_f32 v[156:157], v[156:157], v[170:171] op_sel_hi:[1,0]
	v_pk_mul_f32 v[158:159], v[158:159], v[170:171] op_sel_hi:[1,0]
	v_pk_mul_f32 v[152:153], v[152:153], v[170:171] op_sel_hi:[1,0]
	v_pk_mul_f32 v[154:155], v[154:155], v[170:171] op_sel_hi:[1,0]
	v_and_b32_e32 v72, 0x7fffffff, v156
	v_and_b32_e32 v73, 0x7fffffff, v157
	v_and_b32_e32 v80, 0x7fffffff, v158
	v_and_b32_e32 v81, 0x7fffffff, v159
	v_and_b32_e32 v104, 0x7fffffff, v152
	v_and_b32_e32 v105, 0x7fffffff, v153
	v_and_b32_e32 v112, 0x7fffffff, v154
	v_and_b32_e32 v113, 0x7fffffff, v155
	v_pk_fma_f32 v[72:73], v[72:73], s[42:43], 1.0 op_sel_hi:[1,0,0]
	v_pk_fma_f32 v[80:81], v[80:81], s[42:43], 1.0 op_sel_hi:[1,0,0]
	v_pk_fma_f32 v[104:105], v[104:105], s[42:43], 1.0 op_sel_hi:[1,0,0]
	v_pk_fma_f32 v[112:113], v[112:113], s[42:43], 1.0 op_sel_hi:[1,0,0]
	v_pk_mul_f32 v[78:79], v[156:157], v[156:157]
	v_pk_mul_f32 v[86:87], v[158:159], v[158:159]
	v_pk_mul_f32 v[110:111], v[152:153], v[152:153]
	v_pk_mul_f32 v[118:119], v[154:155], v[154:155]
	v_rcp_f32_e32 v74, v72
	v_rcp_f32_e32 v75, v73
	v_rcp_f32_e32 v82, v80
	v_rcp_f32_e32 v83, v81
	v_rcp_f32_e32 v106, v104
	v_rcp_f32_e32 v107, v105
	v_rcp_f32_e32 v114, v112
	v_rcp_f32_e32 v115, v113
	v_pk_mul_f32 v[78:79], v[78:79], s[54:55] op_sel_hi:[1,0]
	v_pk_mul_f32 v[86:87], v[86:87], s[54:55] op_sel_hi:[1,0]
	v_pk_mul_f32 v[110:111], v[110:111], s[54:55] op_sel_hi:[1,0]
	v_pk_mul_f32 v[118:119], v[118:119], s[54:55] op_sel_hi:[1,0]
	v_pk_fma_f32 v[76:77], v[74:75], s[44:45], v[144:145] op_sel_hi:[1,0,0]
	v_pk_fma_f32 v[84:85], v[82:83], s[44:45], v[144:145] op_sel_hi:[1,0,0]
	v_pk_fma_f32 v[108:109], v[106:107], s[44:45], v[144:145] op_sel_hi:[1,0,0]
	v_pk_fma_f32 v[116:117], v[114:115], s[44:45], v[144:145] op_sel_hi:[1,0,0]
	v_exp_f32_e32 v78, v78
	v_exp_f32_e32 v79, v79
	v_exp_f32_e32 v86, v86
	v_exp_f32_e32 v87, v87
	v_exp_f32_e32 v110, v110
	v_exp_f32_e32 v111, v111
	v_exp_f32_e32 v118, v118
; __device__ __forceinline__ unsigned cvt_pk_bf16(float lo, float hi) { unsigned r; asm volatile("v_cvt_pk_bf16_f32 %0, %1, %2" : "=v"(r) : "v"(lo), "v"(hi)); return r; }
; #define GAS __attribute__((address_space(1)))
; __device__ __forceinline__ f32x2 gelu_pk(f32x2 v) {
;     const f32x2 av = __builtin_elementwise_abs(v), d = av * 0.2316418882f + 1.0f;
;     f32x2 t; t.x = __builtin_amdgcn_rcpf(d.x); t.y = __builtin_amdgcn_rcpf(d.y);
;     f32x2 q = t * 0.5307027145f + (-0.7265760135f); q = q * t + 0.7107068705f; q = q * t + (-0.142248368f); q = q * t + 0.127414796f; q = q * t;
;     const f32x2 s = (v * v) * (-0.72134752044f);
;     f32x2 e; e.x = __builtin_amdgcn_exp2f(s.x); e.y = __builtin_amdgcn_exp2f(s.y);
;     const f32x2 m = v * (q * e), r = v - m;
;     f32x2 o; o.x = v.x < 0.f ? m.x : r.x; o.y = v.y < 0.f ? m.y : r.y; return o;
; }
;     DI void operator()(AccRef acc, const pg8::Unit& u, int wr, int wc, int, int) const {
;     ...
;                 } else if (kind == 3) {
;                     f32x2 a = pg8::gelu_pk((f32x2){v0[0], v0[1]}), b = pg8::gelu_pk((f32x2){v0[2], v0[3]}), c = pg8::gelu_pk((f32x2){v1[0], v1[1]}), d = pg8::gelu_pk((f32x2){v1[2], v1[3]});
;                     v0 = (f32x4){a.x, a.y, b.x, b.y}; v1 = (f32x4){c.x, c.y, d.x, d.y};
;                 } else if (kind == 4) {
; #pragma unroll
;                     for (int e = 0; e < 4; ++e) { v0[e] = __builtin_amdgcn_rcpf(1.0f + __builtin_amdgcn_exp2f(v0[e])); v1[e] = __builtin_amdgcn_rcpf(1.0f + __builtin_amdgcn_exp2f(v1[e])); }
;                 }
;                 u32x4 w; w.x = cvt_pk_bf16(v0[0], v0[1]); w.y = cvt_pk_bf16(v0[2], v0[3]); w.z = cvt_pk_bf16(v1[0], v1[1]); w.w = cvt_pk_bf16(v1[2], v1[3]);
;                 *(GAS u32x4*)(dummy ? dummy + lane_ * 8 : Z + (size_t)lrow * ldz + col) = w;
	v_exp_f32_e32 v119, v119
	v_pk_fma_f32 v[76:77], v[74:75], v[76:77], s[48:49] op_sel_hi:[1,1,0]
	v_pk_fma_f32 v[84:85], v[82:83], v[84:85], s[48:49] op_sel_hi:[1,1,0]
	v_pk_fma_f32 v[108:109], v[106:107], v[108:109], s[48:49] op_sel_hi:[1,1,0]
	v_pk_fma_f32 v[116:117], v[114:115], v[116:117], s[48:49] op_sel_hi:[1,1,0]
	v_pk_fma_f32 v[76:77], v[74:75], v[76:77], s[50:51] op_sel_hi:[1,1,0]
	v_pk_fma_f32 v[84:85], v[82:83], v[84:85], s[50:51] op_sel_hi:[1,1,0]
	v_pk_fma_f32 v[108:109], v[106:107], v[108:109], s[50:51] op_sel_hi:[1,1,0]
	v_pk_fma_f32 v[116:117], v[114:115], v[116:117], s[50:51] op_sel_hi:[1,1,0]
	v_pk_fma_f32 v[76:77], v[74:75], v[76:77], s[52:53] op_sel_hi:[1,1,0]
	v_pk_fma_f32 v[84:85], v[82:83], v[84:85], s[52:53] op_sel_hi:[1,1,0]
	v_pk_fma_f32 v[108:109], v[106:107], v[108:109], s[52:53] op_sel_hi:[1,1,0]
	v_pk_fma_f32 v[116:117], v[114:115], v[116:117], s[52:53] op_sel_hi:[1,1,0]
	v_pk_mul_f32 v[74:75], v[74:75], v[76:77]
	v_pk_mul_f32 v[82:83], v[82:83], v[84:85]
	v_pk_mul_f32 v[106:107], v[106:107], v[108:109]
	v_pk_mul_f32 v[114:115], v[114:115], v[116:117]
	v_pk_mul_f32 v[74:75], v[78:79], v[74:75]
	v_pk_mul_f32 v[82:83], v[86:87], v[82:83]
	v_pk_mul_f32 v[106:107], v[110:111], v[106:107]
	v_pk_mul_f32 v[114:115], v[118:119], v[114:115]
	v_pk_mul_f32 v[78:79], v[156:157], v[74:75]
	v_pk_mul_f32 v[86:87], v[158:159], v[82:83]
	v_pk_mul_f32 v[110:111], v[152:153], v[106:107]
	v_pk_mul_f32 v[118:119], v[154:155], v[114:115]
	v_pk_fma_f32 v[74:75], v[156:157], v[74:75], v[156:157] neg_lo:[1,0,0] neg_hi:[1,0,0]
	v_pk_fma_f32 v[82:83], v[158:159], v[82:83], v[158:159] neg_lo:[1,0,0] neg_hi:[1,0,0]
	v_pk_fma_f32 v[106:107], v[152:153], v[106:107], v[152:153] neg_lo:[1,0,0] neg_hi:[1,0,0]
	v_pk_fma_f32 v[114:115], v[154:155], v[114:115], v[154:155] neg_lo:[1,0,0] neg_hi:[1,0,0]
	v_cmp_gt_f32_e64 s[98:99], 0, v156
	v_cmp_gt_f32_e64 s[16:17], 0, v158
	v_cmp_gt_f32_e64 s[10:11], 0, v152
	v_cmp_gt_f32_e64 s[12:13], 0, v154
	v_cndmask_b32_e64 v156, v74, v78, s[98:99]
	v_cndmask_b32_e64 v158, v82, v86, s[16:17]
	v_cndmask_b32_e64 v152, v106, v110, s[10:11]
	v_cndmask_b32_e64 v154, v114, v118, s[12:13]
	v_cmp_gt_f32_e64 s[98:99], 0, v157
	v_cmp_gt_f32_e64 s[16:17], 0, v159
	v_cmp_gt_f32_e64 s[10:11], 0, v153
	v_cmp_gt_f32_e64 s[12:13], 0, v155
	v_cndmask_b32_e64 v157, v75, v79, s[98:99]
	v_cndmask_b32_e64 v159, v83, v87, s[16:17]
	v_cndmask_b32_e64 v153, v107, v111, s[10:11]
	v_cndmask_b32_e64 v155, v115, v119, s[12:13]
	v_cvt_pk_bf16_f32 v224, v156, v157
	v_cvt_pk_bf16_f32 v225, v158, v159
	v_cvt_pk_bf16_f32 v226, v152, v153
	v_cvt_pk_bf16_f32 v227, v154, v155
	global_store_dwordx4 v[150:151], v[224:227], off
	v_pk_mul_f32 v[132:133], v[132:133], v[170:171] op_sel_hi:[1,0]
	v_pk_mul_f32 v[134:135], v[134:135], v[170:171] op_sel_hi:[1,0]
	v_pk_mul_f32 v[128:129], v[128:129], v[170:171] op_sel_hi:[1,0]
	v_pk_mul_f32 v[130:131], v[130:131], v[170:171] op_sel_hi:[1,0]
	v_and_b32_e32 v72, 0x7fffffff, v132
	v_and_b32_e32 v73, 0x7fffffff, v133
	v_and_b32_e32 v80, 0x7fffffff, v134
	v_and_b32_e32 v81, 0x7fffffff, v135
	v_and_b32_e32 v104, 0x7fffffff, v128
	v_and_b32_e32 v105, 0x7fffffff, v129
	v_and_b32_e32 v112, 0x7fffffff, v130
	v_and_b32_e32 v113, 0x7fffffff, v131
	v_pk_fma_f32 v[72:73], v[72:73], s[42:43], 1.0 op_sel_hi:[1,0,0]
	v_pk_fma_f32 v[80:81], v[80:81], s[42:43], 1.0 op_sel_hi:[1,0,0]
	v_pk_fma_f32 v[104:105], v[104:105], s[42:43], 1.0 op_sel_hi:[1,0,0]
	v_pk_fma_f32 v[112:113], v[112:113], s[42:43], 1.0 op_sel_hi:[1,0,0]
	v_pk_mul_f32 v[78:79], v[132:133], v[132:133]
	v_pk_mul_f32 v[86:87], v[134:135], v[134:135]
	v_pk_mul_f32 v[110:111], v[128:129], v[128:129]
	v_pk_mul_f32 v[118:119], v[130:131], v[130:131]
	v_rcp_f32_e32 v74, v72
	v_rcp_f32_e32 v75, v73
	v_rcp_f32_e32 v82, v80
	v_rcp_f32_e32 v83, v81
	v_rcp_f32_e32 v106, v104
	v_rcp_f32_e32 v107, v105
	v_rcp_f32_e32 v114, v112
	v_rcp_f32_e32 v115, v113
	v_pk_mul_f32 v[78:79], v[78:79], s[54:55] op_sel_hi:[1,0]
	v_pk_mul_f32 v[86:87], v[86:87], s[54:55] op_sel_hi:[1,0]
	v_pk_mul_f32 v[110:111], v[110:111], s[54:55] op_sel_hi:[1,0]
	v_pk_mul_f32 v[118:119], v[118:119], s[54:55] op_sel_hi:[1,0]
	v_pk_fma_f32 v[76:77], v[74:75], s[44:45], v[144:145] op_sel_hi:[1,0,0]
	v_pk_fma_f32 v[84:85], v[82:83], s[44:45], v[144:145] op_sel_hi:[1,0,0]
	v_pk_fma_f32 v[108:109], v[106:107], s[44:45], v[144:145] op_sel_hi:[1,0,0]
	v_pk_fma_f32 v[116:117], v[114:115], s[44:45], v[144:145] op_sel_hi:[1,0,0]
	v_exp_f32_e32 v78, v78
	v_exp_f32_e32 v79, v79
	v_exp_f32_e32 v86, v86
	v_exp_f32_e32 v87, v87
	v_exp_f32_e32 v110, v110
	v_exp_f32_e32 v111, v111
	v_exp_f32_e32 v118, v118
	v_exp_f32_e32 v119, v119
	v_pk_fma_f32 v[76:77], v[74:75], v[76:77], s[48:49] op_sel_hi:[1,1,0]
	v_pk_fma_f32 v[84:85], v[82:83], v[84:85], s[48:49] op_sel_hi:[1,1,0]
	v_pk_fma_f32 v[108:109], v[106:107], v[108:109], s[48:49] op_sel_hi:[1,1,0]
	v_pk_fma_f32 v[116:117], v[114:115], v[116:117], s[48:49] op_sel_hi:[1,1,0]
	v_pk_fma_f32 v[76:77], v[74:75], v[76:77], s[50:51] op_sel_hi:[1,1,0]
	v_pk_fma_f32 v[84:85], v[82:83], v[84:85], s[50:51] op_sel_hi:[1,1,0]
	v_pk_fma_f32 v[108:109], v[106:107], v[108:109], s[50:51] op_sel_hi:[1,1,0]
	v_pk_fma_f32 v[116:117], v[114:115], v[116:117], s[50:51] op_sel_hi:[1,1,0]
	v_pk_fma_f32 v[76:77], v[74:75], v[76:77], s[52:53] op_sel_hi:[1,1,0]
	v_pk_fma_f32 v[84:85], v[82:83], v[84:85], s[52:53] op_sel_hi:[1,1,0]
	v_pk_fma_f32 v[108:109], v[106:107], v[108:109], s[52:53] op_sel_hi:[1,1,0]
	v_pk_fma_f32 v[116:117], v[114:115], v[116:117], s[52:53] op_sel_hi:[1,1,0]
	v_pk_mul_f32 v[74:75], v[74:75], v[76:77]
	v_pk_mul_f32 v[82:83], v[82:83], v[84:85]
	v_pk_mul_f32 v[106:107], v[106:107], v[108:109]
; __device__ __forceinline__ unsigned cvt_pk_bf16(float lo, float hi) { unsigned r; asm volatile("v_cvt_pk_bf16_f32 %0, %1, %2" : "=v"(r) : "v"(lo), "v"(hi)); return r; }
; #define GAS __attribute__((address_space(1)))
; __device__ __forceinline__ f32x2 gelu_pk(f32x2 v) {
;     const f32x2 av = __builtin_elementwise_abs(v), d = av * 0.2316418882f + 1.0f;
;     f32x2 t; t.x = __builtin_amdgcn_rcpf(d.x); t.y = __builtin_amdgcn_rcpf(d.y);
;     f32x2 q = t * 0.5307027145f + (-0.7265760135f); q = q * t + 0.7107068705f; q = q * t + (-0.142248368f); q = q * t + 0.127414796f; q = q * t;
;     const f32x2 s = (v * v) * (-0.72134752044f);
;     f32x2 e; e.x = __builtin_amdgcn_exp2f(s.x); e.y = __builtin_amdgcn_exp2f(s.y);
;     const f32x2 m = v * (q * e), r = v - m;
;     f32x2 o; o.x = v.x < 0.f ? m.x : r.x; o.y = v.y < 0.f ? m.y : r.y; return o;
; }
;     DI void operator()(AccRef acc, const pg8::Unit& u, int wr, int wc, int, int) const {
;     ...
;                 } else if (kind == 3) {
;                     f32x2 a = pg8::gelu_pk((f32x2){v0[0], v0[1]}), b = pg8::gelu_pk((f32x2){v0[2], v0[3]}), c = pg8::gelu_pk((f32x2){v1[0], v1[1]}), d = pg8::gelu_pk((f32x2){v1[2], v1[3]});
;                     v0 = (f32x4){a.x, a.y, b.x, b.y}; v1 = (f32x4){c.x, c.y, d.x, d.y};
;                 } else if (kind == 4) {
; #pragma unroll
;                     for (int e = 0; e < 4; ++e) { v0[e] = __builtin_amdgcn_rcpf(1.0f + __builtin_amdgcn_exp2f(v0[e])); v1[e] = __builtin_amdgcn_rcpf(1.0f + __builtin_amdgcn_exp2f(v1[e])); }
;                 }
;                 u32x4 w; w.x = cvt_pk_bf16(v0[0], v0[1]); w.y = cvt_pk_bf16(v0[2], v0[3]); w.z = cvt_pk_bf16(v1[0], v1[1]); w.w = cvt_pk_bf16(v1[2], v1[3]);
;                 *(GAS u32x4*)(dummy ? dummy + lane_ * 8 : Z + (size_t)lrow * ldz + col) = w;
	v_pk_mul_f32 v[114:115], v[114:115], v[116:117]
	v_pk_mul_f32 v[74:75], v[78:79], v[74:75]
	v_pk_mul_f32 v[82:83], v[86:87], v[82:83]
	v_pk_mul_f32 v[106:107], v[110:111], v[106:107]
	v_pk_mul_f32 v[114:115], v[118:119], v[114:115]
	v_pk_mul_f32 v[78:79], v[132:133], v[74:75]
	v_pk_mul_f32 v[86:87], v[134:135], v[82:83]
	v_pk_mul_f32 v[110:111], v[128:129], v[106:107]
	v_pk_mul_f32 v[118:119], v[130:131], v[114:115]
	v_pk_fma_f32 v[74:75], v[132:133], v[74:75], v[132:133] neg_lo:[1,0,0] neg_hi:[1,0,0]
	v_pk_fma_f32 v[82:83], v[134:135], v[82:83], v[134:135] neg_lo:[1,0,0] neg_hi:[1,0,0]
	v_pk_fma_f32 v[106:107], v[128:129], v[106:107], v[128:129] neg_lo:[1,0,0] neg_hi:[1,0,0]
	v_pk_fma_f32 v[114:115], v[130:131], v[114:115], v[130:131] neg_lo:[1,0,0] neg_hi:[1,0,0]
	v_cmp_gt_f32_e64 s[98:99], 0, v132
	v_cmp_gt_f32_e64 s[16:17], 0, v134
	v_cmp_gt_f32_e64 s[10:11], 0, v128
	v_cmp_gt_f32_e64 s[12:13], 0, v130
	v_cndmask_b32_e64 v132, v74, v78, s[98:99]
	v_cndmask_b32_e64 v134, v82, v86, s[16:17]
	v_cndmask_b32_e64 v128, v106, v110, s[10:11]
	v_cndmask_b32_e64 v130, v114, v118, s[12:13]
	v_cmp_gt_f32_e64 s[98:99], 0, v133
	v_cmp_gt_f32_e64 s[16:17], 0, v135
	v_cmp_gt_f32_e64 s[10:11], 0, v129
	v_cmp_gt_f32_e64 s[12:13], 0, v131
	v_cndmask_b32_e64 v133, v75, v79, s[98:99]
	v_cndmask_b32_e64 v135, v83, v87, s[16:17]
	v_cndmask_b32_e64 v129, v107, v111, s[10:11]
	v_cndmask_b32_e64 v131, v115, v119, s[12:13]
	v_cvt_pk_bf16_f32 v228, v132, v133
	v_cvt_pk_bf16_f32 v229, v134, v135
	v_cvt_pk_bf16_f32 v230, v128, v129
	v_cvt_pk_bf16_f32 v231, v130, v131
	global_store_dwordx4 v[150:151], v[228:231], off offset:256
	v_lshl_add_u64 v[146:147], v[150:151], 0, s[2:3]
	v_pk_mul_f32 v[124:125], v[124:125], v[172:173] op_sel_hi:[1,0]
	v_pk_mul_f32 v[126:127], v[126:127], v[172:173] op_sel_hi:[1,0]
	v_pk_mul_f32 v[120:121], v[120:121], v[172:173] op_sel_hi:[1,0]
	v_pk_mul_f32 v[122:123], v[122:123], v[172:173] op_sel_hi:[1,0]
	v_and_b32_e32 v72, 0x7fffffff, v124
	v_and_b32_e32 v73, 0x7fffffff, v125
	v_and_b32_e32 v80, 0x7fffffff, v126
	v_and_b32_e32 v81, 0x7fffffff, v127
	v_and_b32_e32 v104, 0x7fffffff, v120
	v_and_b32_e32 v105, 0x7fffffff, v121
	v_and_b32_e32 v112, 0x7fffffff, v122
	v_and_b32_e32 v113, 0x7fffffff, v123
	v_pk_fma_f32 v[72:73], v[72:73], s[42:43], 1.0 op_sel_hi:[1,0,0]
	v_pk_fma_f32 v[80:81], v[80:81], s[42:43], 1.0 op_sel_hi:[1,0,0]
	v_pk_fma_f32 v[104:105], v[104:105], s[42:43], 1.0 op_sel_hi:[1,0,0]
	v_pk_fma_f32 v[112:113], v[112:113], s[42:43], 1.0 op_sel_hi:[1,0,0]
	v_pk_mul_f32 v[78:79], v[124:125], v[124:125]
	v_pk_mul_f32 v[86:87], v[126:127], v[126:127]
	v_pk_mul_f32 v[110:111], v[120:121], v[120:121]
	v_pk_mul_f32 v[118:119], v[122:123], v[122:123]
	v_rcp_f32_e32 v74, v72
	v_rcp_f32_e32 v75, v73
	v_rcp_f32_e32 v82, v80
	v_rcp_f32_e32 v83, v81
	v_rcp_f32_e32 v106, v104
	v_rcp_f32_e32 v107, v105
	v_rcp_f32_e32 v114, v112
	v_rcp_f32_e32 v115, v113
	v_pk_mul_f32 v[78:79], v[78:79], s[54:55] op_sel_hi:[1,0]
	v_pk_mul_f32 v[86:87], v[86:87], s[54:55] op_sel_hi:[1,0]
	v_pk_mul_f32 v[110:111], v[110:111], s[54:55] op_sel_hi:[1,0]
	v_pk_mul_f32 v[118:119], v[118:119], s[54:55] op_sel_hi:[1,0]
	v_pk_fma_f32 v[76:77], v[74:75], s[44:45], v[144:145] op_sel_hi:[1,0,0]
	v_pk_fma_f32 v[84:85], v[82:83], s[44:45], v[144:145] op_sel_hi:[1,0,0]
	v_pk_fma_f32 v[108:109], v[106:107], s[44:45], v[144:145] op_sel_hi:[1,0,0]
	v_pk_fma_f32 v[116:117], v[114:115], s[44:45], v[144:145] op_sel_hi:[1,0,0]
	v_exp_f32_e32 v78, v78
	v_exp_f32_e32 v79, v79
	v_exp_f32_e32 v86, v86
	v_exp_f32_e32 v87, v87
	v_exp_f32_e32 v110, v110
	v_exp_f32_e32 v111, v111
	v_exp_f32_e32 v118, v118
	v_exp_f32_e32 v119, v119
	v_pk_fma_f32 v[76:77], v[74:75], v[76:77], s[48:49] op_sel_hi:[1,1,0]
	v_pk_fma_f32 v[84:85], v[82:83], v[84:85], s[48:49] op_sel_hi:[1,1,0]
	v_pk_fma_f32 v[108:109], v[106:107], v[108:109], s[48:49] op_sel_hi:[1,1,0]
	v_pk_fma_f32 v[116:117], v[114:115], v[116:117], s[48:49] op_sel_hi:[1,1,0]
	v_pk_fma_f32 v[76:77], v[74:75], v[76:77], s[50:51] op_sel_hi:[1,1,0]
	v_pk_fma_f32 v[84:85], v[82:83], v[84:85], s[50:51] op_sel_hi:[1,1,0]
	v_pk_fma_f32 v[108:109], v[106:107], v[108:109], s[50:51] op_sel_hi:[1,1,0]
	v_pk_fma_f32 v[116:117], v[114:115], v[116:117], s[50:51] op_sel_hi:[1,1,0]
	v_pk_fma_f32 v[76:77], v[74:75], v[76:77], s[52:53] op_sel_hi:[1,1,0]
	v_pk_fma_f32 v[84:85], v[82:83], v[84:85], s[52:53] op_sel_hi:[1,1,0]
	v_pk_fma_f32 v[108:109], v[106:107], v[108:109], s[52:53] op_sel_hi:[1,1,0]
	v_pk_fma_f32 v[116:117], v[114:115], v[116:117], s[52:53] op_sel_hi:[1,1,0]
	v_pk_mul_f32 v[74:75], v[74:75], v[76:77]
	v_pk_mul_f32 v[82:83], v[82:83], v[84:85]
	v_pk_mul_f32 v[106:107], v[106:107], v[108:109]
	v_pk_mul_f32 v[114:115], v[114:115], v[116:117]
	v_pk_mul_f32 v[74:75], v[78:79], v[74:75]
	v_pk_mul_f32 v[82:83], v[86:87], v[82:83]
	v_pk_mul_f32 v[106:107], v[110:111], v[106:107]
	v_pk_mul_f32 v[114:115], v[118:119], v[114:115]
	v_pk_mul_f32 v[78:79], v[124:125], v[74:75]
	v_pk_mul_f32 v[86:87], v[126:127], v[82:83]
	v_pk_mul_f32 v[110:111], v[120:121], v[106:107]
	v_pk_mul_f32 v[118:119], v[122:123], v[114:115]
	v_pk_fma_f32 v[74:75], v[124:125], v[74:75], v[124:125] neg_lo:[1,0,0] neg_hi:[1,0,0]
	v_pk_fma_f32 v[82:83], v[126:127], v[82:83], v[126:127] neg_lo:[1,0,0] neg_hi:[1,0,0]
	v_pk_fma_f32 v[106:107], v[120:121], v[106:107], v[120:121] neg_lo:[1,0,0] neg_hi:[1,0,0]
	v_pk_fma_f32 v[114:115], v[122:123], v[114:115], v[122:123] neg_lo:[1,0,0] neg_hi:[1,0,0]
	v_cmp_gt_f32_e64 s[98:99], 0, v124
	v_cmp_gt_f32_e64 s[16:17], 0, v126
	v_cmp_gt_f32_e64 s[10:11], 0, v120
	v_cmp_gt_f32_e64 s[12:13], 0, v122
	v_cndmask_b32_e64 v124, v74, v78, s[98:99]
; __device__ __forceinline__ unsigned cvt_pk_bf16(float lo, float hi) { unsigned r; asm volatile("v_cvt_pk_bf16_f32 %0, %1, %2" : "=v"(r) : "v"(lo), "v"(hi)); return r; }
; #define GAS __attribute__((address_space(1)))
; __device__ __forceinline__ f32x2 gelu_pk(f32x2 v) {
;     const f32x2 av = __builtin_elementwise_abs(v), d = av * 0.2316418882f + 1.0f;
;     f32x2 t; t.x = __builtin_amdgcn_rcpf(d.x); t.y = __builtin_amdgcn_rcpf(d.y);
;     f32x2 q = t * 0.5307027145f + (-0.7265760135f); q = q * t + 0.7107068705f; q = q * t + (-0.142248368f); q = q * t + 0.127414796f; q = q * t;
;     const f32x2 s = (v * v) * (-0.72134752044f);
;     f32x2 e; e.x = __builtin_amdgcn_exp2f(s.x); e.y = __builtin_amdgcn_exp2f(s.y);
;     const f32x2 m = v * (q * e), r = v - m;
;     f32x2 o; o.x = v.x < 0.f ? m.x : r.x; o.y = v.y < 0.f ? m.y : r.y; return o;
; }
;     DI void operator()(AccRef acc, const pg8::Unit& u, int wr, int wc, int, int) const {
;     ...
;                 } else if (kind == 3) {
;                     f32x2 a = pg8::gelu_pk((f32x2){v0[0], v0[1]}), b = pg8::gelu_pk((f32x2){v0[2], v0[3]}), c = pg8::gelu_pk((f32x2){v1[0], v1[1]}), d = pg8::gelu_pk((f32x2){v1[2], v1[3]});
;                     v0 = (f32x4){a.x, a.y, b.x, b.y}; v1 = (f32x4){c.x, c.y, d.x, d.y};
;                 } else if (kind == 4) {
; #pragma unroll
;                     for (int e = 0; e < 4; ++e) { v0[e] = __builtin_amdgcn_rcpf(1.0f + __builtin_amdgcn_exp2f(v0[e])); v1[e] = __builtin_amdgcn_rcpf(1.0f + __builtin_amdgcn_exp2f(v1[e])); }
;                 }
;                 u32x4 w; w.x = cvt_pk_bf16(v0[0], v0[1]); w.y = cvt_pk_bf16(v0[2], v0[3]); w.z = cvt_pk_bf16(v1[0], v1[1]); w.w = cvt_pk_bf16(v1[2], v1[3]);
;                 *(GAS u32x4*)(dummy ? dummy + lane_ * 8 : Z + (size_t)lrow * ldz + col) = w;
	v_cndmask_b32_e64 v126, v82, v86, s[16:17]
	v_cndmask_b32_e64 v120, v106, v110, s[10:11]
	v_cndmask_b32_e64 v122, v114, v118, s[12:13]
	v_cmp_gt_f32_e64 s[98:99], 0, v125
	v_cmp_gt_f32_e64 s[16:17], 0, v127
	v_cmp_gt_f32_e64 s[10:11], 0, v121
	v_cmp_gt_f32_e64 s[12:13], 0, v123
	v_cndmask_b32_e64 v125, v75, v79, s[98:99]
	v_cndmask_b32_e64 v127, v83, v87, s[16:17]
	v_cndmask_b32_e64 v121, v107, v111, s[10:11]
	v_cndmask_b32_e64 v123, v115, v119, s[12:13]
	v_cvt_pk_bf16_f32 v216, v124, v125
	v_cvt_pk_bf16_f32 v217, v126, v127
	v_cvt_pk_bf16_f32 v218, v120, v121
	v_cvt_pk_bf16_f32 v219, v122, v123
	global_store_dwordx4 v[146:147], v[216:219], off
	v_pk_mul_f32 v[100:101], v[100:101], v[172:173] op_sel_hi:[1,0]
	v_pk_mul_f32 v[102:103], v[102:103], v[172:173] op_sel_hi:[1,0]
	v_pk_mul_f32 v[96:97], v[96:97], v[172:173] op_sel_hi:[1,0]
	v_pk_mul_f32 v[98:99], v[98:99], v[172:173] op_sel_hi:[1,0]
	v_and_b32_e32 v72, 0x7fffffff, v100
	v_and_b32_e32 v73, 0x7fffffff, v101
	v_and_b32_e32 v80, 0x7fffffff, v102
	v_and_b32_e32 v81, 0x7fffffff, v103
	v_and_b32_e32 v104, 0x7fffffff, v96
	v_and_b32_e32 v105, 0x7fffffff, v97
	v_and_b32_e32 v112, 0x7fffffff, v98
	v_and_b32_e32 v113, 0x7fffffff, v99
	v_pk_fma_f32 v[72:73], v[72:73], s[42:43], 1.0 op_sel_hi:[1,0,0]
	v_pk_fma_f32 v[80:81], v[80:81], s[42:43], 1.0 op_sel_hi:[1,0,0]
	v_pk_fma_f32 v[104:105], v[104:105], s[42:43], 1.0 op_sel_hi:[1,0,0]
	v_pk_fma_f32 v[112:113], v[112:113], s[42:43], 1.0 op_sel_hi:[1,0,0]
	v_pk_mul_f32 v[78:79], v[100:101], v[100:101]
	v_pk_mul_f32 v[86:87], v[102:103], v[102:103]
	v_pk_mul_f32 v[110:111], v[96:97], v[96:97]
	v_pk_mul_f32 v[118:119], v[98:99], v[98:99]
	v_rcp_f32_e32 v74, v72
	v_rcp_f32_e32 v75, v73
	v_rcp_f32_e32 v82, v80
	v_rcp_f32_e32 v83, v81
	v_rcp_f32_e32 v106, v104
	v_rcp_f32_e32 v107, v105
	v_rcp_f32_e32 v114, v112
	v_rcp_f32_e32 v115, v113
	v_pk_mul_f32 v[78:79], v[78:79], s[54:55] op_sel_hi:[1,0]
	v_pk_mul_f32 v[86:87], v[86:87], s[54:55] op_sel_hi:[1,0]
	v_pk_mul_f32 v[110:111], v[110:111], s[54:55] op_sel_hi:[1,0]
	v_pk_mul_f32 v[118:119], v[118:119], s[54:55] op_sel_hi:[1,0]
	v_pk_fma_f32 v[76:77], v[74:75], s[44:45], v[144:145] op_sel_hi:[1,0,0]
	v_pk_fma_f32 v[84:85], v[82:83], s[44:45], v[144:145] op_sel_hi:[1,0,0]
	v_pk_fma_f32 v[108:109], v[106:107], s[44:45], v[144:145] op_sel_hi:[1,0,0]
	v_pk_fma_f32 v[116:117], v[114:115], s[44:45], v[144:145] op_sel_hi:[1,0,0]
	v_exp_f32_e32 v78, v78
	v_exp_f32_e32 v79, v79
	v_exp_f32_e32 v86, v86
	v_exp_f32_e32 v87, v87
	v_exp_f32_e32 v110, v110
	v_exp_f32_e32 v111, v111
	v_exp_f32_e32 v118, v118
	v_exp_f32_e32 v119, v119
	v_pk_fma_f32 v[76:77], v[74:75], v[76:77], s[48:49] op_sel_hi:[1,1,0]
	v_pk_fma_f32 v[84:85], v[82:83], v[84:85], s[48:49] op_sel_hi:[1,1,0]
	v_pk_fma_f32 v[108:109], v[106:107], v[108:109], s[48:49] op_sel_hi:[1,1,0]
	v_pk_fma_f32 v[116:117], v[114:115], v[116:117], s[48:49] op_sel_hi:[1,1,0]
	v_pk_fma_f32 v[76:77], v[74:75], v[76:77], s[50:51] op_sel_hi:[1,1,0]
	v_pk_fma_f32 v[84:85], v[82:83], v[84:85], s[50:51] op_sel_hi:[1,1,0]
	v_pk_fma_f32 v[108:109], v[106:107], v[108:109], s[50:51] op_sel_hi:[1,1,0]
	v_pk_fma_f32 v[116:117], v[114:115], v[116:117], s[50:51] op_sel_hi:[1,1,0]
	v_pk_fma_f32 v[76:77], v[74:75], v[76:77], s[52:53] op_sel_hi:[1,1,0]
	v_pk_fma_f32 v[84:85], v[82:83], v[84:85], s[52:53] op_sel_hi:[1,1,0]
	v_pk_fma_f32 v[108:109], v[106:107], v[108:109], s[52:53] op_sel_hi:[1,1,0]
	v_pk_fma_f32 v[116:117], v[114:115], v[116:117], s[52:53] op_sel_hi:[1,1,0]
	v_pk_mul_f32 v[74:75], v[74:75], v[76:77]
	v_pk_mul_f32 v[82:83], v[82:83], v[84:85]
	v_pk_mul_f32 v[106:107], v[106:107], v[108:109]
	v_pk_mul_f32 v[114:115], v[114:115], v[116:117]
	v_pk_mul_f32 v[74:75], v[78:79], v[74:75]
	v_pk_mul_f32 v[82:83], v[86:87], v[82:83]
	v_pk_mul_f32 v[106:107], v[110:111], v[106:107]
	v_pk_mul_f32 v[114:115], v[118:119], v[114:115]
	v_pk_mul_f32 v[78:79], v[100:101], v[74:75]
	v_pk_mul_f32 v[86:87], v[102:103], v[82:83]
	v_pk_mul_f32 v[110:111], v[96:97], v[106:107]
	v_pk_mul_f32 v[118:119], v[98:99], v[114:115]
	v_pk_fma_f32 v[74:75], v[100:101], v[74:75], v[100:101] neg_lo:[1,0,0] neg_hi:[1,0,0]
	v_pk_fma_f32 v[82:83], v[102:103], v[82:83], v[102:103] neg_lo:[1,0,0] neg_hi:[1,0,0]
	v_pk_fma_f32 v[106:107], v[96:97], v[106:107], v[96:97] neg_lo:[1,0,0] neg_hi:[1,0,0]
	v_pk_fma_f32 v[114:115], v[98:99], v[114:115], v[98:99] neg_lo:[1,0,0] neg_hi:[1,0,0]
	v_cmp_gt_f32_e64 s[98:99], 0, v100
	v_cmp_gt_f32_e64 s[16:17], 0, v102
	v_cmp_gt_f32_e64 s[10:11], 0, v96
	v_cmp_gt_f32_e64 s[12:13], 0, v98
	v_cndmask_b32_e64 v100, v74, v78, s[98:99]
	v_cndmask_b32_e64 v102, v82, v86, s[16:17]
	v_cndmask_b32_e64 v96, v106, v110, s[10:11]
	v_cndmask_b32_e64 v98, v114, v118, s[12:13]
	v_cmp_gt_f32_e64 s[98:99], 0, v101
	v_cmp_gt_f32_e64 s[16:17], 0, v103
	v_cmp_gt_f32_e64 s[10:11], 0, v97
	v_cmp_gt_f32_e64 s[12:13], 0, v99
	v_cndmask_b32_e64 v101, v75, v79, s[98:99]
	v_cndmask_b32_e64 v103, v83, v87, s[16:17]
	v_cndmask_b32_e64 v97, v107, v111, s[10:11]
	v_cndmask_b32_e64 v99, v115, v119, s[12:13]
	v_cvt_pk_bf16_f32 v220, v100, v101
	v_cvt_pk_bf16_f32 v221, v102, v103
	v_cvt_pk_bf16_f32 v222, v96, v97
	v_cvt_pk_bf16_f32 v223, v98, v99
	global_store_dwordx4 v[146:147], v[220:223], off offset:256
	v_lshl_add_u64 v[150:151], v[146:147], 0, s[2:3]
	v_pk_mul_f32 v[92:93], v[92:93], v[174:175] op_sel_hi:[1,0]
	v_pk_mul_f32 v[94:95], v[94:95], v[174:175] op_sel_hi:[1,0]
	v_pk_mul_f32 v[88:89], v[88:89], v[174:175] op_sel_hi:[1,0]
	v_pk_mul_f32 v[90:91], v[90:91], v[174:175] op_sel_hi:[1,0]
	v_and_b32_e32 v72, 0x7fffffff, v92
	v_and_b32_e32 v73, 0x7fffffff, v93
	v_and_b32_e32 v80, 0x7fffffff, v94
; __device__ __forceinline__ unsigned cvt_pk_bf16(float lo, float hi) { unsigned r; asm volatile("v_cvt_pk_bf16_f32 %0, %1, %2" : "=v"(r) : "v"(lo), "v"(hi)); return r; }
; #define GAS __attribute__((address_space(1)))
; __device__ __forceinline__ f32x2 gelu_pk(f32x2 v) {
;     const f32x2 av = __builtin_elementwise_abs(v), d = av * 0.2316418882f + 1.0f;
;     f32x2 t; t.x = __builtin_amdgcn_rcpf(d.x); t.y = __builtin_amdgcn_rcpf(d.y);
;     f32x2 q = t * 0.5307027145f + (-0.7265760135f); q = q * t + 0.7107068705f; q = q * t + (-0.142248368f); q = q * t + 0.127414796f; q = q * t;
;     const f32x2 s = (v * v) * (-0.72134752044f);
;     f32x2 e; e.x = __builtin_amdgcn_exp2f(s.x); e.y = __builtin_amdgcn_exp2f(s.y);
;     const f32x2 m = v * (q * e), r = v - m;
;     f32x2 o; o.x = v.x < 0.f ? m.x : r.x; o.y = v.y < 0.f ? m.y : r.y; return o;
; }
;     DI void operator()(AccRef acc, const pg8::Unit& u, int wr, int wc, int, int) const {
;     ...
;                 } else if (kind == 3) {
;                     f32x2 a = pg8::gelu_pk((f32x2){v0[0], v0[1]}), b = pg8::gelu_pk((f32x2){v0[2], v0[3]}), c = pg8::gelu_pk((f32x2){v1[0], v1[1]}), d = pg8::gelu_pk((f32x2){v1[2], v1[3]});
;                     v0 = (f32x4){a.x, a.y, b.x, b.y}; v1 = (f32x4){c.x, c.y, d.x, d.y};
;                 } else if (kind == 4) {
; #pragma unroll
;                     for (int e = 0; e < 4; ++e) { v0[e] = __builtin_amdgcn_rcpf(1.0f + __builtin_amdgcn_exp2f(v0[e])); v1[e] = __builtin_amdgcn_rcpf(1.0f + __builtin_amdgcn_exp2f(v1[e])); }
;                 }
;                 u32x4 w; w.x = cvt_pk_bf16(v0[0], v0[1]); w.y = cvt_pk_bf16(v0[2], v0[3]); w.z = cvt_pk_bf16(v1[0], v1[1]); w.w = cvt_pk_bf16(v1[2], v1[3]);
;                 *(GAS u32x4*)(dummy ? dummy + lane_ * 8 : Z + (size_t)lrow * ldz + col) = w;
	v_and_b32_e32 v81, 0x7fffffff, v95
	v_and_b32_e32 v104, 0x7fffffff, v88
	v_and_b32_e32 v105, 0x7fffffff, v89
	v_and_b32_e32 v112, 0x7fffffff, v90
	v_and_b32_e32 v113, 0x7fffffff, v91
	v_pk_fma_f32 v[72:73], v[72:73], s[42:43], 1.0 op_sel_hi:[1,0,0]
	v_pk_fma_f32 v[80:81], v[80:81], s[42:43], 1.0 op_sel_hi:[1,0,0]
	v_pk_fma_f32 v[104:105], v[104:105], s[42:43], 1.0 op_sel_hi:[1,0,0]
	v_pk_fma_f32 v[112:113], v[112:113], s[42:43], 1.0 op_sel_hi:[1,0,0]
	v_pk_mul_f32 v[78:79], v[92:93], v[92:93]
	v_pk_mul_f32 v[86:87], v[94:95], v[94:95]
	v_pk_mul_f32 v[110:111], v[88:89], v[88:89]
	v_pk_mul_f32 v[118:119], v[90:91], v[90:91]
	v_rcp_f32_e32 v74, v72
	v_rcp_f32_e32 v75, v73
	v_rcp_f32_e32 v82, v80
	v_rcp_f32_e32 v83, v81
	v_rcp_f32_e32 v106, v104
	v_rcp_f32_e32 v107, v105
	v_rcp_f32_e32 v114, v112
	v_rcp_f32_e32 v115, v113
	v_pk_mul_f32 v[78:79], v[78:79], s[54:55] op_sel_hi:[1,0]
	v_pk_mul_f32 v[86:87], v[86:87], s[54:55] op_sel_hi:[1,0]
	v_pk_mul_f32 v[110:111], v[110:111], s[54:55] op_sel_hi:[1,0]
	v_pk_mul_f32 v[118:119], v[118:119], s[54:55] op_sel_hi:[1,0]
	v_pk_fma_f32 v[76:77], v[74:75], s[44:45], v[144:145] op_sel_hi:[1,0,0]
	v_pk_fma_f32 v[84:85], v[82:83], s[44:45], v[144:145] op_sel_hi:[1,0,0]
	v_pk_fma_f32 v[108:109], v[106:107], s[44:45], v[144:145] op_sel_hi:[1,0,0]
	v_pk_fma_f32 v[116:117], v[114:115], s[44:45], v[144:145] op_sel_hi:[1,0,0]
	v_exp_f32_e32 v78, v78
	v_exp_f32_e32 v79, v79
	v_exp_f32_e32 v86, v86
	v_exp_f32_e32 v87, v87
	v_exp_f32_e32 v110, v110
	v_exp_f32_e32 v111, v111
	v_exp_f32_e32 v118, v118
	v_exp_f32_e32 v119, v119
	v_pk_fma_f32 v[76:77], v[74:75], v[76:77], s[48:49] op_sel_hi:[1,1,0]
	v_pk_fma_f32 v[84:85], v[82:83], v[84:85], s[48:49] op_sel_hi:[1,1,0]
	v_pk_fma_f32 v[108:109], v[106:107], v[108:109], s[48:49] op_sel_hi:[1,1,0]
	v_pk_fma_f32 v[116:117], v[114:115], v[116:117], s[48:49] op_sel_hi:[1,1,0]
	v_pk_fma_f32 v[76:77], v[74:75], v[76:77], s[50:51] op_sel_hi:[1,1,0]
	v_pk_fma_f32 v[84:85], v[82:83], v[84:85], s[50:51] op_sel_hi:[1,1,0]
	v_pk_fma_f32 v[108:109], v[106:107], v[108:109], s[50:51] op_sel_hi:[1,1,0]
	v_pk_fma_f32 v[116:117], v[114:115], v[116:117], s[50:51] op_sel_hi:[1,1,0]
	v_pk_fma_f32 v[76:77], v[74:75], v[76:77], s[52:53] op_sel_hi:[1,1,0]
	v_pk_fma_f32 v[84:85], v[82:83], v[84:85], s[52:53] op_sel_hi:[1,1,0]
	v_pk_fma_f32 v[108:109], v[106:107], v[108:109], s[52:53] op_sel_hi:[1,1,0]
	v_pk_fma_f32 v[116:117], v[114:115], v[116:117], s[52:53] op_sel_hi:[1,1,0]
	v_pk_mul_f32 v[74:75], v[74:75], v[76:77]
	v_pk_mul_f32 v[82:83], v[82:83], v[84:85]
	v_pk_mul_f32 v[106:107], v[106:107], v[108:109]
	v_pk_mul_f32 v[114:115], v[114:115], v[116:117]
	v_pk_mul_f32 v[74:75], v[78:79], v[74:75]
	v_pk_mul_f32 v[82:83], v[86:87], v[82:83]
	v_pk_mul_f32 v[106:107], v[110:111], v[106:107]
	v_pk_mul_f32 v[114:115], v[118:119], v[114:115]
	v_pk_mul_f32 v[78:79], v[92:93], v[74:75]
	v_pk_mul_f32 v[86:87], v[94:95], v[82:83]
	v_pk_mul_f32 v[110:111], v[88:89], v[106:107]
	v_pk_mul_f32 v[118:119], v[90:91], v[114:115]
	v_pk_fma_f32 v[74:75], v[92:93], v[74:75], v[92:93] neg_lo:[1,0,0] neg_hi:[1,0,0]
	v_pk_fma_f32 v[82:83], v[94:95], v[82:83], v[94:95] neg_lo:[1,0,0] neg_hi:[1,0,0]
	v_pk_fma_f32 v[106:107], v[88:89], v[106:107], v[88:89] neg_lo:[1,0,0] neg_hi:[1,0,0]
	v_pk_fma_f32 v[114:115], v[90:91], v[114:115], v[90:91] neg_lo:[1,0,0] neg_hi:[1,0,0]
	v_cmp_gt_f32_e64 s[98:99], 0, v92
	v_cmp_gt_f32_e64 s[16:17], 0, v94
	v_cmp_gt_f32_e64 s[10:11], 0, v88
	v_cmp_gt_f32_e64 s[12:13], 0, v90
	v_cndmask_b32_e64 v92, v74, v78, s[98:99]
	v_cndmask_b32_e64 v94, v82, v86, s[16:17]
	v_cndmask_b32_e64 v88, v106, v110, s[10:11]
	v_cndmask_b32_e64 v90, v114, v118, s[12:13]
	v_cmp_gt_f32_e64 s[98:99], 0, v93
	v_cmp_gt_f32_e64 s[16:17], 0, v95
	v_cmp_gt_f32_e64 s[10:11], 0, v89
	v_cmp_gt_f32_e64 s[12:13], 0, v91
	v_cndmask_b32_e64 v93, v75, v79, s[98:99]
	v_cndmask_b32_e64 v95, v83, v87, s[16:17]
	v_cndmask_b32_e64 v89, v107, v111, s[10:11]
	v_cndmask_b32_e64 v91, v115, v119, s[12:13]
	v_cvt_pk_bf16_f32 v224, v92, v93
	v_cvt_pk_bf16_f32 v225, v94, v95
	v_cvt_pk_bf16_f32 v226, v88, v89
	v_cvt_pk_bf16_f32 v227, v90, v91
	global_store_dwordx4 v[150:151], v[224:227], off
	v_pk_mul_f32 v[68:69], v[68:69], v[174:175] op_sel_hi:[1,0]
	v_pk_mul_f32 v[70:71], v[70:71], v[174:175] op_sel_hi:[1,0]
	v_pk_mul_f32 v[64:65], v[64:65], v[174:175] op_sel_hi:[1,0]
	v_pk_mul_f32 v[66:67], v[66:67], v[174:175] op_sel_hi:[1,0]
	v_and_b32_e32 v72, 0x7fffffff, v68
	v_and_b32_e32 v73, 0x7fffffff, v69
	v_and_b32_e32 v80, 0x7fffffff, v70
	v_and_b32_e32 v81, 0x7fffffff, v71
	v_and_b32_e32 v104, 0x7fffffff, v64
	v_and_b32_e32 v105, 0x7fffffff, v65
	v_and_b32_e32 v112, 0x7fffffff, v66
	v_and_b32_e32 v113, 0x7fffffff, v67
	v_pk_fma_f32 v[72:73], v[72:73], s[42:43], 1.0 op_sel_hi:[1,0,0]
	v_pk_fma_f32 v[80:81], v[80:81], s[42:43], 1.0 op_sel_hi:[1,0,0]
	v_pk_fma_f32 v[104:105], v[104:105], s[42:43], 1.0 op_sel_hi:[1,0,0]
	v_pk_fma_f32 v[112:113], v[112:113], s[42:43], 1.0 op_sel_hi:[1,0,0]
	v_pk_mul_f32 v[78:79], v[68:69], v[68:69]
	v_pk_mul_f32 v[86:87], v[70:71], v[70:71]
	v_pk_mul_f32 v[110:111], v[64:65], v[64:65]
	v_pk_mul_f32 v[118:119], v[66:67], v[66:67]
	v_rcp_f32_e32 v74, v72
	v_rcp_f32_e32 v75, v73
	v_rcp_f32_e32 v82, v80
	v_rcp_f32_e32 v83, v81
	v_rcp_f32_e32 v106, v104
	v_rcp_f32_e32 v107, v105
	v_rcp_f32_e32 v114, v112
	v_rcp_f32_e32 v115, v113
	v_pk_mul_f32 v[78:79], v[78:79], s[54:55] op_sel_hi:[1,0]
	v_pk_mul_f32 v[86:87], v[86:87], s[54:55] op_sel_hi:[1,0]
	v_pk_mul_f32 v[110:111], v[110:111], s[54:55] op_sel_hi:[1,0]
	v_pk_mul_f32 v[118:119], v[118:119], s[54:55] op_sel_hi:[1,0]
	v_pk_fma_f32 v[76:77], v[74:75], s[44:45], v[144:145] op_sel_hi:[1,0,0]
; __device__ __forceinline__ unsigned cvt_pk_bf16(float lo, float hi) { unsigned r; asm volatile("v_cvt_pk_bf16_f32 %0, %1, %2" : "=v"(r) : "v"(lo), "v"(hi)); return r; }
; #define GAS __attribute__((address_space(1)))
; __device__ __forceinline__ f32x2 gelu_pk(f32x2 v) {
;     const f32x2 av = __builtin_elementwise_abs(v), d = av * 0.2316418882f + 1.0f;
;     f32x2 t; t.x = __builtin_amdgcn_rcpf(d.x); t.y = __builtin_amdgcn_rcpf(d.y);
;     f32x2 q = t * 0.5307027145f + (-0.7265760135f); q = q * t + 0.7107068705f; q = q * t + (-0.142248368f); q = q * t + 0.127414796f; q = q * t;
;     const f32x2 s = (v * v) * (-0.72134752044f);
;     f32x2 e; e.x = __builtin_amdgcn_exp2f(s.x); e.y = __builtin_amdgcn_exp2f(s.y);
;     const f32x2 m = v * (q * e), r = v - m;
;     f32x2 o; o.x = v.x < 0.f ? m.x : r.x; o.y = v.y < 0.f ? m.y : r.y; return o;
; }
;     DI void operator()(AccRef acc, const pg8::Unit& u, int wr, int wc, int, int) const {
;     ...
;                 } else if (kind == 3) {
;                     f32x2 a = pg8::gelu_pk((f32x2){v0[0], v0[1]}), b = pg8::gelu_pk((f32x2){v0[2], v0[3]}), c = pg8::gelu_pk((f32x2){v1[0], v1[1]}), d = pg8::gelu_pk((f32x2){v1[2], v1[3]});
;                     v0 = (f32x4){a.x, a.y, b.x, b.y}; v1 = (f32x4){c.x, c.y, d.x, d.y};
;                 } else if (kind == 4) {
; #pragma unroll
;                     for (int e = 0; e < 4; ++e) { v0[e] = __builtin_amdgcn_rcpf(1.0f + __builtin_amdgcn_exp2f(v0[e])); v1[e] = __builtin_amdgcn_rcpf(1.0f + __builtin_amdgcn_exp2f(v1[e])); }
;                 }
;                 u32x4 w; w.x = cvt_pk_bf16(v0[0], v0[1]); w.y = cvt_pk_bf16(v0[2], v0[3]); w.z = cvt_pk_bf16(v1[0], v1[1]); w.w = cvt_pk_bf16(v1[2], v1[3]);
;                 *(GAS u32x4*)(dummy ? dummy + lane_ * 8 : Z + (size_t)lrow * ldz + col) = w;
	v_pk_fma_f32 v[84:85], v[82:83], s[44:45], v[144:145] op_sel_hi:[1,0,0]
	v_pk_fma_f32 v[108:109], v[106:107], s[44:45], v[144:145] op_sel_hi:[1,0,0]
	v_pk_fma_f32 v[116:117], v[114:115], s[44:45], v[144:145] op_sel_hi:[1,0,0]
	v_exp_f32_e32 v78, v78
	v_exp_f32_e32 v79, v79
	v_exp_f32_e32 v86, v86
	v_exp_f32_e32 v87, v87
	v_exp_f32_e32 v110, v110
	v_exp_f32_e32 v111, v111
	v_exp_f32_e32 v118, v118
	v_exp_f32_e32 v119, v119
	v_pk_fma_f32 v[76:77], v[74:75], v[76:77], s[48:49] op_sel_hi:[1,1,0]
	v_pk_fma_f32 v[84:85], v[82:83], v[84:85], s[48:49] op_sel_hi:[1,1,0]
	v_pk_fma_f32 v[108:109], v[106:107], v[108:109], s[48:49] op_sel_hi:[1,1,0]
	v_pk_fma_f32 v[116:117], v[114:115], v[116:117], s[48:49] op_sel_hi:[1,1,0]
	v_pk_fma_f32 v[76:77], v[74:75], v[76:77], s[50:51] op_sel_hi:[1,1,0]
	v_pk_fma_f32 v[84:85], v[82:83], v[84:85], s[50:51] op_sel_hi:[1,1,0]
	v_pk_fma_f32 v[108:109], v[106:107], v[108:109], s[50:51] op_sel_hi:[1,1,0]
	v_pk_fma_f32 v[116:117], v[114:115], v[116:117], s[50:51] op_sel_hi:[1,1,0]
	v_pk_fma_f32 v[76:77], v[74:75], v[76:77], s[52:53] op_sel_hi:[1,1,0]
	v_pk_fma_f32 v[84:85], v[82:83], v[84:85], s[52:53] op_sel_hi:[1,1,0]
	v_pk_fma_f32 v[108:109], v[106:107], v[108:109], s[52:53] op_sel_hi:[1,1,0]
	v_pk_fma_f32 v[116:117], v[114:115], v[116:117], s[52:53] op_sel_hi:[1,1,0]
	v_pk_mul_f32 v[74:75], v[74:75], v[76:77]
	v_pk_mul_f32 v[82:83], v[82:83], v[84:85]
	v_pk_mul_f32 v[106:107], v[106:107], v[108:109]
	v_pk_mul_f32 v[114:115], v[114:115], v[116:117]
	v_pk_mul_f32 v[74:75], v[78:79], v[74:75]
	v_pk_mul_f32 v[82:83], v[86:87], v[82:83]
	v_pk_mul_f32 v[106:107], v[110:111], v[106:107]
	v_pk_mul_f32 v[114:115], v[118:119], v[114:115]
	v_pk_mul_f32 v[78:79], v[68:69], v[74:75]
	v_pk_mul_f32 v[86:87], v[70:71], v[82:83]
	v_pk_mul_f32 v[110:111], v[64:65], v[106:107]
	v_pk_mul_f32 v[118:119], v[66:67], v[114:115]
	v_pk_fma_f32 v[74:75], v[68:69], v[74:75], v[68:69] neg_lo:[1,0,0] neg_hi:[1,0,0]
	v_pk_fma_f32 v[82:83], v[70:71], v[82:83], v[70:71] neg_lo:[1,0,0] neg_hi:[1,0,0]
	v_pk_fma_f32 v[106:107], v[64:65], v[106:107], v[64:65] neg_lo:[1,0,0] neg_hi:[1,0,0]
	v_pk_fma_f32 v[114:115], v[66:67], v[114:115], v[66:67] neg_lo:[1,0,0] neg_hi:[1,0,0]
	v_cmp_gt_f32_e64 s[98:99], 0, v68
	v_cmp_gt_f32_e64 s[16:17], 0, v70
	v_cmp_gt_f32_e64 s[10:11], 0, v64
	v_cmp_gt_f32_e64 s[12:13], 0, v66
	v_cndmask_b32_e64 v68, v74, v78, s[98:99]
	v_cndmask_b32_e64 v70, v82, v86, s[16:17]
	v_cndmask_b32_e64 v64, v106, v110, s[10:11]
	v_cndmask_b32_e64 v66, v114, v118, s[12:13]
	v_cmp_gt_f32_e64 s[98:99], 0, v69
	v_cmp_gt_f32_e64 s[16:17], 0, v71
	v_cmp_gt_f32_e64 s[10:11], 0, v65
	v_cmp_gt_f32_e64 s[12:13], 0, v67
	v_cndmask_b32_e64 v69, v75, v79, s[98:99]
	v_cndmask_b32_e64 v71, v83, v87, s[16:17]
	v_cndmask_b32_e64 v65, v107, v111, s[10:11]
	v_cndmask_b32_e64 v67, v115, v119, s[12:13]
	v_cvt_pk_bf16_f32 v228, v68, v69
	v_cvt_pk_bf16_f32 v229, v70, v71
	v_cvt_pk_bf16_f32 v230, v64, v65
	v_cvt_pk_bf16_f32 v231, v66, v67
	global_store_dwordx4 v[150:151], v[228:231], off offset:256
	v_lshl_add_u64 v[146:147], v[150:151], 0, s[0:1]
	v_pk_mul_f32 v[60:61], v[60:61], v[176:177] op_sel_hi:[1,0]
	v_pk_mul_f32 v[62:63], v[62:63], v[176:177] op_sel_hi:[1,0]
	v_pk_mul_f32 v[56:57], v[56:57], v[176:177] op_sel_hi:[1,0]
	v_pk_mul_f32 v[58:59], v[58:59], v[176:177] op_sel_hi:[1,0]
	v_and_b32_e32 v72, 0x7fffffff, v60
	v_and_b32_e32 v73, 0x7fffffff, v61
	v_and_b32_e32 v80, 0x7fffffff, v62
	v_and_b32_e32 v81, 0x7fffffff, v63
	v_and_b32_e32 v104, 0x7fffffff, v56
	v_and_b32_e32 v105, 0x7fffffff, v57
	v_and_b32_e32 v112, 0x7fffffff, v58
	v_and_b32_e32 v113, 0x7fffffff, v59
	v_pk_fma_f32 v[72:73], v[72:73], s[42:43], 1.0 op_sel_hi:[1,0,0]
	v_pk_fma_f32 v[80:81], v[80:81], s[42:43], 1.0 op_sel_hi:[1,0,0]
	v_pk_fma_f32 v[104:105], v[104:105], s[42:43], 1.0 op_sel_hi:[1,0,0]
	v_pk_fma_f32 v[112:113], v[112:113], s[42:43], 1.0 op_sel_hi:[1,0,0]
	v_pk_mul_f32 v[78:79], v[60:61], v[60:61]
	v_pk_mul_f32 v[86:87], v[62:63], v[62:63]
	v_pk_mul_f32 v[110:111], v[56:57], v[56:57]
	v_pk_mul_f32 v[118:119], v[58:59], v[58:59]
	v_rcp_f32_e32 v74, v72
	v_rcp_f32_e32 v75, v73
	v_rcp_f32_e32 v82, v80
	v_rcp_f32_e32 v83, v81
	v_rcp_f32_e32 v106, v104
	v_rcp_f32_e32 v107, v105
	v_rcp_f32_e32 v114, v112
	v_rcp_f32_e32 v115, v113
	v_pk_mul_f32 v[78:79], v[78:79], s[54:55] op_sel_hi:[1,0]
	v_pk_mul_f32 v[86:87], v[86:87], s[54:55] op_sel_hi:[1,0]
	v_pk_mul_f32 v[110:111], v[110:111], s[54:55] op_sel_hi:[1,0]
	v_pk_mul_f32 v[118:119], v[118:119], s[54:55] op_sel_hi:[1,0]
	v_pk_fma_f32 v[76:77], v[74:75], s[44:45], v[144:145] op_sel_hi:[1,0,0]
	v_pk_fma_f32 v[84:85], v[82:83], s[44:45], v[144:145] op_sel_hi:[1,0,0]
	v_pk_fma_f32 v[108:109], v[106:107], s[44:45], v[144:145] op_sel_hi:[1,0,0]
	v_pk_fma_f32 v[116:117], v[114:115], s[44:45], v[144:145] op_sel_hi:[1,0,0]
	v_exp_f32_e32 v78, v78
	v_exp_f32_e32 v79, v79
	v_exp_f32_e32 v86, v86
	v_exp_f32_e32 v87, v87
	v_exp_f32_e32 v110, v110
	v_exp_f32_e32 v111, v111
	v_exp_f32_e32 v118, v118
	v_exp_f32_e32 v119, v119
	v_pk_fma_f32 v[76:77], v[74:75], v[76:77], s[48:49] op_sel_hi:[1,1,0]
	v_pk_fma_f32 v[84:85], v[82:83], v[84:85], s[48:49] op_sel_hi:[1,1,0]
	v_pk_fma_f32 v[108:109], v[106:107], v[108:109], s[48:49] op_sel_hi:[1,1,0]
	v_pk_fma_f32 v[116:117], v[114:115], v[116:117], s[48:49] op_sel_hi:[1,1,0]
	v_pk_fma_f32 v[76:77], v[74:75], v[76:77], s[50:51] op_sel_hi:[1,1,0]
	v_pk_fma_f32 v[84:85], v[82:83], v[84:85], s[50:51] op_sel_hi:[1,1,0]
	v_pk_fma_f32 v[108:109], v[106:107], v[108:109], s[50:51] op_sel_hi:[1,1,0]
	v_pk_fma_f32 v[116:117], v[114:115], v[116:117], s[50:51] op_sel_hi:[1,1,0]
	v_pk_fma_f32 v[76:77], v[74:75], v[76:77], s[52:53] op_sel_hi:[1,1,0]
; __device__ __forceinline__ unsigned cvt_pk_bf16(float lo, float hi) { unsigned r; asm volatile("v_cvt_pk_bf16_f32 %0, %1, %2" : "=v"(r) : "v"(lo), "v"(hi)); return r; }
; #define GAS __attribute__((address_space(1)))
; __device__ __forceinline__ f32x2 gelu_pk(f32x2 v) {
;     const f32x2 av = __builtin_elementwise_abs(v), d = av * 0.2316418882f + 1.0f;
;     f32x2 t; t.x = __builtin_amdgcn_rcpf(d.x); t.y = __builtin_amdgcn_rcpf(d.y);
;     f32x2 q = t * 0.5307027145f + (-0.7265760135f); q = q * t + 0.7107068705f; q = q * t + (-0.142248368f); q = q * t + 0.127414796f; q = q * t;
;     const f32x2 s = (v * v) * (-0.72134752044f);
;     f32x2 e; e.x = __builtin_amdgcn_exp2f(s.x); e.y = __builtin_amdgcn_exp2f(s.y);
;     const f32x2 m = v * (q * e), r = v - m;
;     f32x2 o; o.x = v.x < 0.f ? m.x : r.x; o.y = v.y < 0.f ? m.y : r.y; return o;
; }
;     DI void operator()(AccRef acc, const pg8::Unit& u, int wr, int wc, int, int) const {
;     ...
;                 } else if (kind == 3) {
;                     f32x2 a = pg8::gelu_pk((f32x2){v0[0], v0[1]}), b = pg8::gelu_pk((f32x2){v0[2], v0[3]}), c = pg8::gelu_pk((f32x2){v1[0], v1[1]}), d = pg8::gelu_pk((f32x2){v1[2], v1[3]});
;                     v0 = (f32x4){a.x, a.y, b.x, b.y}; v1 = (f32x4){c.x, c.y, d.x, d.y};
;                 } else if (kind == 4) {
; #pragma unroll
;                     for (int e = 0; e < 4; ++e) { v0[e] = __builtin_amdgcn_rcpf(1.0f + __builtin_amdgcn_exp2f(v0[e])); v1[e] = __builtin_amdgcn_rcpf(1.0f + __builtin_amdgcn_exp2f(v1[e])); }
;                 }
;                 u32x4 w; w.x = cvt_pk_bf16(v0[0], v0[1]); w.y = cvt_pk_bf16(v0[2], v0[3]); w.z = cvt_pk_bf16(v1[0], v1[1]); w.w = cvt_pk_bf16(v1[2], v1[3]);
;                 *(GAS u32x4*)(dummy ? dummy + lane_ * 8 : Z + (size_t)lrow * ldz + col) = w;
	v_pk_fma_f32 v[84:85], v[82:83], v[84:85], s[52:53] op_sel_hi:[1,1,0]
	v_pk_fma_f32 v[108:109], v[106:107], v[108:109], s[52:53] op_sel_hi:[1,1,0]
	v_pk_fma_f32 v[116:117], v[114:115], v[116:117], s[52:53] op_sel_hi:[1,1,0]
	v_pk_mul_f32 v[74:75], v[74:75], v[76:77]
	v_pk_mul_f32 v[82:83], v[82:83], v[84:85]
	v_pk_mul_f32 v[106:107], v[106:107], v[108:109]
	v_pk_mul_f32 v[114:115], v[114:115], v[116:117]
	v_pk_mul_f32 v[74:75], v[78:79], v[74:75]
	v_pk_mul_f32 v[82:83], v[86:87], v[82:83]
	v_pk_mul_f32 v[106:107], v[110:111], v[106:107]
	v_pk_mul_f32 v[114:115], v[118:119], v[114:115]
	v_pk_mul_f32 v[78:79], v[60:61], v[74:75]
	v_pk_mul_f32 v[86:87], v[62:63], v[82:83]
	v_pk_mul_f32 v[110:111], v[56:57], v[106:107]
	v_pk_mul_f32 v[118:119], v[58:59], v[114:115]
	v_pk_fma_f32 v[74:75], v[60:61], v[74:75], v[60:61] neg_lo:[1,0,0] neg_hi:[1,0,0]
	v_pk_fma_f32 v[82:83], v[62:63], v[82:83], v[62:63] neg_lo:[1,0,0] neg_hi:[1,0,0]
	v_pk_fma_f32 v[106:107], v[56:57], v[106:107], v[56:57] neg_lo:[1,0,0] neg_hi:[1,0,0]
	v_pk_fma_f32 v[114:115], v[58:59], v[114:115], v[58:59] neg_lo:[1,0,0] neg_hi:[1,0,0]
	v_cmp_gt_f32_e64 s[98:99], 0, v60
	v_cmp_gt_f32_e64 s[16:17], 0, v62
	v_cmp_gt_f32_e64 s[10:11], 0, v56
	v_cmp_gt_f32_e64 s[12:13], 0, v58
	v_cndmask_b32_e64 v60, v74, v78, s[98:99]
	v_cndmask_b32_e64 v62, v82, v86, s[16:17]
	v_cndmask_b32_e64 v56, v106, v110, s[10:11]
	v_cndmask_b32_e64 v58, v114, v118, s[12:13]
	v_cmp_gt_f32_e64 s[98:99], 0, v61
	v_cmp_gt_f32_e64 s[16:17], 0, v63
	v_cmp_gt_f32_e64 s[10:11], 0, v57
	v_cmp_gt_f32_e64 s[12:13], 0, v59
	v_cndmask_b32_e64 v61, v75, v79, s[98:99]
	v_cndmask_b32_e64 v63, v83, v87, s[16:17]
	v_cndmask_b32_e64 v57, v107, v111, s[10:11]
	v_cndmask_b32_e64 v59, v115, v119, s[12:13]
	v_cvt_pk_bf16_f32 v216, v60, v61
	v_cvt_pk_bf16_f32 v217, v62, v63
	v_cvt_pk_bf16_f32 v218, v56, v57
	v_cvt_pk_bf16_f32 v219, v58, v59
	global_store_dwordx4 v[146:147], v[216:219], off
	v_pk_mul_f32 v[52:53], v[52:53], v[176:177] op_sel_hi:[1,0]
	v_pk_mul_f32 v[54:55], v[54:55], v[176:177] op_sel_hi:[1,0]
	v_pk_mul_f32 v[48:49], v[48:49], v[176:177] op_sel_hi:[1,0]
	v_pk_mul_f32 v[50:51], v[50:51], v[176:177] op_sel_hi:[1,0]
	v_and_b32_e32 v72, 0x7fffffff, v52
	v_and_b32_e32 v73, 0x7fffffff, v53
	v_and_b32_e32 v80, 0x7fffffff, v54
	v_and_b32_e32 v81, 0x7fffffff, v55
	v_and_b32_e32 v104, 0x7fffffff, v48
	v_and_b32_e32 v105, 0x7fffffff, v49
	v_and_b32_e32 v112, 0x7fffffff, v50
	v_and_b32_e32 v113, 0x7fffffff, v51
	v_pk_fma_f32 v[72:73], v[72:73], s[42:43], 1.0 op_sel_hi:[1,0,0]
	v_pk_fma_f32 v[80:81], v[80:81], s[42:43], 1.0 op_sel_hi:[1,0,0]
	v_pk_fma_f32 v[104:105], v[104:105], s[42:43], 1.0 op_sel_hi:[1,0,0]
	v_pk_fma_f32 v[112:113], v[112:113], s[42:43], 1.0 op_sel_hi:[1,0,0]
	v_pk_mul_f32 v[78:79], v[52:53], v[52:53]
	v_pk_mul_f32 v[86:87], v[54:55], v[54:55]
	v_pk_mul_f32 v[110:111], v[48:49], v[48:49]
	v_pk_mul_f32 v[118:119], v[50:51], v[50:51]
	v_rcp_f32_e32 v74, v72
	v_rcp_f32_e32 v75, v73
	v_rcp_f32_e32 v82, v80
	v_rcp_f32_e32 v83, v81
	v_rcp_f32_e32 v106, v104
	v_rcp_f32_e32 v107, v105
	v_rcp_f32_e32 v114, v112
	v_rcp_f32_e32 v115, v113
	v_pk_mul_f32 v[78:79], v[78:79], s[54:55] op_sel_hi:[1,0]
	v_pk_mul_f32 v[86:87], v[86:87], s[54:55] op_sel_hi:[1,0]
	v_pk_mul_f32 v[110:111], v[110:111], s[54:55] op_sel_hi:[1,0]
	v_pk_mul_f32 v[118:119], v[118:119], s[54:55] op_sel_hi:[1,0]
	v_pk_fma_f32 v[76:77], v[74:75], s[44:45], v[144:145] op_sel_hi:[1,0,0]
	v_pk_fma_f32 v[84:85], v[82:83], s[44:45], v[144:145] op_sel_hi:[1,0,0]
	v_pk_fma_f32 v[108:109], v[106:107], s[44:45], v[144:145] op_sel_hi:[1,0,0]
	v_pk_fma_f32 v[116:117], v[114:115], s[44:45], v[144:145] op_sel_hi:[1,0,0]
	v_exp_f32_e32 v78, v78
	v_exp_f32_e32 v79, v79
	v_exp_f32_e32 v86, v86
	v_exp_f32_e32 v87, v87
	v_exp_f32_e32 v110, v110
	v_exp_f32_e32 v111, v111
	v_exp_f32_e32 v118, v118
	v_exp_f32_e32 v119, v119
	v_pk_fma_f32 v[76:77], v[74:75], v[76:77], s[48:49] op_sel_hi:[1,1,0]
	v_pk_fma_f32 v[84:85], v[82:83], v[84:85], s[48:49] op_sel_hi:[1,1,0]
	v_pk_fma_f32 v[108:109], v[106:107], v[108:109], s[48:49] op_sel_hi:[1,1,0]
	v_pk_fma_f32 v[116:117], v[114:115], v[116:117], s[48:49] op_sel_hi:[1,1,0]
	v_pk_fma_f32 v[76:77], v[74:75], v[76:77], s[50:51] op_sel_hi:[1,1,0]
	v_pk_fma_f32 v[84:85], v[82:83], v[84:85], s[50:51] op_sel_hi:[1,1,0]
	v_pk_fma_f32 v[108:109], v[106:107], v[108:109], s[50:51] op_sel_hi:[1,1,0]
	v_pk_fma_f32 v[116:117], v[114:115], v[116:117], s[50:51] op_sel_hi:[1,1,0]
	v_pk_fma_f32 v[76:77], v[74:75], v[76:77], s[52:53] op_sel_hi:[1,1,0]
	v_pk_fma_f32 v[84:85], v[82:83], v[84:85], s[52:53] op_sel_hi:[1,1,0]
	v_pk_fma_f32 v[108:109], v[106:107], v[108:109], s[52:53] op_sel_hi:[1,1,0]
	v_pk_fma_f32 v[116:117], v[114:115], v[116:117], s[52:53] op_sel_hi:[1,1,0]
	v_pk_mul_f32 v[74:75], v[74:75], v[76:77]
	v_pk_mul_f32 v[82:83], v[82:83], v[84:85]
	v_pk_mul_f32 v[106:107], v[106:107], v[108:109]
	v_pk_mul_f32 v[114:115], v[114:115], v[116:117]
	v_pk_mul_f32 v[74:75], v[78:79], v[74:75]
	v_pk_mul_f32 v[82:83], v[86:87], v[82:83]
	v_pk_mul_f32 v[106:107], v[110:111], v[106:107]
	v_pk_mul_f32 v[114:115], v[118:119], v[114:115]
	v_pk_mul_f32 v[78:79], v[52:53], v[74:75]
	v_pk_mul_f32 v[86:87], v[54:55], v[82:83]
	v_pk_mul_f32 v[110:111], v[48:49], v[106:107]
	v_pk_mul_f32 v[118:119], v[50:51], v[114:115]
	v_pk_fma_f32 v[74:75], v[52:53], v[74:75], v[52:53] neg_lo:[1,0,0] neg_hi:[1,0,0]
	v_pk_fma_f32 v[82:83], v[54:55], v[82:83], v[54:55] neg_lo:[1,0,0] neg_hi:[1,0,0]
	v_pk_fma_f32 v[106:107], v[48:49], v[106:107], v[48:49] neg_lo:[1,0,0] neg_hi:[1,0,0]
	v_pk_fma_f32 v[114:115], v[50:51], v[114:115], v[50:51] neg_lo:[1,0,0] neg_hi:[1,0,0]
; __device__ __forceinline__ unsigned cvt_pk_bf16(float lo, float hi) { unsigned r; asm volatile("v_cvt_pk_bf16_f32 %0, %1, %2" : "=v"(r) : "v"(lo), "v"(hi)); return r; }
; #define GAS __attribute__((address_space(1)))
; __device__ __forceinline__ f32x2 gelu_pk(f32x2 v) {
;     const f32x2 av = __builtin_elementwise_abs(v), d = av * 0.2316418882f + 1.0f;
;     f32x2 t; t.x = __builtin_amdgcn_rcpf(d.x); t.y = __builtin_amdgcn_rcpf(d.y);
;     f32x2 q = t * 0.5307027145f + (-0.7265760135f); q = q * t + 0.7107068705f; q = q * t + (-0.142248368f); q = q * t + 0.127414796f; q = q * t;
;     const f32x2 s = (v * v) * (-0.72134752044f);
;     f32x2 e; e.x = __builtin_amdgcn_exp2f(s.x); e.y = __builtin_amdgcn_exp2f(s.y);
;     const f32x2 m = v * (q * e), r = v - m;
;     f32x2 o; o.x = v.x < 0.f ? m.x : r.x; o.y = v.y < 0.f ? m.y : r.y; return o;
; }
;     DI void operator()(AccRef acc, const pg8::Unit& u, int wr, int wc, int, int) const {
;     ...
;                 } else if (kind == 3) {
;                     f32x2 a = pg8::gelu_pk((f32x2){v0[0], v0[1]}), b = pg8::gelu_pk((f32x2){v0[2], v0[3]}), c = pg8::gelu_pk((f32x2){v1[0], v1[1]}), d = pg8::gelu_pk((f32x2){v1[2], v1[3]});
;                     v0 = (f32x4){a.x, a.y, b.x, b.y}; v1 = (f32x4){c.x, c.y, d.x, d.y};
;                 } else if (kind == 4) {
; #pragma unroll
;                     for (int e = 0; e < 4; ++e) { v0[e] = __builtin_amdgcn_rcpf(1.0f + __builtin_amdgcn_exp2f(v0[e])); v1[e] = __builtin_amdgcn_rcpf(1.0f + __builtin_amdgcn_exp2f(v1[e])); }
;                 }
;                 u32x4 w; w.x = cvt_pk_bf16(v0[0], v0[1]); w.y = cvt_pk_bf16(v0[2], v0[3]); w.z = cvt_pk_bf16(v1[0], v1[1]); w.w = cvt_pk_bf16(v1[2], v1[3]);
;                 *(GAS u32x4*)(dummy ? dummy + lane_ * 8 : Z + (size_t)lrow * ldz + col) = w;
	v_cmp_gt_f32_e64 s[98:99], 0, v52
	v_cmp_gt_f32_e64 s[16:17], 0, v54
	v_cmp_gt_f32_e64 s[10:11], 0, v48
	v_cmp_gt_f32_e64 s[12:13], 0, v50
	v_cndmask_b32_e64 v52, v74, v78, s[98:99]
	v_cndmask_b32_e64 v54, v82, v86, s[16:17]
	v_cndmask_b32_e64 v48, v106, v110, s[10:11]
	v_cndmask_b32_e64 v50, v114, v118, s[12:13]
	v_cmp_gt_f32_e64 s[98:99], 0, v53
	v_cmp_gt_f32_e64 s[16:17], 0, v55
	v_cmp_gt_f32_e64 s[10:11], 0, v49
	v_cmp_gt_f32_e64 s[12:13], 0, v51
	v_cndmask_b32_e64 v53, v75, v79, s[98:99]
	v_cndmask_b32_e64 v55, v83, v87, s[16:17]
	v_cndmask_b32_e64 v49, v107, v111, s[10:11]
	v_cndmask_b32_e64 v51, v115, v119, s[12:13]
	v_cvt_pk_bf16_f32 v220, v52, v53
	v_cvt_pk_bf16_f32 v221, v54, v55
	v_cvt_pk_bf16_f32 v222, v48, v49
	v_cvt_pk_bf16_f32 v223, v50, v51
	global_store_dwordx4 v[146:147], v[220:223], off offset:256
	v_lshl_add_u64 v[150:151], v[146:147], 0, s[2:3]
	v_pk_mul_f32 v[44:45], v[44:45], v[178:179] op_sel_hi:[1,0]
	v_pk_mul_f32 v[46:47], v[46:47], v[178:179] op_sel_hi:[1,0]
	v_pk_mul_f32 v[40:41], v[40:41], v[178:179] op_sel_hi:[1,0]
	v_pk_mul_f32 v[42:43], v[42:43], v[178:179] op_sel_hi:[1,0]
	v_and_b32_e32 v72, 0x7fffffff, v44
	v_and_b32_e32 v73, 0x7fffffff, v45
	v_and_b32_e32 v80, 0x7fffffff, v46
	v_and_b32_e32 v81, 0x7fffffff, v47
	v_and_b32_e32 v104, 0x7fffffff, v40
	v_and_b32_e32 v105, 0x7fffffff, v41
	v_and_b32_e32 v112, 0x7fffffff, v42
	v_and_b32_e32 v113, 0x7fffffff, v43
	v_pk_fma_f32 v[72:73], v[72:73], s[42:43], 1.0 op_sel_hi:[1,0,0]
	v_pk_fma_f32 v[80:81], v[80:81], s[42:43], 1.0 op_sel_hi:[1,0,0]
	v_pk_fma_f32 v[104:105], v[104:105], s[42:43], 1.0 op_sel_hi:[1,0,0]
	v_pk_fma_f32 v[112:113], v[112:113], s[42:43], 1.0 op_sel_hi:[1,0,0]
	v_pk_mul_f32 v[78:79], v[44:45], v[44:45]
	v_pk_mul_f32 v[86:87], v[46:47], v[46:47]
	v_pk_mul_f32 v[110:111], v[40:41], v[40:41]
	v_pk_mul_f32 v[118:119], v[42:43], v[42:43]
	v_rcp_f32_e32 v74, v72
	v_rcp_f32_e32 v75, v73
	v_rcp_f32_e32 v82, v80
	v_rcp_f32_e32 v83, v81
	v_rcp_f32_e32 v106, v104
	v_rcp_f32_e32 v107, v105
	v_rcp_f32_e32 v114, v112
	v_rcp_f32_e32 v115, v113
	v_pk_mul_f32 v[78:79], v[78:79], s[54:55] op_sel_hi:[1,0]
	v_pk_mul_f32 v[86:87], v[86:87], s[54:55] op_sel_hi:[1,0]
	v_pk_mul_f32 v[110:111], v[110:111], s[54:55] op_sel_hi:[1,0]
	v_pk_mul_f32 v[118:119], v[118:119], s[54:55] op_sel_hi:[1,0]
	v_pk_fma_f32 v[76:77], v[74:75], s[44:45], v[144:145] op_sel_hi:[1,0,0]
	v_pk_fma_f32 v[84:85], v[82:83], s[44:45], v[144:145] op_sel_hi:[1,0,0]
	v_pk_fma_f32 v[108:109], v[106:107], s[44:45], v[144:145] op_sel_hi:[1,0,0]
	v_pk_fma_f32 v[116:117], v[114:115], s[44:45], v[144:145] op_sel_hi:[1,0,0]
	v_exp_f32_e32 v78, v78
	v_exp_f32_e32 v79, v79
	v_exp_f32_e32 v86, v86
	v_exp_f32_e32 v87, v87
	v_exp_f32_e32 v110, v110
	v_exp_f32_e32 v111, v111
	v_exp_f32_e32 v118, v118
	v_exp_f32_e32 v119, v119
	v_pk_fma_f32 v[76:77], v[74:75], v[76:77], s[48:49] op_sel_hi:[1,1,0]
	v_pk_fma_f32 v[84:85], v[82:83], v[84:85], s[48:49] op_sel_hi:[1,1,0]
	v_pk_fma_f32 v[108:109], v[106:107], v[108:109], s[48:49] op_sel_hi:[1,1,0]
	v_pk_fma_f32 v[116:117], v[114:115], v[116:117], s[48:49] op_sel_hi:[1,1,0]
	v_pk_fma_f32 v[76:77], v[74:75], v[76:77], s[50:51] op_sel_hi:[1,1,0]
	v_pk_fma_f32 v[84:85], v[82:83], v[84:85], s[50:51] op_sel_hi:[1,1,0]
	v_pk_fma_f32 v[108:109], v[106:107], v[108:109], s[50:51] op_sel_hi:[1,1,0]
	v_pk_fma_f32 v[116:117], v[114:115], v[116:117], s[50:51] op_sel_hi:[1,1,0]
	v_pk_fma_f32 v[76:77], v[74:75], v[76:77], s[52:53] op_sel_hi:[1,1,0]
	v_pk_fma_f32 v[84:85], v[82:83], v[84:85], s[52:53] op_sel_hi:[1,1,0]
	v_pk_fma_f32 v[108:109], v[106:107], v[108:109], s[52:53] op_sel_hi:[1,1,0]
	v_pk_fma_f32 v[116:117], v[114:115], v[116:117], s[52:53] op_sel_hi:[1,1,0]
	v_pk_mul_f32 v[74:75], v[74:75], v[76:77]
	v_pk_mul_f32 v[82:83], v[82:83], v[84:85]
	v_pk_mul_f32 v[106:107], v[106:107], v[108:109]
	v_pk_mul_f32 v[114:115], v[114:115], v[116:117]
	v_pk_mul_f32 v[74:75], v[78:79], v[74:75]
	v_pk_mul_f32 v[82:83], v[86:87], v[82:83]
	v_pk_mul_f32 v[106:107], v[110:111], v[106:107]
	v_pk_mul_f32 v[114:115], v[118:119], v[114:115]
	v_pk_mul_f32 v[78:79], v[44:45], v[74:75]
	v_pk_mul_f32 v[86:87], v[46:47], v[82:83]
	v_pk_mul_f32 v[110:111], v[40:41], v[106:107]
	v_pk_mul_f32 v[118:119], v[42:43], v[114:115]
	v_pk_fma_f32 v[74:75], v[44:45], v[74:75], v[44:45] neg_lo:[1,0,0] neg_hi:[1,0,0]
	v_pk_fma_f32 v[82:83], v[46:47], v[82:83], v[46:47] neg_lo:[1,0,0] neg_hi:[1,0,0]
	v_pk_fma_f32 v[106:107], v[40:41], v[106:107], v[40:41] neg_lo:[1,0,0] neg_hi:[1,0,0]
	v_pk_fma_f32 v[114:115], v[42:43], v[114:115], v[42:43] neg_lo:[1,0,0] neg_hi:[1,0,0]
	v_cmp_gt_f32_e64 s[98:99], 0, v44
	v_cmp_gt_f32_e64 s[16:17], 0, v46
	v_cmp_gt_f32_e64 s[10:11], 0, v40
	v_cmp_gt_f32_e64 s[12:13], 0, v42
	v_cndmask_b32_e64 v44, v74, v78, s[98:99]
	v_cndmask_b32_e64 v46, v82, v86, s[16:17]
	v_cndmask_b32_e64 v40, v106, v110, s[10:11]
	v_cndmask_b32_e64 v42, v114, v118, s[12:13]
	v_cmp_gt_f32_e64 s[98:99], 0, v45
	v_cmp_gt_f32_e64 s[16:17], 0, v47
	v_cmp_gt_f32_e64 s[10:11], 0, v41
	v_cmp_gt_f32_e64 s[12:13], 0, v43
	v_cndmask_b32_e64 v45, v75, v79, s[98:99]
	v_cndmask_b32_e64 v47, v83, v87, s[16:17]
	v_cndmask_b32_e64 v41, v107, v111, s[10:11]
	v_cndmask_b32_e64 v43, v115, v119, s[12:13]
	v_cvt_pk_bf16_f32 v224, v44, v45
	v_cvt_pk_bf16_f32 v225, v46, v47
	v_cvt_pk_bf16_f32 v226, v40, v41
	v_cvt_pk_bf16_f32 v227, v42, v43
	global_store_dwordx4 v[150:151], v[224:227], off
	v_pk_mul_f32 v[36:37], v[36:37], v[178:179] op_sel_hi:[1,0]
	v_pk_mul_f32 v[38:39], v[38:39], v[178:179] op_sel_hi:[1,0]
	v_pk_mul_f32 v[32:33], v[32:33], v[178:179] op_sel_hi:[1,0]
	v_pk_mul_f32 v[34:35], v[34:35], v[178:179] op_sel_hi:[1,0]
; __device__ __forceinline__ unsigned cvt_pk_bf16(float lo, float hi) { unsigned r; asm volatile("v_cvt_pk_bf16_f32 %0, %1, %2" : "=v"(r) : "v"(lo), "v"(hi)); return r; }
; #define GAS __attribute__((address_space(1)))
; __device__ __forceinline__ f32x2 gelu_pk(f32x2 v) {
;     const f32x2 av = __builtin_elementwise_abs(v), d = av * 0.2316418882f + 1.0f;
;     f32x2 t; t.x = __builtin_amdgcn_rcpf(d.x); t.y = __builtin_amdgcn_rcpf(d.y);
;     f32x2 q = t * 0.5307027145f + (-0.7265760135f); q = q * t + 0.7107068705f; q = q * t + (-0.142248368f); q = q * t + 0.127414796f; q = q * t;
;     const f32x2 s = (v * v) * (-0.72134752044f);
;     f32x2 e; e.x = __builtin_amdgcn_exp2f(s.x); e.y = __builtin_amdgcn_exp2f(s.y);
;     const f32x2 m = v * (q * e), r = v - m;
;     f32x2 o; o.x = v.x < 0.f ? m.x : r.x; o.y = v.y < 0.f ? m.y : r.y; return o;
; }
;     DI void operator()(AccRef acc, const pg8::Unit& u, int wr, int wc, int, int) const {
;     ...
;                 } else if (kind == 3) {
;                     f32x2 a = pg8::gelu_pk((f32x2){v0[0], v0[1]}), b = pg8::gelu_pk((f32x2){v0[2], v0[3]}), c = pg8::gelu_pk((f32x2){v1[0], v1[1]}), d = pg8::gelu_pk((f32x2){v1[2], v1[3]});
;                     v0 = (f32x4){a.x, a.y, b.x, b.y}; v1 = (f32x4){c.x, c.y, d.x, d.y};
;                 } else if (kind == 4) {
; #pragma unroll
;                     for (int e = 0; e < 4; ++e) { v0[e] = __builtin_amdgcn_rcpf(1.0f + __builtin_amdgcn_exp2f(v0[e])); v1[e] = __builtin_amdgcn_rcpf(1.0f + __builtin_amdgcn_exp2f(v1[e])); }
;                 }
;                 u32x4 w; w.x = cvt_pk_bf16(v0[0], v0[1]); w.y = cvt_pk_bf16(v0[2], v0[3]); w.z = cvt_pk_bf16(v1[0], v1[1]); w.w = cvt_pk_bf16(v1[2], v1[3]);
;                 *(GAS u32x4*)(dummy ? dummy + lane_ * 8 : Z + (size_t)lrow * ldz + col) = w;
	v_and_b32_e32 v72, 0x7fffffff, v36
	v_and_b32_e32 v73, 0x7fffffff, v37
	v_and_b32_e32 v80, 0x7fffffff, v38
	v_and_b32_e32 v81, 0x7fffffff, v39
	v_and_b32_e32 v104, 0x7fffffff, v32
	v_and_b32_e32 v105, 0x7fffffff, v33
	v_and_b32_e32 v112, 0x7fffffff, v34
	v_and_b32_e32 v113, 0x7fffffff, v35
	v_pk_fma_f32 v[72:73], v[72:73], s[42:43], 1.0 op_sel_hi:[1,0,0]
	v_pk_fma_f32 v[80:81], v[80:81], s[42:43], 1.0 op_sel_hi:[1,0,0]
	v_pk_fma_f32 v[104:105], v[104:105], s[42:43], 1.0 op_sel_hi:[1,0,0]
	v_pk_fma_f32 v[112:113], v[112:113], s[42:43], 1.0 op_sel_hi:[1,0,0]
	v_pk_mul_f32 v[78:79], v[36:37], v[36:37]
	v_pk_mul_f32 v[86:87], v[38:39], v[38:39]
	v_pk_mul_f32 v[110:111], v[32:33], v[32:33]
	v_pk_mul_f32 v[118:119], v[34:35], v[34:35]
	v_rcp_f32_e32 v74, v72
	v_rcp_f32_e32 v75, v73
	v_rcp_f32_e32 v82, v80
	v_rcp_f32_e32 v83, v81
	v_rcp_f32_e32 v106, v104
	v_rcp_f32_e32 v107, v105
	v_rcp_f32_e32 v114, v112
	v_rcp_f32_e32 v115, v113
	v_pk_mul_f32 v[78:79], v[78:79], s[54:55] op_sel_hi:[1,0]
	v_pk_mul_f32 v[86:87], v[86:87], s[54:55] op_sel_hi:[1,0]
	v_pk_mul_f32 v[110:111], v[110:111], s[54:55] op_sel_hi:[1,0]
	v_pk_mul_f32 v[118:119], v[118:119], s[54:55] op_sel_hi:[1,0]
	v_pk_fma_f32 v[76:77], v[74:75], s[44:45], v[144:145] op_sel_hi:[1,0,0]
	v_pk_fma_f32 v[84:85], v[82:83], s[44:45], v[144:145] op_sel_hi:[1,0,0]
	v_pk_fma_f32 v[108:109], v[106:107], s[44:45], v[144:145] op_sel_hi:[1,0,0]
	v_pk_fma_f32 v[116:117], v[114:115], s[44:45], v[144:145] op_sel_hi:[1,0,0]
	v_exp_f32_e32 v78, v78
	v_exp_f32_e32 v79, v79
	v_exp_f32_e32 v86, v86
	v_exp_f32_e32 v87, v87
	v_exp_f32_e32 v110, v110
	v_exp_f32_e32 v111, v111
	v_exp_f32_e32 v118, v118
	v_exp_f32_e32 v119, v119
	v_pk_fma_f32 v[76:77], v[74:75], v[76:77], s[48:49] op_sel_hi:[1,1,0]
	v_pk_fma_f32 v[84:85], v[82:83], v[84:85], s[48:49] op_sel_hi:[1,1,0]
	v_pk_fma_f32 v[108:109], v[106:107], v[108:109], s[48:49] op_sel_hi:[1,1,0]
	v_pk_fma_f32 v[116:117], v[114:115], v[116:117], s[48:49] op_sel_hi:[1,1,0]
	v_pk_fma_f32 v[76:77], v[74:75], v[76:77], s[50:51] op_sel_hi:[1,1,0]
	v_pk_fma_f32 v[84:85], v[82:83], v[84:85], s[50:51] op_sel_hi:[1,1,0]
	v_pk_fma_f32 v[108:109], v[106:107], v[108:109], s[50:51] op_sel_hi:[1,1,0]
	v_pk_fma_f32 v[116:117], v[114:115], v[116:117], s[50:51] op_sel_hi:[1,1,0]
	v_pk_fma_f32 v[76:77], v[74:75], v[76:77], s[52:53] op_sel_hi:[1,1,0]
	v_pk_fma_f32 v[84:85], v[82:83], v[84:85], s[52:53] op_sel_hi:[1,1,0]
	v_pk_fma_f32 v[108:109], v[106:107], v[108:109], s[52:53] op_sel_hi:[1,1,0]
	v_pk_fma_f32 v[116:117], v[114:115], v[116:117], s[52:53] op_sel_hi:[1,1,0]
	v_pk_mul_f32 v[74:75], v[74:75], v[76:77]
	v_pk_mul_f32 v[82:83], v[82:83], v[84:85]
	v_pk_mul_f32 v[106:107], v[106:107], v[108:109]
	v_pk_mul_f32 v[114:115], v[114:115], v[116:117]
	v_pk_mul_f32 v[74:75], v[78:79], v[74:75]
	v_pk_mul_f32 v[82:83], v[86:87], v[82:83]
	v_pk_mul_f32 v[106:107], v[110:111], v[106:107]
	v_pk_mul_f32 v[114:115], v[118:119], v[114:115]
	v_pk_mul_f32 v[78:79], v[36:37], v[74:75]
	v_pk_mul_f32 v[86:87], v[38:39], v[82:83]
	v_pk_mul_f32 v[110:111], v[32:33], v[106:107]
	v_pk_mul_f32 v[118:119], v[34:35], v[114:115]
	v_pk_fma_f32 v[74:75], v[36:37], v[74:75], v[36:37] neg_lo:[1,0,0] neg_hi:[1,0,0]
	v_pk_fma_f32 v[82:83], v[38:39], v[82:83], v[38:39] neg_lo:[1,0,0] neg_hi:[1,0,0]
	v_pk_fma_f32 v[106:107], v[32:33], v[106:107], v[32:33] neg_lo:[1,0,0] neg_hi:[1,0,0]
	v_pk_fma_f32 v[114:115], v[34:35], v[114:115], v[34:35] neg_lo:[1,0,0] neg_hi:[1,0,0]
	v_cmp_gt_f32_e64 s[98:99], 0, v36
	v_cmp_gt_f32_e64 s[16:17], 0, v38
	v_cmp_gt_f32_e64 s[10:11], 0, v32
	v_cmp_gt_f32_e64 s[12:13], 0, v34
	v_cndmask_b32_e64 v36, v74, v78, s[98:99]
	v_cndmask_b32_e64 v38, v82, v86, s[16:17]
	v_cndmask_b32_e64 v32, v106, v110, s[10:11]
	v_cndmask_b32_e64 v34, v114, v118, s[12:13]
	v_cmp_gt_f32_e64 s[98:99], 0, v37
	v_cmp_gt_f32_e64 s[16:17], 0, v39
	v_cmp_gt_f32_e64 s[10:11], 0, v33
	v_cmp_gt_f32_e64 s[12:13], 0, v35
	v_cndmask_b32_e64 v37, v75, v79, s[98:99]
	v_cndmask_b32_e64 v39, v83, v87, s[16:17]
	v_cndmask_b32_e64 v33, v107, v111, s[10:11]
	v_cndmask_b32_e64 v35, v115, v119, s[12:13]
	v_cvt_pk_bf16_f32 v228, v36, v37
	v_cvt_pk_bf16_f32 v229, v38, v39
	v_cvt_pk_bf16_f32 v230, v32, v33
	v_cvt_pk_bf16_f32 v231, v34, v35
	global_store_dwordx4 v[150:151], v[228:231], off offset:256
	v_lshl_add_u64 v[146:147], v[150:151], 0, s[2:3]
	v_pk_mul_f32 v[28:29], v[28:29], v[180:181] op_sel_hi:[1,0]
	v_pk_mul_f32 v[30:31], v[30:31], v[180:181] op_sel_hi:[1,0]
	v_pk_mul_f32 v[24:25], v[24:25], v[180:181] op_sel_hi:[1,0]
	v_pk_mul_f32 v[26:27], v[26:27], v[180:181] op_sel_hi:[1,0]
	v_and_b32_e32 v72, 0x7fffffff, v28
	v_and_b32_e32 v73, 0x7fffffff, v29
	v_and_b32_e32 v80, 0x7fffffff, v30
	v_and_b32_e32 v81, 0x7fffffff, v31
	v_and_b32_e32 v104, 0x7fffffff, v24
	v_and_b32_e32 v105, 0x7fffffff, v25
	v_and_b32_e32 v112, 0x7fffffff, v26
	v_and_b32_e32 v113, 0x7fffffff, v27
	v_pk_fma_f32 v[72:73], v[72:73], s[42:43], 1.0 op_sel_hi:[1,0,0]
	v_pk_fma_f32 v[80:81], v[80:81], s[42:43], 1.0 op_sel_hi:[1,0,0]
	v_pk_fma_f32 v[104:105], v[104:105], s[42:43], 1.0 op_sel_hi:[1,0,0]
	v_pk_fma_f32 v[112:113], v[112:113], s[42:43], 1.0 op_sel_hi:[1,0,0]
	v_pk_mul_f32 v[78:79], v[28:29], v[28:29]
	v_pk_mul_f32 v[86:87], v[30:31], v[30:31]
	v_pk_mul_f32 v[110:111], v[24:25], v[24:25]
	v_pk_mul_f32 v[118:119], v[26:27], v[26:27]
	v_rcp_f32_e32 v74, v72
	v_rcp_f32_e32 v75, v73
	v_rcp_f32_e32 v82, v80
	v_rcp_f32_e32 v83, v81
	v_rcp_f32_e32 v106, v104
	v_rcp_f32_e32 v107, v105
	v_rcp_f32_e32 v114, v112
	v_rcp_f32_e32 v115, v113
	v_pk_mul_f32 v[78:79], v[78:79], s[54:55] op_sel_hi:[1,0]
	v_pk_mul_f32 v[86:87], v[86:87], s[54:55] op_sel_hi:[1,0]
; __device__ __forceinline__ unsigned cvt_pk_bf16(float lo, float hi) { unsigned r; asm volatile("v_cvt_pk_bf16_f32 %0, %1, %2" : "=v"(r) : "v"(lo), "v"(hi)); return r; }
; #define GAS __attribute__((address_space(1)))
; __device__ __forceinline__ f32x2 gelu_pk(f32x2 v) {
;     const f32x2 av = __builtin_elementwise_abs(v), d = av * 0.2316418882f + 1.0f;
;     f32x2 t; t.x = __builtin_amdgcn_rcpf(d.x); t.y = __builtin_amdgcn_rcpf(d.y);
;     f32x2 q = t * 0.5307027145f + (-0.7265760135f); q = q * t + 0.7107068705f; q = q * t + (-0.142248368f); q = q * t + 0.127414796f; q = q * t;
;     const f32x2 s = (v * v) * (-0.72134752044f);
;     f32x2 e; e.x = __builtin_amdgcn_exp2f(s.x); e.y = __builtin_amdgcn_exp2f(s.y);
;     const f32x2 m = v * (q * e), r = v - m;
;     f32x2 o; o.x = v.x < 0.f ? m.x : r.x; o.y = v.y < 0.f ? m.y : r.y; return o;
; }
;     DI void operator()(AccRef acc, const pg8::Unit& u, int wr, int wc, int, int) const {
;     ...
;                 } else if (kind == 3) {
;                     f32x2 a = pg8::gelu_pk((f32x2){v0[0], v0[1]}), b = pg8::gelu_pk((f32x2){v0[2], v0[3]}), c = pg8::gelu_pk((f32x2){v1[0], v1[1]}), d = pg8::gelu_pk((f32x2){v1[2], v1[3]});
;                     v0 = (f32x4){a.x, a.y, b.x, b.y}; v1 = (f32x4){c.x, c.y, d.x, d.y};
;                 } else if (kind == 4) {
; #pragma unroll
;                     for (int e = 0; e < 4; ++e) { v0[e] = __builtin_amdgcn_rcpf(1.0f + __builtin_amdgcn_exp2f(v0[e])); v1[e] = __builtin_amdgcn_rcpf(1.0f + __builtin_amdgcn_exp2f(v1[e])); }
;                 }
;                 u32x4 w; w.x = cvt_pk_bf16(v0[0], v0[1]); w.y = cvt_pk_bf16(v0[2], v0[3]); w.z = cvt_pk_bf16(v1[0], v1[1]); w.w = cvt_pk_bf16(v1[2], v1[3]);
;                 *(GAS u32x4*)(dummy ? dummy + lane_ * 8 : Z + (size_t)lrow * ldz + col) = w;
	v_pk_mul_f32 v[110:111], v[110:111], s[54:55] op_sel_hi:[1,0]
	v_pk_mul_f32 v[118:119], v[118:119], s[54:55] op_sel_hi:[1,0]
	v_pk_fma_f32 v[76:77], v[74:75], s[44:45], v[144:145] op_sel_hi:[1,0,0]
	v_pk_fma_f32 v[84:85], v[82:83], s[44:45], v[144:145] op_sel_hi:[1,0,0]
	v_pk_fma_f32 v[108:109], v[106:107], s[44:45], v[144:145] op_sel_hi:[1,0,0]
	v_pk_fma_f32 v[116:117], v[114:115], s[44:45], v[144:145] op_sel_hi:[1,0,0]
	v_exp_f32_e32 v78, v78
	v_exp_f32_e32 v79, v79
	v_exp_f32_e32 v86, v86
	v_exp_f32_e32 v87, v87
	v_exp_f32_e32 v110, v110
	v_exp_f32_e32 v111, v111
	v_exp_f32_e32 v118, v118
	v_exp_f32_e32 v119, v119
	v_pk_fma_f32 v[76:77], v[74:75], v[76:77], s[48:49] op_sel_hi:[1,1,0]
	v_pk_fma_f32 v[84:85], v[82:83], v[84:85], s[48:49] op_sel_hi:[1,1,0]
	v_pk_fma_f32 v[108:109], v[106:107], v[108:109], s[48:49] op_sel_hi:[1,1,0]
	v_pk_fma_f32 v[116:117], v[114:115], v[116:117], s[48:49] op_sel_hi:[1,1,0]
	v_pk_fma_f32 v[76:77], v[74:75], v[76:77], s[50:51] op_sel_hi:[1,1,0]
	v_pk_fma_f32 v[84:85], v[82:83], v[84:85], s[50:51] op_sel_hi:[1,1,0]
	v_pk_fma_f32 v[108:109], v[106:107], v[108:109], s[50:51] op_sel_hi:[1,1,0]
	v_pk_fma_f32 v[116:117], v[114:115], v[116:117], s[50:51] op_sel_hi:[1,1,0]
	v_pk_fma_f32 v[76:77], v[74:75], v[76:77], s[52:53] op_sel_hi:[1,1,0]
	v_pk_fma_f32 v[84:85], v[82:83], v[84:85], s[52:53] op_sel_hi:[1,1,0]
	v_pk_fma_f32 v[108:109], v[106:107], v[108:109], s[52:53] op_sel_hi:[1,1,0]
	v_pk_fma_f32 v[116:117], v[114:115], v[116:117], s[52:53] op_sel_hi:[1,1,0]
	v_pk_mul_f32 v[74:75], v[74:75], v[76:77]
	v_pk_mul_f32 v[82:83], v[82:83], v[84:85]
	v_pk_mul_f32 v[106:107], v[106:107], v[108:109]
	v_pk_mul_f32 v[114:115], v[114:115], v[116:117]
	v_pk_mul_f32 v[74:75], v[78:79], v[74:75]
	v_pk_mul_f32 v[82:83], v[86:87], v[82:83]
	v_pk_mul_f32 v[106:107], v[110:111], v[106:107]
	v_pk_mul_f32 v[114:115], v[118:119], v[114:115]
	v_pk_mul_f32 v[78:79], v[28:29], v[74:75]
	v_pk_mul_f32 v[86:87], v[30:31], v[82:83]
	v_pk_mul_f32 v[110:111], v[24:25], v[106:107]
	v_pk_mul_f32 v[118:119], v[26:27], v[114:115]
	v_pk_fma_f32 v[74:75], v[28:29], v[74:75], v[28:29] neg_lo:[1,0,0] neg_hi:[1,0,0]
	v_pk_fma_f32 v[82:83], v[30:31], v[82:83], v[30:31] neg_lo:[1,0,0] neg_hi:[1,0,0]
	v_pk_fma_f32 v[106:107], v[24:25], v[106:107], v[24:25] neg_lo:[1,0,0] neg_hi:[1,0,0]
	v_pk_fma_f32 v[114:115], v[26:27], v[114:115], v[26:27] neg_lo:[1,0,0] neg_hi:[1,0,0]
	v_cmp_gt_f32_e64 s[98:99], 0, v28
	v_cmp_gt_f32_e64 s[16:17], 0, v30
	v_cmp_gt_f32_e64 s[10:11], 0, v24
	v_cmp_gt_f32_e64 s[12:13], 0, v26
	v_cndmask_b32_e64 v28, v74, v78, s[98:99]
	v_cndmask_b32_e64 v30, v82, v86, s[16:17]
	v_cndmask_b32_e64 v24, v106, v110, s[10:11]
	v_cndmask_b32_e64 v26, v114, v118, s[12:13]
	v_cmp_gt_f32_e64 s[98:99], 0, v29
	v_cmp_gt_f32_e64 s[16:17], 0, v31
	v_cmp_gt_f32_e64 s[10:11], 0, v25
	v_cmp_gt_f32_e64 s[12:13], 0, v27
	v_cndmask_b32_e64 v29, v75, v79, s[98:99]
	v_cndmask_b32_e64 v31, v83, v87, s[16:17]
	v_cndmask_b32_e64 v25, v107, v111, s[10:11]
	v_cndmask_b32_e64 v27, v115, v119, s[12:13]
	v_cvt_pk_bf16_f32 v216, v28, v29
	v_cvt_pk_bf16_f32 v217, v30, v31
	v_cvt_pk_bf16_f32 v218, v24, v25
	v_cvt_pk_bf16_f32 v219, v26, v27
	global_store_dwordx4 v[146:147], v[216:219], off
	v_pk_mul_f32 v[20:21], v[20:21], v[180:181] op_sel_hi:[1,0]
	v_pk_mul_f32 v[22:23], v[22:23], v[180:181] op_sel_hi:[1,0]
	v_pk_mul_f32 v[16:17], v[16:17], v[180:181] op_sel_hi:[1,0]
	v_pk_mul_f32 v[18:19], v[18:19], v[180:181] op_sel_hi:[1,0]
	v_and_b32_e32 v72, 0x7fffffff, v20
	v_and_b32_e32 v73, 0x7fffffff, v21
	v_and_b32_e32 v80, 0x7fffffff, v22
	v_and_b32_e32 v81, 0x7fffffff, v23
	v_and_b32_e32 v104, 0x7fffffff, v16
	v_and_b32_e32 v105, 0x7fffffff, v17
	v_and_b32_e32 v112, 0x7fffffff, v18
	v_and_b32_e32 v113, 0x7fffffff, v19
	v_pk_fma_f32 v[72:73], v[72:73], s[42:43], 1.0 op_sel_hi:[1,0,0]
	v_pk_fma_f32 v[80:81], v[80:81], s[42:43], 1.0 op_sel_hi:[1,0,0]
	v_pk_fma_f32 v[104:105], v[104:105], s[42:43], 1.0 op_sel_hi:[1,0,0]
	v_pk_fma_f32 v[112:113], v[112:113], s[42:43], 1.0 op_sel_hi:[1,0,0]
	v_pk_mul_f32 v[78:79], v[20:21], v[20:21]
	v_pk_mul_f32 v[86:87], v[22:23], v[22:23]
	v_pk_mul_f32 v[110:111], v[16:17], v[16:17]
	v_pk_mul_f32 v[118:119], v[18:19], v[18:19]
	v_rcp_f32_e32 v74, v72
	v_rcp_f32_e32 v75, v73
	v_rcp_f32_e32 v82, v80
	v_rcp_f32_e32 v83, v81
	v_rcp_f32_e32 v106, v104
	v_rcp_f32_e32 v107, v105
	v_rcp_f32_e32 v114, v112
	v_rcp_f32_e32 v115, v113
	v_pk_mul_f32 v[78:79], v[78:79], s[54:55] op_sel_hi:[1,0]
	v_pk_mul_f32 v[86:87], v[86:87], s[54:55] op_sel_hi:[1,0]
	v_pk_mul_f32 v[110:111], v[110:111], s[54:55] op_sel_hi:[1,0]
	v_pk_mul_f32 v[118:119], v[118:119], s[54:55] op_sel_hi:[1,0]
	v_pk_fma_f32 v[76:77], v[74:75], s[44:45], v[144:145] op_sel_hi:[1,0,0]
	v_pk_fma_f32 v[84:85], v[82:83], s[44:45], v[144:145] op_sel_hi:[1,0,0]
	v_pk_fma_f32 v[108:109], v[106:107], s[44:45], v[144:145] op_sel_hi:[1,0,0]
	v_pk_fma_f32 v[116:117], v[114:115], s[44:45], v[144:145] op_sel_hi:[1,0,0]
	v_exp_f32_e32 v78, v78
	v_exp_f32_e32 v79, v79
	v_exp_f32_e32 v86, v86
	v_exp_f32_e32 v87, v87
	v_exp_f32_e32 v110, v110
	v_exp_f32_e32 v111, v111
	v_exp_f32_e32 v118, v118
	v_exp_f32_e32 v119, v119
	v_pk_fma_f32 v[76:77], v[74:75], v[76:77], s[48:49] op_sel_hi:[1,1,0]
	v_pk_fma_f32 v[84:85], v[82:83], v[84:85], s[48:49] op_sel_hi:[1,1,0]
	v_pk_fma_f32 v[108:109], v[106:107], v[108:109], s[48:49] op_sel_hi:[1,1,0]
	v_pk_fma_f32 v[116:117], v[114:115], v[116:117], s[48:49] op_sel_hi:[1,1,0]
	v_pk_fma_f32 v[76:77], v[74:75], v[76:77], s[50:51] op_sel_hi:[1,1,0]
	v_pk_fma_f32 v[84:85], v[82:83], v[84:85], s[50:51] op_sel_hi:[1,1,0]
	v_pk_fma_f32 v[108:109], v[106:107], v[108:109], s[50:51] op_sel_hi:[1,1,0]
; __device__ __forceinline__ unsigned cvt_pk_bf16(float lo, float hi) { unsigned r; asm volatile("v_cvt_pk_bf16_f32 %0, %1, %2" : "=v"(r) : "v"(lo), "v"(hi)); return r; }
; #define GAS __attribute__((address_space(1)))
; __device__ __forceinline__ f32x2 gelu_pk(f32x2 v) {
;     const f32x2 av = __builtin_elementwise_abs(v), d = av * 0.2316418882f + 1.0f;
;     f32x2 t; t.x = __builtin_amdgcn_rcpf(d.x); t.y = __builtin_amdgcn_rcpf(d.y);
;     f32x2 q = t * 0.5307027145f + (-0.7265760135f); q = q * t + 0.7107068705f; q = q * t + (-0.142248368f); q = q * t + 0.127414796f; q = q * t;
;     const f32x2 s = (v * v) * (-0.72134752044f);
;     f32x2 e; e.x = __builtin_amdgcn_exp2f(s.x); e.y = __builtin_amdgcn_exp2f(s.y);
;     const f32x2 m = v * (q * e), r = v - m;
;     f32x2 o; o.x = v.x < 0.f ? m.x : r.x; o.y = v.y < 0.f ? m.y : r.y; return o;
; }
;     DI void operator()(AccRef acc, const pg8::Unit& u, int wr, int wc, int, int) const {
;     ...
;                 } else if (kind == 3) {
;                     f32x2 a = pg8::gelu_pk((f32x2){v0[0], v0[1]}), b = pg8::gelu_pk((f32x2){v0[2], v0[3]}), c = pg8::gelu_pk((f32x2){v1[0], v1[1]}), d = pg8::gelu_pk((f32x2){v1[2], v1[3]});
;                     v0 = (f32x4){a.x, a.y, b.x, b.y}; v1 = (f32x4){c.x, c.y, d.x, d.y};
;                 } else if (kind == 4) {
; #pragma unroll
;                     for (int e = 0; e < 4; ++e) { v0[e] = __builtin_amdgcn_rcpf(1.0f + __builtin_amdgcn_exp2f(v0[e])); v1[e] = __builtin_amdgcn_rcpf(1.0f + __builtin_amdgcn_exp2f(v1[e])); }
;                 }
;                 u32x4 w; w.x = cvt_pk_bf16(v0[0], v0[1]); w.y = cvt_pk_bf16(v0[2], v0[3]); w.z = cvt_pk_bf16(v1[0], v1[1]); w.w = cvt_pk_bf16(v1[2], v1[3]);
;                 *(GAS u32x4*)(dummy ? dummy + lane_ * 8 : Z + (size_t)lrow * ldz + col) = w;
	v_pk_fma_f32 v[116:117], v[114:115], v[116:117], s[50:51] op_sel_hi:[1,1,0]
	v_pk_fma_f32 v[76:77], v[74:75], v[76:77], s[52:53] op_sel_hi:[1,1,0]
	v_pk_fma_f32 v[84:85], v[82:83], v[84:85], s[52:53] op_sel_hi:[1,1,0]
	v_pk_fma_f32 v[108:109], v[106:107], v[108:109], s[52:53] op_sel_hi:[1,1,0]
	v_pk_fma_f32 v[116:117], v[114:115], v[116:117], s[52:53] op_sel_hi:[1,1,0]
	v_pk_mul_f32 v[74:75], v[74:75], v[76:77]
	v_pk_mul_f32 v[82:83], v[82:83], v[84:85]
	v_pk_mul_f32 v[106:107], v[106:107], v[108:109]
	v_pk_mul_f32 v[114:115], v[114:115], v[116:117]
	v_pk_mul_f32 v[74:75], v[78:79], v[74:75]
	v_pk_mul_f32 v[82:83], v[86:87], v[82:83]
	v_pk_mul_f32 v[106:107], v[110:111], v[106:107]
	v_pk_mul_f32 v[114:115], v[118:119], v[114:115]
	v_pk_mul_f32 v[78:79], v[20:21], v[74:75]
	v_pk_mul_f32 v[86:87], v[22:23], v[82:83]
	v_pk_mul_f32 v[110:111], v[16:17], v[106:107]
	v_pk_mul_f32 v[118:119], v[18:19], v[114:115]
	v_pk_fma_f32 v[74:75], v[20:21], v[74:75], v[20:21] neg_lo:[1,0,0] neg_hi:[1,0,0]
	v_pk_fma_f32 v[82:83], v[22:23], v[82:83], v[22:23] neg_lo:[1,0,0] neg_hi:[1,0,0]
	v_pk_fma_f32 v[106:107], v[16:17], v[106:107], v[16:17] neg_lo:[1,0,0] neg_hi:[1,0,0]
	v_pk_fma_f32 v[114:115], v[18:19], v[114:115], v[18:19] neg_lo:[1,0,0] neg_hi:[1,0,0]
	v_cmp_gt_f32_e64 s[98:99], 0, v20
	v_cmp_gt_f32_e64 s[16:17], 0, v22
	v_cmp_gt_f32_e64 s[10:11], 0, v16
	v_cmp_gt_f32_e64 s[12:13], 0, v18
	v_cndmask_b32_e64 v20, v74, v78, s[98:99]
	v_cndmask_b32_e64 v22, v82, v86, s[16:17]
	v_cndmask_b32_e64 v16, v106, v110, s[10:11]
	v_cndmask_b32_e64 v18, v114, v118, s[12:13]
	v_cmp_gt_f32_e64 s[98:99], 0, v21
	v_cmp_gt_f32_e64 s[16:17], 0, v23
	v_cmp_gt_f32_e64 s[10:11], 0, v17
	v_cmp_gt_f32_e64 s[12:13], 0, v19
	v_cndmask_b32_e64 v21, v75, v79, s[98:99]
	v_cndmask_b32_e64 v23, v83, v87, s[16:17]
	v_cndmask_b32_e64 v17, v107, v111, s[10:11]
	v_cndmask_b32_e64 v19, v115, v119, s[12:13]
	v_cvt_pk_bf16_f32 v220, v20, v21
	v_cvt_pk_bf16_f32 v221, v22, v23
	v_cvt_pk_bf16_f32 v222, v16, v17
	v_cvt_pk_bf16_f32 v223, v18, v19
	global_store_dwordx4 v[146:147], v[220:223], off offset:256
	v_lshl_add_u64 v[150:151], v[146:147], 0, s[2:3]
	v_pk_mul_f32 v[12:13], v[12:13], v[182:183] op_sel_hi:[1,0]
	v_pk_mul_f32 v[14:15], v[14:15], v[182:183] op_sel_hi:[1,0]
	v_pk_mul_f32 v[8:9], v[8:9], v[182:183] op_sel_hi:[1,0]
	v_pk_mul_f32 v[10:11], v[10:11], v[182:183] op_sel_hi:[1,0]
	v_and_b32_e32 v72, 0x7fffffff, v12
	v_and_b32_e32 v73, 0x7fffffff, v13
	v_and_b32_e32 v80, 0x7fffffff, v14
	v_and_b32_e32 v81, 0x7fffffff, v15
	v_and_b32_e32 v104, 0x7fffffff, v8
	v_and_b32_e32 v105, 0x7fffffff, v9
	v_and_b32_e32 v112, 0x7fffffff, v10
	v_and_b32_e32 v113, 0x7fffffff, v11
	v_pk_fma_f32 v[72:73], v[72:73], s[42:43], 1.0 op_sel_hi:[1,0,0]
	v_pk_fma_f32 v[80:81], v[80:81], s[42:43], 1.0 op_sel_hi:[1,0,0]
	v_pk_fma_f32 v[104:105], v[104:105], s[42:43], 1.0 op_sel_hi:[1,0,0]
	v_pk_fma_f32 v[112:113], v[112:113], s[42:43], 1.0 op_sel_hi:[1,0,0]
	v_pk_mul_f32 v[78:79], v[12:13], v[12:13]
	v_pk_mul_f32 v[86:87], v[14:15], v[14:15]
	v_pk_mul_f32 v[110:111], v[8:9], v[8:9]
	v_pk_mul_f32 v[118:119], v[10:11], v[10:11]
	v_rcp_f32_e32 v74, v72
	v_rcp_f32_e32 v75, v73
	v_rcp_f32_e32 v82, v80
	v_rcp_f32_e32 v83, v81
	v_rcp_f32_e32 v106, v104
	v_rcp_f32_e32 v107, v105
	v_rcp_f32_e32 v114, v112
	v_rcp_f32_e32 v115, v113
	v_pk_mul_f32 v[78:79], v[78:79], s[54:55] op_sel_hi:[1,0]
	v_pk_mul_f32 v[86:87], v[86:87], s[54:55] op_sel_hi:[1,0]
	v_pk_mul_f32 v[110:111], v[110:111], s[54:55] op_sel_hi:[1,0]
	v_pk_mul_f32 v[118:119], v[118:119], s[54:55] op_sel_hi:[1,0]
	v_pk_fma_f32 v[76:77], v[74:75], s[44:45], v[144:145] op_sel_hi:[1,0,0]
	v_pk_fma_f32 v[84:85], v[82:83], s[44:45], v[144:145] op_sel_hi:[1,0,0]
	v_pk_fma_f32 v[108:109], v[106:107], s[44:45], v[144:145] op_sel_hi:[1,0,0]
	v_pk_fma_f32 v[116:117], v[114:115], s[44:45], v[144:145] op_sel_hi:[1,0,0]
	v_exp_f32_e32 v78, v78
	v_exp_f32_e32 v79, v79
	v_exp_f32_e32 v86, v86
	v_exp_f32_e32 v87, v87
	v_exp_f32_e32 v110, v110
	v_exp_f32_e32 v111, v111
	v_exp_f32_e32 v118, v118
	v_exp_f32_e32 v119, v119
	v_pk_fma_f32 v[76:77], v[74:75], v[76:77], s[48:49] op_sel_hi:[1,1,0]
	v_pk_fma_f32 v[84:85], v[82:83], v[84:85], s[48:49] op_sel_hi:[1,1,0]
	v_pk_fma_f32 v[108:109], v[106:107], v[108:109], s[48:49] op_sel_hi:[1,1,0]
	v_pk_fma_f32 v[116:117], v[114:115], v[116:117], s[48:49] op_sel_hi:[1,1,0]
	v_pk_fma_f32 v[76:77], v[74:75], v[76:77], s[50:51] op_sel_hi:[1,1,0]
	v_pk_fma_f32 v[84:85], v[82:83], v[84:85], s[50:51] op_sel_hi:[1,1,0]
	v_pk_fma_f32 v[108:109], v[106:107], v[108:109], s[50:51] op_sel_hi:[1,1,0]
	v_pk_fma_f32 v[116:117], v[114:115], v[116:117], s[50:51] op_sel_hi:[1,1,0]
	v_pk_fma_f32 v[76:77], v[74:75], v[76:77], s[52:53] op_sel_hi:[1,1,0]
	v_pk_fma_f32 v[84:85], v[82:83], v[84:85], s[52:53] op_sel_hi:[1,1,0]
	v_pk_fma_f32 v[108:109], v[106:107], v[108:109], s[52:53] op_sel_hi:[1,1,0]
	v_pk_fma_f32 v[116:117], v[114:115], v[116:117], s[52:53] op_sel_hi:[1,1,0]
	v_pk_mul_f32 v[74:75], v[74:75], v[76:77]
	v_pk_mul_f32 v[82:83], v[82:83], v[84:85]
	v_pk_mul_f32 v[106:107], v[106:107], v[108:109]
	v_pk_mul_f32 v[114:115], v[114:115], v[116:117]
	v_pk_mul_f32 v[74:75], v[78:79], v[74:75]
	v_pk_mul_f32 v[82:83], v[86:87], v[82:83]
	v_pk_mul_f32 v[106:107], v[110:111], v[106:107]
	v_pk_mul_f32 v[114:115], v[118:119], v[114:115]
	v_pk_mul_f32 v[78:79], v[12:13], v[74:75]
	v_pk_mul_f32 v[86:87], v[14:15], v[82:83]
	v_pk_mul_f32 v[110:111], v[8:9], v[106:107]
	v_pk_mul_f32 v[118:119], v[10:11], v[114:115]
	v_pk_fma_f32 v[74:75], v[12:13], v[74:75], v[12:13] neg_lo:[1,0,0] neg_hi:[1,0,0]
; __device__ __forceinline__ unsigned cvt_pk_bf16(float lo, float hi) { unsigned r; asm volatile("v_cvt_pk_bf16_f32 %0, %1, %2" : "=v"(r) : "v"(lo), "v"(hi)); return r; }
; #define GAS __attribute__((address_space(1)))
; __device__ __forceinline__ f32x2 gelu_pk(f32x2 v) {
;     const f32x2 av = __builtin_elementwise_abs(v), d = av * 0.2316418882f + 1.0f;
;     f32x2 t; t.x = __builtin_amdgcn_rcpf(d.x); t.y = __builtin_amdgcn_rcpf(d.y);
;     f32x2 q = t * 0.5307027145f + (-0.7265760135f); q = q * t + 0.7107068705f; q = q * t + (-0.142248368f); q = q * t + 0.127414796f; q = q * t;
;     const f32x2 s = (v * v) * (-0.72134752044f);
;     f32x2 e; e.x = __builtin_amdgcn_exp2f(s.x); e.y = __builtin_amdgcn_exp2f(s.y);
;     const f32x2 m = v * (q * e), r = v - m;
;     f32x2 o; o.x = v.x < 0.f ? m.x : r.x; o.y = v.y < 0.f ? m.y : r.y; return o;
; }
;     DI void operator()(AccRef acc, const pg8::Unit& u, int wr, int wc, int, int) const {
;     ...
;                 } else if (kind == 3) {
;                     f32x2 a = pg8::gelu_pk((f32x2){v0[0], v0[1]}), b = pg8::gelu_pk((f32x2){v0[2], v0[3]}), c = pg8::gelu_pk((f32x2){v1[0], v1[1]}), d = pg8::gelu_pk((f32x2){v1[2], v1[3]});
;                     v0 = (f32x4){a.x, a.y, b.x, b.y}; v1 = (f32x4){c.x, c.y, d.x, d.y};
;                 } else if (kind == 4) {
; #pragma unroll
;                     for (int e = 0; e < 4; ++e) { v0[e] = __builtin_amdgcn_rcpf(1.0f + __builtin_amdgcn_exp2f(v0[e])); v1[e] = __builtin_amdgcn_rcpf(1.0f + __builtin_amdgcn_exp2f(v1[e])); }
;                 }
;                 u32x4 w; w.x = cvt_pk_bf16(v0[0], v0[1]); w.y = cvt_pk_bf16(v0[2], v0[3]); w.z = cvt_pk_bf16(v1[0], v1[1]); w.w = cvt_pk_bf16(v1[2], v1[3]);
;                 *(GAS u32x4*)(dummy ? dummy + lane_ * 8 : Z + (size_t)lrow * ldz + col) = w;
	v_pk_fma_f32 v[82:83], v[14:15], v[82:83], v[14:15] neg_lo:[1,0,0] neg_hi:[1,0,0]
	v_pk_fma_f32 v[106:107], v[8:9], v[106:107], v[8:9] neg_lo:[1,0,0] neg_hi:[1,0,0]
	v_pk_fma_f32 v[114:115], v[10:11], v[114:115], v[10:11] neg_lo:[1,0,0] neg_hi:[1,0,0]
	v_cmp_gt_f32_e64 s[98:99], 0, v12
	v_cmp_gt_f32_e64 s[16:17], 0, v14
	v_cmp_gt_f32_e64 s[10:11], 0, v8
	v_cmp_gt_f32_e64 s[12:13], 0, v10
	v_cndmask_b32_e64 v12, v74, v78, s[98:99]
	v_cndmask_b32_e64 v14, v82, v86, s[16:17]
	v_cndmask_b32_e64 v8, v106, v110, s[10:11]
	v_cndmask_b32_e64 v10, v114, v118, s[12:13]
	v_cmp_gt_f32_e64 s[98:99], 0, v13
	v_cmp_gt_f32_e64 s[16:17], 0, v15
	v_cmp_gt_f32_e64 s[10:11], 0, v9
	v_cmp_gt_f32_e64 s[12:13], 0, v11
	v_cndmask_b32_e64 v13, v75, v79, s[98:99]
	v_cndmask_b32_e64 v15, v83, v87, s[16:17]
	v_cndmask_b32_e64 v9, v107, v111, s[10:11]
	v_cndmask_b32_e64 v11, v115, v119, s[12:13]
	v_cvt_pk_bf16_f32 v224, v12, v13
	v_cvt_pk_bf16_f32 v225, v14, v15
	v_cvt_pk_bf16_f32 v226, v8, v9
	v_cvt_pk_bf16_f32 v227, v10, v11
	global_store_dwordx4 v[150:151], v[224:227], off
	v_pk_mul_f32 v[4:5], v[4:5], v[182:183] op_sel_hi:[1,0]
	v_pk_mul_f32 v[6:7], v[6:7], v[182:183] op_sel_hi:[1,0]
	v_pk_mul_f32 v[0:1], v[0:1], v[182:183] op_sel_hi:[1,0]
	v_pk_mul_f32 v[2:3], v[2:3], v[182:183] op_sel_hi:[1,0]
	v_and_b32_e32 v72, 0x7fffffff, v4
	v_and_b32_e32 v73, 0x7fffffff, v5
	v_and_b32_e32 v80, 0x7fffffff, v6
	v_and_b32_e32 v81, 0x7fffffff, v7
	v_and_b32_e32 v104, 0x7fffffff, v0
	v_and_b32_e32 v105, 0x7fffffff, v1
	v_and_b32_e32 v112, 0x7fffffff, v2
	v_and_b32_e32 v113, 0x7fffffff, v3
	v_pk_fma_f32 v[72:73], v[72:73], s[42:43], 1.0 op_sel_hi:[1,0,0]
	v_pk_fma_f32 v[80:81], v[80:81], s[42:43], 1.0 op_sel_hi:[1,0,0]
	v_pk_fma_f32 v[104:105], v[104:105], s[42:43], 1.0 op_sel_hi:[1,0,0]
	v_pk_fma_f32 v[112:113], v[112:113], s[42:43], 1.0 op_sel_hi:[1,0,0]
	v_pk_mul_f32 v[78:79], v[4:5], v[4:5]
	v_pk_mul_f32 v[86:87], v[6:7], v[6:7]
	v_pk_mul_f32 v[110:111], v[0:1], v[0:1]
	v_pk_mul_f32 v[118:119], v[2:3], v[2:3]
	v_rcp_f32_e32 v74, v72
	v_rcp_f32_e32 v75, v73
	v_rcp_f32_e32 v82, v80
	v_rcp_f32_e32 v83, v81
	v_rcp_f32_e32 v106, v104
	v_rcp_f32_e32 v107, v105
	v_rcp_f32_e32 v114, v112
	v_rcp_f32_e32 v115, v113
	v_pk_mul_f32 v[78:79], v[78:79], s[54:55] op_sel_hi:[1,0]
	v_pk_mul_f32 v[86:87], v[86:87], s[54:55] op_sel_hi:[1,0]
	v_pk_mul_f32 v[110:111], v[110:111], s[54:55] op_sel_hi:[1,0]
	v_pk_mul_f32 v[118:119], v[118:119], s[54:55] op_sel_hi:[1,0]
	v_pk_fma_f32 v[76:77], v[74:75], s[44:45], v[144:145] op_sel_hi:[1,0,0]
	v_pk_fma_f32 v[84:85], v[82:83], s[44:45], v[144:145] op_sel_hi:[1,0,0]
	v_pk_fma_f32 v[108:109], v[106:107], s[44:45], v[144:145] op_sel_hi:[1,0,0]
	v_pk_fma_f32 v[116:117], v[114:115], s[44:45], v[144:145] op_sel_hi:[1,0,0]
	v_exp_f32_e32 v78, v78
	v_exp_f32_e32 v79, v79
	v_exp_f32_e32 v86, v86
	v_exp_f32_e32 v87, v87
	v_exp_f32_e32 v110, v110
	v_exp_f32_e32 v111, v111
	v_exp_f32_e32 v118, v118
	v_exp_f32_e32 v119, v119
	v_pk_fma_f32 v[76:77], v[74:75], v[76:77], s[48:49] op_sel_hi:[1,1,0]
	v_pk_fma_f32 v[84:85], v[82:83], v[84:85], s[48:49] op_sel_hi:[1,1,0]
	v_pk_fma_f32 v[108:109], v[106:107], v[108:109], s[48:49] op_sel_hi:[1,1,0]
	v_pk_fma_f32 v[116:117], v[114:115], v[116:117], s[48:49] op_sel_hi:[1,1,0]
	v_pk_fma_f32 v[76:77], v[74:75], v[76:77], s[50:51] op_sel_hi:[1,1,0]
	v_pk_fma_f32 v[84:85], v[82:83], v[84:85], s[50:51] op_sel_hi:[1,1,0]
	v_pk_fma_f32 v[108:109], v[106:107], v[108:109], s[50:51] op_sel_hi:[1,1,0]
	v_pk_fma_f32 v[116:117], v[114:115], v[116:117], s[50:51] op_sel_hi:[1,1,0]
	v_pk_fma_f32 v[76:77], v[74:75], v[76:77], s[52:53] op_sel_hi:[1,1,0]
	v_pk_fma_f32 v[84:85], v[82:83], v[84:85], s[52:53] op_sel_hi:[1,1,0]
	v_pk_fma_f32 v[108:109], v[106:107], v[108:109], s[52:53] op_sel_hi:[1,1,0]
	v_pk_fma_f32 v[116:117], v[114:115], v[116:117], s[52:53] op_sel_hi:[1,1,0]
	v_pk_mul_f32 v[74:75], v[74:75], v[76:77]
	v_pk_mul_f32 v[82:83], v[82:83], v[84:85]
	v_pk_mul_f32 v[106:107], v[106:107], v[108:109]
	v_pk_mul_f32 v[114:115], v[114:115], v[116:117]
	v_pk_mul_f32 v[74:75], v[78:79], v[74:75]
	v_pk_mul_f32 v[82:83], v[86:87], v[82:83]
	v_pk_mul_f32 v[106:107], v[110:111], v[106:107]
	v_pk_mul_f32 v[114:115], v[118:119], v[114:115]
	v_pk_mul_f32 v[78:79], v[4:5], v[74:75]
	v_pk_mul_f32 v[86:87], v[6:7], v[82:83]
	v_pk_mul_f32 v[110:111], v[0:1], v[106:107]
	v_pk_mul_f32 v[118:119], v[2:3], v[114:115]
	v_pk_fma_f32 v[74:75], v[4:5], v[74:75], v[4:5] neg_lo:[1,0,0] neg_hi:[1,0,0]
	v_pk_fma_f32 v[82:83], v[6:7], v[82:83], v[6:7] neg_lo:[1,0,0] neg_hi:[1,0,0]
	v_pk_fma_f32 v[106:107], v[0:1], v[106:107], v[0:1] neg_lo:[1,0,0] neg_hi:[1,0,0]
	v_pk_fma_f32 v[114:115], v[2:3], v[114:115], v[2:3] neg_lo:[1,0,0] neg_hi:[1,0,0]
	v_cmp_gt_f32_e64 s[98:99], 0, v4
	v_cmp_gt_f32_e64 s[16:17], 0, v6
	v_cmp_gt_f32_e64 s[10:11], 0, v0
	v_cmp_gt_f32_e64 s[12:13], 0, v2
	v_cndmask_b32_e64 v4, v74, v78, s[98:99]
	v_cndmask_b32_e64 v6, v82, v86, s[16:17]
	v_cndmask_b32_e64 v0, v106, v110, s[10:11]
	v_cndmask_b32_e64 v2, v114, v118, s[12:13]
	v_cmp_gt_f32_e64 s[98:99], 0, v5
	v_cmp_gt_f32_e64 s[16:17], 0, v7
	v_cmp_gt_f32_e64 s[10:11], 0, v1
	v_cmp_gt_f32_e64 s[12:13], 0, v3
	v_cndmask_b32_e64 v5, v75, v79, s[98:99]
	v_cndmask_b32_e64 v7, v83, v87, s[16:17]
	v_cndmask_b32_e64 v1, v107, v111, s[10:11]
	v_cndmask_b32_e64 v3, v115, v119, s[12:13]
	v_cvt_pk_bf16_f32 v228, v4, v5
	v_cvt_pk_bf16_f32 v229, v6, v7
	v_cvt_pk_bf16_f32 v230, v0, v1
	v_cvt_pk_bf16_f32 v231, v2, v3
	global_store_dwordx4 v[150:151], v[228:231], off offset:256

; #define GAS __attribute__((address_space(1)))
;     DI void operator()(AccRef acc, const pg8::Unit& u, int wr, int wc, int, int) const {
;     ...
;         const int kind = dummy ? 2 : (kind_force >= 0 ? kind_force : (pn < 6 ? (pn < 3 ? 0 : 1) : (pn < 15 ? 2 : (pn < 19 ? 3 : 4))));
;         const bool rot = (kind < 2) && ((wc & 1) == 0);
;         const float qs = (kind == 0) ? 0.125f : 1.0f;
;         EPI_PRELOAD_RSTD(ssq)
; #pragma unroll
;         for (int ai = 0; ai < 2; ++ai) {
;         f32x4 rc0[4], rc1[4], rs0[4], rs1[4];
; #pragma unroll
;         for (int m = 0; m < 4; ++m) { rc0[m] = (f32x4){1.f, 1.f, 1.f, 1.f}; rc1[m] = rc0[m]; rs0[m] = (f32x4){0.f, 0.f, 0.f, 0.f}; rs1[m] = rs0[m]; }
;         if (rot) {
; #pragma unroll
;             for (int m = 0; m < 4; ++m) { const GAS f32x4* rp = (const GAS f32x4*)(rope + (size_t)(u.pm * 256 + ai * 128 + wr * 64 + m * 16 + fr) * 16); rc0[m] = rp[0]; rc1[m] = rp[1]; rs0[m] = rp[2]; rs1[m] = rp[3]; }
.LBB0_825:
	s_cmp_gt_u32 s8, 1
	s_cbranch_scc1 .Llean_F_entry
	v_and_or_b32 v72, v226, 15, s49
	v_ashrrev_i32_e32 v245, 4, v226
	v_lshl_add_u32 v224, s6, 8, v72
	v_lshlrev_b32_e32 v72, 2, v245
	v_or_b32_e32 v222, 16, v224
	v_ashrrev_i32_e32 v73, 31, v72
	v_ashrrev_i32_e32 v225, 31, v224
	v_ashrrev_i32_e32 v223, 31, v222
	v_lshl_add_u64 v[140:141], v[72:73], 2, s[26:27]
	v_lshlrev_b64 v[78:79], 6, v[224:225]
	v_lshlrev_b64 v[76:77], 6, v[222:223]
	v_or_b32_e32 v220, 32, v224
	v_or_b32_e32 v218, 48, v224
	v_lshl_add_u64 v[72:73], v[140:141], 0, v[78:79]
	v_lshl_add_u64 v[74:75], v[140:141], 0, v[76:77]
	v_ashrrev_i32_e32 v221, 31, v220
	v_ashrrev_i32_e32 v219, 31, v218
	v_add_u32_e32 v214, 0x80, v224
	global_load_dwordx4 v[80:83], v[72:73], off
	global_load_dwordx4 v[84:87], v[74:75], off
	v_lshlrev_b64 v[74:75], 6, v[220:221]
	v_lshlrev_b64 v[72:73], 6, v[218:219]
	v_ashrrev_i32_e32 v215, 31, v214
	v_lshl_add_u64 v[104:105], v[140:141], 0, v[74:75]
	v_lshl_add_u64 v[108:109], v[140:141], 0, v[72:73]
	v_lshlrev_b64 v[216:217], 6, v[214:215]
	global_load_dwordx4 v[104:107], v[104:105], off
	s_nop 0
	global_load_dwordx4 v[108:111], v[108:109], off
	v_lshl_add_u64 v[112:113], v[140:141], 0, v[216:217]
	global_load_dwordx4 v[112:115], v[112:113], off
	v_add_u32_e32 v212, 0x90, v224
	v_add_u32_e32 v210, 0xa0, v224
	v_add_u32_e32 v208, 0xb0, v224
	v_ashrrev_i32_e32 v213, 31, v212
	v_ashrrev_i32_e32 v211, 31, v210
	v_ashrrev_i32_e32 v209, 31, v208
	v_lshlrev_b64 v[116:117], 6, v[212:213]
	v_lshlrev_b64 v[136:137], 6, v[210:211]
	v_lshlrev_b64 v[142:143], 6, v[208:209]
	v_lshl_add_u64 v[116:117], v[140:141], 0, v[116:117]
	v_lshl_add_u64 v[136:137], v[140:141], 0, v[136:137]
	v_lshl_add_u64 v[140:141], v[140:141], 0, v[142:143]
	global_load_dwordx4 v[116:119], v[116:117], off
	s_cmp_gt_u32 s8, 1
	global_load_dwordx4 v[136:139], v[136:137], off
	s_cselect_b64 s[84:85], -1, 0
	global_load_dwordx4 v[140:143], v[140:141], off
	s_cmp_lt_u32 s8, 2
	s_cselect_b64 s[0:1], -1, 0
	s_and_b64 s[0:1], s[96:97], s[0:1]
	v_mov_b32_e32 v228, 0x260
	v_mov_b64_e32 v[242:243], 0x200
	s_andn2_b64 vcc, exec, s[0:1]
	s_waitcnt vmcnt(0)
	v_add_f32_e32 v80, v80, v81
	v_add_f32_e32 v81, v82, v83
	v_add_f32_e32 v80, v80, v81
	v_add_f32_e32 v81, v84, v85
	v_add_f32_e32 v82, v86, v87
	v_add_f32_e32 v81, v81, v82
	v_add_f32_e32 v83, v104, v105
	v_add_f32_e32 v84, v106, v107
	v_add_f32_e32 v85, v108, v109
	v_add_f32_e32 v86, v110, v111
	v_add_f32_e32 v87, v112, v113
	v_add_f32_e32 v104, v114, v115
	v_add_f32_e32 v82, v83, v84
	v_add_f32_e32 v83, v85, v86
	ds_swizzle_b32 v107, v80 offset:swizzle(SWAP,16)
	v_add_f32_e32 v84, v87, v104
	ds_swizzle_b32 v86, v81 offset:swizzle(SWAP,16)
	ds_swizzle_b32 v87, v82 offset:swizzle(SWAP,16)
	ds_swizzle_b32 v104, v83 offset:swizzle(SWAP,16)
	s_waitcnt lgkmcnt(3)
	v_add_f32_e32 v225, v80, v107
	v_mov_b32_e32 v227, v225
	s_waitcnt lgkmcnt(2)
	v_add_f32_e32 v252, v81, v86
	v_add_f32_e32 v105, v116, v117
	v_add_f32_e32 v106, v118, v119
	s_waitcnt lgkmcnt(1)
	v_add_f32_e32 v250, v82, v87
	s_waitcnt lgkmcnt(0)
	v_add_f32_e32 v248, v83, v104
	v_add_f32_e32 v80, v136, v137
	v_add_f32_e32 v81, v138, v139
	v_add_f32_e32 v82, v140, v141
	v_add_f32_e32 v83, v142, v143
	v_add_f32_e32 v85, v105, v106
	v_add_f32_e32 v80, v80, v81
	v_add_f32_e32 v82, v82, v83
	ds_swizzle_b32 v105, v84 offset:swizzle(SWAP,16)
	ds_swizzle_b32 v106, v85 offset:swizzle(SWAP,16)
	ds_swizzle_b32 v81, v80 offset:swizzle(SWAP,16)
	ds_swizzle_b32 v83, v82 offset:swizzle(SWAP,16)
	v_mov_b32_e32 v244, v252
	s_waitcnt lgkmcnt(3)
	v_add_f32_e32 v223, v84, v105
	s_waitcnt lgkmcnt(2)
	v_add_f32_e32 v219, v85, v106
	s_waitcnt lgkmcnt(1)
	v_add_f32_e32 v213, v80, v81
	s_waitcnt lgkmcnt(0)
	v_add_f32_e32 v209, v82, v83
	v_mov_b32_e32 v251, v250
	v_mov_b32_e32 v249, v248
	v_mov_b32_e32 v247, v223
	v_mov_b32_e32 v221, v219
	v_mov_b32_e32 v215, v213
	v_mov_b32_e32 v211, v209
	v_cndmask_b32_e64 v80, 0, 1, s[0:1]
	v_permlane32_swap_b32_e32 v225, v227
	v_permlane32_swap_b32_e32 v252, v244
	v_permlane32_swap_b32_e32 v250, v251
	v_permlane32_swap_b32_e32 v248, v249
	v_permlane32_swap_b32_e32 v223, v247
	v_permlane32_swap_b32_e32 v219, v221
	v_permlane32_swap_b32_e32 v213, v215
	v_permlane32_swap_b32_e32 v209, v211
	v_cmp_ne_u32_e64 s[6:7], 1, v80
	s_cbranch_vccnz .LBB0_827
	v_lshl_add_u64 v[78:79], s[56:57], 0, v[78:79]
	v_lshl_add_u64 v[76:77], s[56:57], 0, v[76:77]
	v_lshl_add_u64 v[74:75], s[56:57], 0, v[74:75]
	v_lshl_add_u64 v[84:85], s[56:57], 0, v[72:73]
	global_load_dwordx4 v[176:179], v[78:79], off offset:32
	global_load_dwordx4 v[168:171], v[78:79], off offset:48
	global_load_dwordx4 v[172:175], v[78:79], off offset:16
	global_load_dwordx4 v[180:183], v[78:79], off
	global_load_dwordx4 v[144:147], v[76:77], off offset:32
	global_load_dwordx4 v[136:139], v[76:77], off offset:48
	global_load_dwordx4 v[140:143], v[76:77], off offset:16
	global_load_dwordx4 v[148:151], v[76:77], off
	global_load_dwordx4 v[108:111], v[74:75], off offset:32
	global_load_dwordx4 v[104:107], v[74:75], off offset:48
	global_load_dwordx4 v[112:115], v[74:75], off offset:16
	global_load_dwordx4 v[116:119], v[74:75], off
	global_load_dwordx4 v[80:83], v[84:85], off offset:32
	global_load_dwordx4 v[76:79], v[84:85], off offset:48
	s_nop 0
	global_load_dwordx4 v[72:75], v[84:85], off offset:16
	s_nop 0
	global_load_dwordx4 v[84:87], v[84:85], off
	s_branch .LBB0_828
